# hand-written bf16 epilogues (rope/silu/sigmoid/plain slab paths, batched rope loads, packed LDS transpose) for SWA and NSA in-projection GEMMs
# speedup vs baseline: 1.0909x; 1.0209x over previous
.LBB0_1470:
	ds_read_b128 v[128:131], v233
	ds_read_b128 v[136:139], v237
	ds_read_b128 v[132:135], v233 offset:4096
	ds_read_b128 v[140:143], v237 offset:4096
	ds_read_b128 v[144:147], v237 offset:8192
	ds_read_b128 v[148:151], v237 offset:12288
	s_waitcnt lgkmcnt(6)
	v_mfma_f32_32x32x16_bf16 v[112:127], v[188:191], v[216:219], v[112:127]
	v_mfma_f32_32x32x16_bf16 v[48:63], v[212:215], v[216:219], v[48:63]
	v_mfma_f32_32x32x16_bf16 v[96:111], v[188:191], v[220:223], v[96:111]
	v_mfma_f32_32x32x16_bf16 v[32:47], v[212:215], v[220:223], v[32:47]
	v_mfma_f32_32x32x16_bf16 v[80:95], v[188:191], v[224:227], v[80:95]
	v_mfma_f32_32x32x16_bf16 v[16:31], v[212:215], v[224:227], v[16:31]
	v_mfma_f32_32x32x16_bf16 v[64:79], v[188:191], v[228:231], v[64:79]
	v_mfma_f32_32x32x16_bf16 v[0:15], v[212:215], v[228:231], v[0:15]
	ds_read_b128 v[188:191], v234
	ds_read_b128 v[216:219], v238
	ds_read_b128 v[212:215], v234 offset:4096
	ds_read_b128 v[220:223], v238 offset:4096
	ds_read_b128 v[224:227], v238 offset:8192
	ds_read_b128 v[228:231], v238 offset:12288
	s_waitcnt lgkmcnt(6)
	v_mfma_f32_32x32x16_bf16 v[112:127], v[128:131], v[136:139], v[112:127]
	v_mfma_f32_32x32x16_bf16 v[48:63], v[132:135], v[136:139], v[48:63]
	v_mfma_f32_32x32x16_bf16 v[96:111], v[128:131], v[140:143], v[96:111]
	v_mfma_f32_32x32x16_bf16 v[32:47], v[132:135], v[140:143], v[32:47]
	v_mfma_f32_32x32x16_bf16 v[80:95], v[128:131], v[144:147], v[80:95]
	v_mfma_f32_32x32x16_bf16 v[16:31], v[132:135], v[144:147], v[16:31]
	v_mfma_f32_32x32x16_bf16 v[64:79], v[128:131], v[148:151], v[64:79]
	v_mfma_f32_32x32x16_bf16 v[0:15], v[132:135], v[148:151], v[0:15]
	ds_read_b128 v[128:131], v235
	ds_read_b128 v[136:139], v239
	ds_read_b128 v[132:135], v235 offset:4096
	ds_read_b128 v[140:143], v239 offset:4096
	ds_read_b128 v[144:147], v239 offset:8192
	ds_read_b128 v[148:151], v239 offset:12288
	s_waitcnt lgkmcnt(6)
	v_mfma_f32_32x32x16_bf16 v[112:127], v[188:191], v[216:219], v[112:127]
	v_mfma_f32_32x32x16_bf16 v[48:63], v[212:215], v[216:219], v[48:63]
	v_mfma_f32_32x32x16_bf16 v[96:111], v[188:191], v[220:223], v[96:111]
	v_mfma_f32_32x32x16_bf16 v[32:47], v[212:215], v[220:223], v[32:47]
	v_mfma_f32_32x32x16_bf16 v[80:95], v[188:191], v[224:227], v[80:95]
	v_mfma_f32_32x32x16_bf16 v[16:31], v[212:215], v[224:227], v[16:31]
	v_mfma_f32_32x32x16_bf16 v[64:79], v[188:191], v[228:231], v[64:79]
	v_mfma_f32_32x32x16_bf16 v[0:15], v[212:215], v[228:231], v[0:15]
	s_waitcnt vmcnt(0) lgkmcnt(0)
	s_barrier
	v_xor_b32_e32 v232, 0x10000, v232
	v_xor_b32_e32 v236, 0x10000, v236
	v_mfma_f32_32x32x16_bf16 v[112:127], v[128:131], v[136:139], v[112:127]
	v_xor_b32_e32 v233, 0x10000, v233
	v_xor_b32_e32 v237, 0x10000, v237
	v_mfma_f32_32x32x16_bf16 v[48:63], v[132:135], v[136:139], v[48:63]
	v_xor_b32_e32 v234, 0x10000, v234
	v_xor_b32_e32 v238, 0x10000, v238
	v_mfma_f32_32x32x16_bf16 v[96:111], v[128:131], v[140:143], v[96:111]
	v_xor_b32_e32 v235, 0x10000, v235
	v_xor_b32_e32 v239, 0x10000, v239
	v_mfma_f32_32x32x16_bf16 v[32:47], v[132:135], v[140:143], v[32:47]
	v_mfma_f32_32x32x16_bf16 v[80:95], v[128:131], v[144:147], v[80:95]
	v_mfma_f32_32x32x16_bf16 v[16:31], v[132:135], v[144:147], v[16:31]
	v_mfma_f32_32x32x16_bf16 v[64:79], v[128:131], v[148:151], v[64:79]
	v_mfma_f32_32x32x16_bf16 v[0:15], v[132:135], v[148:151], v[0:15]
	v_mbcnt_hi_u32_b32 v230, -1, v210
	v_and_b32_e32 v231, 31, v230
	v_lshrrev_b32_e32 v232, 5, v230
	v_lshlrev_b32_e32 v224, 3, v231
	v_lshlrev_b32_e32 v227, 2, v232
	s_lshr_b32 s90, s70, 6
	s_mul_i32 s91, s90, 0x1200
	s_add_u32 s91, s91, 0x12000
	v_mul_u32_u24_e32 v233, 0x240, v232
	v_lshl_add_u32 v233, v231, 1, v233
	v_add_u32_e32 v225, s91, v233
	v_lshrrev_b32_e32 v228, 3, v230
	v_and_b32_e32 v234, 7, v230
	v_lshlrev_b32_e32 v229, 4, v234
	v_mul_u32_u24_e32 v233, 0x90, v228
	v_add3_u32 v226, v233, v229, s91
	s_mul_i32 s92, s4, 9
	s_sub_u32 s93, s8, s92
	s_lshl_b32 s93, s93, 8
	s_lshl_b32 s92, s4, 8
	s_lshr_b32 s94, s90, 1
	s_lshl_b32 s94, s94, 6
	s_add_u32 s92, s92, s94
	s_and_b32 s94, s90, 1
	s_lshl_b32 s94, s94, 7
	s_add_u32 s93, s93, s94
	s_load_dwordx2 s[98:99], s[0:1], 0x148
.Lep2_00:
	s_add_u32 s94, s92, 0
	s_add_u32 s95, s93, 0
	s_lshr_b32 s90, s95, 6
	s_cmp_lt_u32 s90, 16
	s_cbranch_scc1 .Lep2_00_t0
	s_cmp_lt_u32 s90, 18
	s_cbranch_scc1 .Lep2_00_t16
	s_cmp_lt_u32 s90, 20
	s_cbranch_scc1 .Lep2_00_t18
	s_cmp_lt_u32 s90, 36
	s_cbranch_scc1 .Lep2_00_t20
	s_branch .Lep2_00_end
.Lep2_00_t0:
	s_load_dwordx2 s[96:97], s[0:1], 0x190
	s_mov_b32 s89, 2048
	s_sub_u32 s91, s95, 0
	s_lshl_b32 s91, s91, 1
	s_mov_b32 s88, 0x3e38aa3b
	s_branch .Lep2_00_mR
.Lep2_00_t16:
	s_load_dwordx2 s[96:97], s[0:1], 0x198
	s_mov_b32 s89, 256
	s_sub_u32 s91, s95, 1024
	s_lshl_b32 s91, s91, 1
	s_mov_b32 s88, 1.0
	s_branch .Lep2_00_mR
.Lep2_00_t18:
	s_load_dwordx2 s[96:97], s[0:1], 0x1a0
	s_mov_b32 s89, 256
	s_sub_u32 s91, s95, 1152
	s_lshl_b32 s91, s91, 1
	s_branch .Lep2_00_mP
.Lep2_00_t20:
	s_load_dwordx2 s[96:97], s[0:1], 0x160
	s_mov_b32 s89, 2048
	s_sub_u32 s91, s95, 1280
	s_lshl_b32 s91, s91, 1
	s_branch .Lep2_00_mS
.Lep2_00_mP:
	v_cvt_pk_bf16_f32 v230, v112, v96
	ds_write_b16 v225, v230
	ds_write_b16_d16_hi v225, v230 offset:64
	v_cvt_pk_bf16_f32 v231, v113, v97
	ds_write_b16 v225, v231 offset:144
	ds_write_b16_d16_hi v225, v231 offset:208
	v_cvt_pk_bf16_f32 v232, v114, v98
	ds_write_b16 v225, v232 offset:288
	ds_write_b16_d16_hi v225, v232 offset:352
	v_cvt_pk_bf16_f32 v233, v115, v99
	ds_write_b16 v225, v233 offset:432
	ds_write_b16_d16_hi v225, v233 offset:496
	v_cvt_pk_bf16_f32 v230, v116, v100
	ds_write_b16 v225, v230 offset:1152
	ds_write_b16_d16_hi v225, v230 offset:1216
	v_cvt_pk_bf16_f32 v231, v117, v101
	ds_write_b16 v225, v231 offset:1296
	ds_write_b16_d16_hi v225, v231 offset:1360
	v_cvt_pk_bf16_f32 v232, v118, v102
	ds_write_b16 v225, v232 offset:1440
	ds_write_b16_d16_hi v225, v232 offset:1504
	v_cvt_pk_bf16_f32 v233, v119, v103
	ds_write_b16 v225, v233 offset:1584
	ds_write_b16_d16_hi v225, v233 offset:1648
	v_cvt_pk_bf16_f32 v230, v120, v104
	ds_write_b16 v225, v230 offset:2304
	ds_write_b16_d16_hi v225, v230 offset:2368
	v_cvt_pk_bf16_f32 v231, v121, v105
	ds_write_b16 v225, v231 offset:2448
	ds_write_b16_d16_hi v225, v231 offset:2512
	v_cvt_pk_bf16_f32 v232, v122, v106
	ds_write_b16 v225, v232 offset:2592
	ds_write_b16_d16_hi v225, v232 offset:2656
	v_cvt_pk_bf16_f32 v233, v123, v107
	ds_write_b16 v225, v233 offset:2736
	ds_write_b16_d16_hi v225, v233 offset:2800
	v_cvt_pk_bf16_f32 v230, v124, v108
	ds_write_b16 v225, v230 offset:3456
	ds_write_b16_d16_hi v225, v230 offset:3520
	v_cvt_pk_bf16_f32 v231, v125, v109
	ds_write_b16 v225, v231 offset:3600
	ds_write_b16_d16_hi v225, v231 offset:3664
	v_cvt_pk_bf16_f32 v232, v126, v110
	ds_write_b16 v225, v232 offset:3744
	ds_write_b16_d16_hi v225, v232 offset:3808
	v_cvt_pk_bf16_f32 v233, v127, v111
	ds_write_b16 v225, v233 offset:3888
	ds_write_b16_d16_hi v225, v233 offset:3952
	s_branch .Lep2_00_st
.Lep2_00_mR:
	v_add_u32_e32 v230, s94, v227
	v_lshlrev_b32_e32 v230, 8, v230
	v_add_u32_e32 v236, v230, v224
	v_mov_b32_e32 v237, 0
	s_waitcnt lgkmcnt(0)
	v_lshl_add_u64 v[236:237], s[98:99], 0, v[236:237]
	global_load_dwordx2 v[128:129], v[236:237], off
	global_load_dwordx2 v[130:131], v[236:237], off offset:256
	global_load_dwordx2 v[132:133], v[236:237], off offset:512
	global_load_dwordx2 v[134:135], v[236:237], off offset:768
	global_load_dwordx2 v[136:137], v[236:237], off offset:2048
	global_load_dwordx2 v[138:139], v[236:237], off offset:2304
	global_load_dwordx2 v[140:141], v[236:237], off offset:2560
	global_load_dwordx2 v[142:143], v[236:237], off offset:2816
	v_add_co_u32_e32 v238, vcc, 0x1000, v236
	s_nop 1
	v_addc_co_u32_e32 v239, vcc, 0, v237, vcc
	global_load_dwordx2 v[144:145], v[238:239], off
	global_load_dwordx2 v[146:147], v[238:239], off offset:256
	global_load_dwordx2 v[148:149], v[238:239], off offset:512
	global_load_dwordx2 v[150:151], v[238:239], off offset:768
	global_load_dwordx2 v[152:153], v[238:239], off offset:2048
	global_load_dwordx2 v[154:155], v[238:239], off offset:2304
	global_load_dwordx2 v[156:157], v[238:239], off offset:2560
	global_load_dwordx2 v[158:159], v[238:239], off offset:2816
	s_waitcnt vmcnt(15)
	v_mul_f32_e32 v230, v96, v129
	v_mul_f32_e32 v231, v112, v129
	v_fma_f32 v230, v112, v128, -v230
	v_fma_f32 v231, v96, v128, v231
	v_mul_f32_e32 v230, s88, v230
	v_mul_f32_e32 v231, s88, v231
	v_cvt_pk_bf16_f32 v230, v230, v231
	ds_write_b16 v225, v230
	ds_write_b16_d16_hi v225, v230 offset:64
	s_waitcnt vmcnt(14)
	v_mul_f32_e32 v230, v97, v131
	v_mul_f32_e32 v231, v113, v131
	v_fma_f32 v230, v113, v130, -v230
	v_fma_f32 v231, v97, v130, v231
	v_mul_f32_e32 v230, s88, v230
	v_mul_f32_e32 v231, s88, v231
	v_cvt_pk_bf16_f32 v230, v230, v231
	ds_write_b16 v225, v230 offset:144
	ds_write_b16_d16_hi v225, v230 offset:208
	s_waitcnt vmcnt(13)
	v_mul_f32_e32 v230, v98, v133
	v_mul_f32_e32 v231, v114, v133
	v_fma_f32 v230, v114, v132, -v230
	v_fma_f32 v231, v98, v132, v231
	v_mul_f32_e32 v230, s88, v230
	v_mul_f32_e32 v231, s88, v231
	v_cvt_pk_bf16_f32 v230, v230, v231
	ds_write_b16 v225, v230 offset:288
	ds_write_b16_d16_hi v225, v230 offset:352
	s_waitcnt vmcnt(12)
	v_mul_f32_e32 v230, v99, v135
	v_mul_f32_e32 v231, v115, v135
	v_fma_f32 v230, v115, v134, -v230
	v_fma_f32 v231, v99, v134, v231
	v_mul_f32_e32 v230, s88, v230
	v_mul_f32_e32 v231, s88, v231
	v_cvt_pk_bf16_f32 v230, v230, v231
	ds_write_b16 v225, v230 offset:432
	ds_write_b16_d16_hi v225, v230 offset:496
	s_waitcnt vmcnt(11)
	v_mul_f32_e32 v230, v100, v137
	v_mul_f32_e32 v231, v116, v137
	v_fma_f32 v230, v116, v136, -v230
	v_fma_f32 v231, v100, v136, v231
	v_mul_f32_e32 v230, s88, v230
	v_mul_f32_e32 v231, s88, v231
	v_cvt_pk_bf16_f32 v230, v230, v231
	ds_write_b16 v225, v230 offset:1152
	ds_write_b16_d16_hi v225, v230 offset:1216
	s_waitcnt vmcnt(10)
	v_mul_f32_e32 v230, v101, v139
	v_mul_f32_e32 v231, v117, v139
	v_fma_f32 v230, v117, v138, -v230
	v_fma_f32 v231, v101, v138, v231
	v_mul_f32_e32 v230, s88, v230
	v_mul_f32_e32 v231, s88, v231
	v_cvt_pk_bf16_f32 v230, v230, v231
	ds_write_b16 v225, v230 offset:1296
	ds_write_b16_d16_hi v225, v230 offset:1360
	s_waitcnt vmcnt(9)
	v_mul_f32_e32 v230, v102, v141
	v_mul_f32_e32 v231, v118, v141
	v_fma_f32 v230, v118, v140, -v230
	v_fma_f32 v231, v102, v140, v231
	v_mul_f32_e32 v230, s88, v230
	v_mul_f32_e32 v231, s88, v231
	v_cvt_pk_bf16_f32 v230, v230, v231
	ds_write_b16 v225, v230 offset:1440
	ds_write_b16_d16_hi v225, v230 offset:1504
	s_waitcnt vmcnt(8)
	v_mul_f32_e32 v230, v103, v143
	v_mul_f32_e32 v231, v119, v143
	v_fma_f32 v230, v119, v142, -v230
	v_fma_f32 v231, v103, v142, v231
	v_mul_f32_e32 v230, s88, v230
	v_mul_f32_e32 v231, s88, v231
	v_cvt_pk_bf16_f32 v230, v230, v231
	ds_write_b16 v225, v230 offset:1584
	ds_write_b16_d16_hi v225, v230 offset:1648
	s_waitcnt vmcnt(7)
	v_mul_f32_e32 v230, v104, v145
	v_mul_f32_e32 v231, v120, v145
	v_fma_f32 v230, v120, v144, -v230
	v_fma_f32 v231, v104, v144, v231
	v_mul_f32_e32 v230, s88, v230
	v_mul_f32_e32 v231, s88, v231
	v_cvt_pk_bf16_f32 v230, v230, v231
	ds_write_b16 v225, v230 offset:2304
	ds_write_b16_d16_hi v225, v230 offset:2368
	s_waitcnt vmcnt(6)
	v_mul_f32_e32 v230, v105, v147
	v_mul_f32_e32 v231, v121, v147
	v_fma_f32 v230, v121, v146, -v230
	v_fma_f32 v231, v105, v146, v231
	v_mul_f32_e32 v230, s88, v230
	v_mul_f32_e32 v231, s88, v231
	v_cvt_pk_bf16_f32 v230, v230, v231
	ds_write_b16 v225, v230 offset:2448
	ds_write_b16_d16_hi v225, v230 offset:2512
	s_waitcnt vmcnt(5)
	v_mul_f32_e32 v230, v106, v149
	v_mul_f32_e32 v231, v122, v149
	v_fma_f32 v230, v122, v148, -v230
	v_fma_f32 v231, v106, v148, v231
	v_mul_f32_e32 v230, s88, v230
	v_mul_f32_e32 v231, s88, v231
	v_cvt_pk_bf16_f32 v230, v230, v231
	ds_write_b16 v225, v230 offset:2592
	ds_write_b16_d16_hi v225, v230 offset:2656
	s_waitcnt vmcnt(4)
	v_mul_f32_e32 v230, v107, v151
	v_mul_f32_e32 v231, v123, v151
	v_fma_f32 v230, v123, v150, -v230
	v_fma_f32 v231, v107, v150, v231
	v_mul_f32_e32 v230, s88, v230
	v_mul_f32_e32 v231, s88, v231
	v_cvt_pk_bf16_f32 v230, v230, v231
	ds_write_b16 v225, v230 offset:2736
	ds_write_b16_d16_hi v225, v230 offset:2800
	s_waitcnt vmcnt(3)
	v_mul_f32_e32 v230, v108, v153
	v_mul_f32_e32 v231, v124, v153
	v_fma_f32 v230, v124, v152, -v230
	v_fma_f32 v231, v108, v152, v231
	v_mul_f32_e32 v230, s88, v230
	v_mul_f32_e32 v231, s88, v231
	v_cvt_pk_bf16_f32 v230, v230, v231
	ds_write_b16 v225, v230 offset:3456
	ds_write_b16_d16_hi v225, v230 offset:3520
	s_waitcnt vmcnt(2)
	v_mul_f32_e32 v230, v109, v155
	v_mul_f32_e32 v231, v125, v155
	v_fma_f32 v230, v125, v154, -v230
	v_fma_f32 v231, v109, v154, v231
	v_mul_f32_e32 v230, s88, v230
	v_mul_f32_e32 v231, s88, v231
	v_cvt_pk_bf16_f32 v230, v230, v231
	ds_write_b16 v225, v230 offset:3600
	ds_write_b16_d16_hi v225, v230 offset:3664
	s_waitcnt vmcnt(1)
	v_mul_f32_e32 v230, v110, v157
	v_mul_f32_e32 v231, v126, v157
	v_fma_f32 v230, v126, v156, -v230
	v_fma_f32 v231, v110, v156, v231
	v_mul_f32_e32 v230, s88, v230
	v_mul_f32_e32 v231, s88, v231
	v_cvt_pk_bf16_f32 v230, v230, v231
	ds_write_b16 v225, v230 offset:3744
	ds_write_b16_d16_hi v225, v230 offset:3808
	s_waitcnt vmcnt(0)
	v_mul_f32_e32 v230, v111, v159
	v_mul_f32_e32 v231, v127, v159
	v_fma_f32 v230, v127, v158, -v230
	v_fma_f32 v231, v111, v158, v231
	v_mul_f32_e32 v230, s88, v230
	v_mul_f32_e32 v231, s88, v231
	v_cvt_pk_bf16_f32 v230, v230, v231
	ds_write_b16 v225, v230 offset:3888
	ds_write_b16_d16_hi v225, v230 offset:3952
	s_branch .Lep2_00_st
.Lep2_00_mS:
	v_mul_f32_e32 v230, 0xbfb8aa3b, v112
	v_mul_f32_e32 v231, 0xbfb8aa3b, v96
	v_exp_f32_e32 v230, v230
	v_exp_f32_e32 v231, v231
	v_add_f32_e32 v230, 1.0, v230
	v_add_f32_e32 v231, 1.0, v231
	v_rcp_f32_e32 v230, v230
	v_rcp_f32_e32 v231, v231
	v_mul_f32_e32 v230, v112, v230
	v_mul_f32_e32 v231, v96, v231
	v_cvt_pk_bf16_f32 v230, v230, v231
	ds_write_b16 v225, v230
	ds_write_b16_d16_hi v225, v230 offset:64
	v_mul_f32_e32 v232, 0xbfb8aa3b, v113
	v_mul_f32_e32 v233, 0xbfb8aa3b, v97
	v_exp_f32_e32 v232, v232
	v_exp_f32_e32 v233, v233
	v_add_f32_e32 v232, 1.0, v232
	v_add_f32_e32 v233, 1.0, v233
	v_rcp_f32_e32 v232, v232
	v_rcp_f32_e32 v233, v233
	v_mul_f32_e32 v232, v113, v232
	v_mul_f32_e32 v233, v97, v233
	v_cvt_pk_bf16_f32 v232, v232, v233
	ds_write_b16 v225, v232 offset:144
	ds_write_b16_d16_hi v225, v232 offset:208
	v_mul_f32_e32 v230, 0xbfb8aa3b, v114
	v_mul_f32_e32 v231, 0xbfb8aa3b, v98
	v_exp_f32_e32 v230, v230
	v_exp_f32_e32 v231, v231
	v_add_f32_e32 v230, 1.0, v230
	v_add_f32_e32 v231, 1.0, v231
	v_rcp_f32_e32 v230, v230
	v_rcp_f32_e32 v231, v231
	v_mul_f32_e32 v230, v114, v230
	v_mul_f32_e32 v231, v98, v231
	v_cvt_pk_bf16_f32 v230, v230, v231
	ds_write_b16 v225, v230 offset:288
	ds_write_b16_d16_hi v225, v230 offset:352
	v_mul_f32_e32 v232, 0xbfb8aa3b, v115
	v_mul_f32_e32 v233, 0xbfb8aa3b, v99
	v_exp_f32_e32 v232, v232
	v_exp_f32_e32 v233, v233
	v_add_f32_e32 v232, 1.0, v232
	v_add_f32_e32 v233, 1.0, v233
	v_rcp_f32_e32 v232, v232
	v_rcp_f32_e32 v233, v233
	v_mul_f32_e32 v232, v115, v232
	v_mul_f32_e32 v233, v99, v233
	v_cvt_pk_bf16_f32 v232, v232, v233
	ds_write_b16 v225, v232 offset:432
	ds_write_b16_d16_hi v225, v232 offset:496
	v_mul_f32_e32 v230, 0xbfb8aa3b, v116
	v_mul_f32_e32 v231, 0xbfb8aa3b, v100
	v_exp_f32_e32 v230, v230
	v_exp_f32_e32 v231, v231
	v_add_f32_e32 v230, 1.0, v230
	v_add_f32_e32 v231, 1.0, v231
	v_rcp_f32_e32 v230, v230
	v_rcp_f32_e32 v231, v231
	v_mul_f32_e32 v230, v116, v230
	v_mul_f32_e32 v231, v100, v231
	v_cvt_pk_bf16_f32 v230, v230, v231
	ds_write_b16 v225, v230 offset:1152
	ds_write_b16_d16_hi v225, v230 offset:1216
	v_mul_f32_e32 v232, 0xbfb8aa3b, v117
	v_mul_f32_e32 v233, 0xbfb8aa3b, v101
	v_exp_f32_e32 v232, v232
	v_exp_f32_e32 v233, v233
	v_add_f32_e32 v232, 1.0, v232
	v_add_f32_e32 v233, 1.0, v233
	v_rcp_f32_e32 v232, v232
	v_rcp_f32_e32 v233, v233
	v_mul_f32_e32 v232, v117, v232
	v_mul_f32_e32 v233, v101, v233
	v_cvt_pk_bf16_f32 v232, v232, v233
	ds_write_b16 v225, v232 offset:1296
	ds_write_b16_d16_hi v225, v232 offset:1360
	v_mul_f32_e32 v230, 0xbfb8aa3b, v118
	v_mul_f32_e32 v231, 0xbfb8aa3b, v102
	v_exp_f32_e32 v230, v230
	v_exp_f32_e32 v231, v231
	v_add_f32_e32 v230, 1.0, v230
	v_add_f32_e32 v231, 1.0, v231
	v_rcp_f32_e32 v230, v230
	v_rcp_f32_e32 v231, v231
	v_mul_f32_e32 v230, v118, v230
	v_mul_f32_e32 v231, v102, v231
	v_cvt_pk_bf16_f32 v230, v230, v231
	ds_write_b16 v225, v230 offset:1440
	ds_write_b16_d16_hi v225, v230 offset:1504
	v_mul_f32_e32 v232, 0xbfb8aa3b, v119
	v_mul_f32_e32 v233, 0xbfb8aa3b, v103
	v_exp_f32_e32 v232, v232
	v_exp_f32_e32 v233, v233
	v_add_f32_e32 v232, 1.0, v232
	v_add_f32_e32 v233, 1.0, v233
	v_rcp_f32_e32 v232, v232
	v_rcp_f32_e32 v233, v233
	v_mul_f32_e32 v232, v119, v232
	v_mul_f32_e32 v233, v103, v233
	v_cvt_pk_bf16_f32 v232, v232, v233
	ds_write_b16 v225, v232 offset:1584
	ds_write_b16_d16_hi v225, v232 offset:1648
	v_mul_f32_e32 v230, 0xbfb8aa3b, v120
	v_mul_f32_e32 v231, 0xbfb8aa3b, v104
	v_exp_f32_e32 v230, v230
	v_exp_f32_e32 v231, v231
	v_add_f32_e32 v230, 1.0, v230
	v_add_f32_e32 v231, 1.0, v231
	v_rcp_f32_e32 v230, v230
	v_rcp_f32_e32 v231, v231
	v_mul_f32_e32 v230, v120, v230
	v_mul_f32_e32 v231, v104, v231
	v_cvt_pk_bf16_f32 v230, v230, v231
	ds_write_b16 v225, v230 offset:2304
	ds_write_b16_d16_hi v225, v230 offset:2368
	v_mul_f32_e32 v232, 0xbfb8aa3b, v121
	v_mul_f32_e32 v233, 0xbfb8aa3b, v105
	v_exp_f32_e32 v232, v232
	v_exp_f32_e32 v233, v233
	v_add_f32_e32 v232, 1.0, v232
	v_add_f32_e32 v233, 1.0, v233
	v_rcp_f32_e32 v232, v232
	v_rcp_f32_e32 v233, v233
	v_mul_f32_e32 v232, v121, v232
	v_mul_f32_e32 v233, v105, v233
	v_cvt_pk_bf16_f32 v232, v232, v233
	ds_write_b16 v225, v232 offset:2448
	ds_write_b16_d16_hi v225, v232 offset:2512
	v_mul_f32_e32 v230, 0xbfb8aa3b, v122
	v_mul_f32_e32 v231, 0xbfb8aa3b, v106
	v_exp_f32_e32 v230, v230
	v_exp_f32_e32 v231, v231
	v_add_f32_e32 v230, 1.0, v230
	v_add_f32_e32 v231, 1.0, v231
	v_rcp_f32_e32 v230, v230
	v_rcp_f32_e32 v231, v231
	v_mul_f32_e32 v230, v122, v230
	v_mul_f32_e32 v231, v106, v231
	v_cvt_pk_bf16_f32 v230, v230, v231
	ds_write_b16 v225, v230 offset:2592
	ds_write_b16_d16_hi v225, v230 offset:2656
	v_mul_f32_e32 v232, 0xbfb8aa3b, v123
	v_mul_f32_e32 v233, 0xbfb8aa3b, v107
	v_exp_f32_e32 v232, v232
	v_exp_f32_e32 v233, v233
	v_add_f32_e32 v232, 1.0, v232
	v_add_f32_e32 v233, 1.0, v233
	v_rcp_f32_e32 v232, v232
	v_rcp_f32_e32 v233, v233
	v_mul_f32_e32 v232, v123, v232
	v_mul_f32_e32 v233, v107, v233
	v_cvt_pk_bf16_f32 v232, v232, v233
	ds_write_b16 v225, v232 offset:2736
	ds_write_b16_d16_hi v225, v232 offset:2800
	v_mul_f32_e32 v230, 0xbfb8aa3b, v124
	v_mul_f32_e32 v231, 0xbfb8aa3b, v108
	v_exp_f32_e32 v230, v230
	v_exp_f32_e32 v231, v231
	v_add_f32_e32 v230, 1.0, v230
	v_add_f32_e32 v231, 1.0, v231
	v_rcp_f32_e32 v230, v230
	v_rcp_f32_e32 v231, v231
	v_mul_f32_e32 v230, v124, v230
	v_mul_f32_e32 v231, v108, v231
	v_cvt_pk_bf16_f32 v230, v230, v231
	ds_write_b16 v225, v230 offset:3456
	ds_write_b16_d16_hi v225, v230 offset:3520
	v_mul_f32_e32 v232, 0xbfb8aa3b, v125
	v_mul_f32_e32 v233, 0xbfb8aa3b, v109
	v_exp_f32_e32 v232, v232
	v_exp_f32_e32 v233, v233
	v_add_f32_e32 v232, 1.0, v232
	v_add_f32_e32 v233, 1.0, v233
	v_rcp_f32_e32 v232, v232
	v_rcp_f32_e32 v233, v233
	v_mul_f32_e32 v232, v125, v232
	v_mul_f32_e32 v233, v109, v233
	v_cvt_pk_bf16_f32 v232, v232, v233
	ds_write_b16 v225, v232 offset:3600
	ds_write_b16_d16_hi v225, v232 offset:3664
	v_mul_f32_e32 v230, 0xbfb8aa3b, v126
	v_mul_f32_e32 v231, 0xbfb8aa3b, v110
	v_exp_f32_e32 v230, v230
	v_exp_f32_e32 v231, v231
	v_add_f32_e32 v230, 1.0, v230
	v_add_f32_e32 v231, 1.0, v231
	v_rcp_f32_e32 v230, v230
	v_rcp_f32_e32 v231, v231
	v_mul_f32_e32 v230, v126, v230
	v_mul_f32_e32 v231, v110, v231
	v_cvt_pk_bf16_f32 v230, v230, v231
	ds_write_b16 v225, v230 offset:3744
	ds_write_b16_d16_hi v225, v230 offset:3808
	v_mul_f32_e32 v232, 0xbfb8aa3b, v127
	v_mul_f32_e32 v233, 0xbfb8aa3b, v111
	v_exp_f32_e32 v232, v232
	v_exp_f32_e32 v233, v233
	v_add_f32_e32 v232, 1.0, v232
	v_add_f32_e32 v233, 1.0, v233
	v_rcp_f32_e32 v232, v232
	v_rcp_f32_e32 v233, v233
	v_mul_f32_e32 v232, v127, v232
	v_mul_f32_e32 v233, v111, v233
	v_cvt_pk_bf16_f32 v232, v232, v233
	ds_write_b16 v225, v232 offset:3888
	ds_write_b16_d16_hi v225, v232 offset:3952
	s_branch .Lep2_00_st
.Lep2_00_st:
	v_add_u32_e32 v234, s94, v228
	s_waitcnt lgkmcnt(0)
	ds_read_b128 v[188:191], v226
	ds_read_b128 v[212:215], v226 offset:1152
	ds_read_b128 v[216:219], v226 offset:2304
	ds_read_b128 v[220:223], v226 offset:3456
	v_add_u32_e32 v230, 0, v234
	v_mul_lo_u32 v230, v230, s89
	v_add3_u32 v230, v230, v229, s91
	v_add_u32_e32 v231, 8, v234
	v_mul_lo_u32 v231, v231, s89
	v_add3_u32 v231, v231, v229, s91
	v_add_u32_e32 v232, 16, v234
	v_mul_lo_u32 v232, v232, s89
	v_add3_u32 v232, v232, v229, s91
	v_add_u32_e32 v233, 24, v234
	v_mul_lo_u32 v233, v233, s89
	v_add3_u32 v233, v233, v229, s91
	s_waitcnt lgkmcnt(3)
	global_store_dwordx4 v230, v[188:191], s[96:97]
	s_waitcnt lgkmcnt(2)
	global_store_dwordx4 v231, v[212:215], s[96:97]
	s_waitcnt lgkmcnt(1)
	global_store_dwordx4 v232, v[216:219], s[96:97]
	s_waitcnt lgkmcnt(0)
	global_store_dwordx4 v233, v[220:223], s[96:97]
.Lep2_00_end:
.Lep2_01:
	s_add_u32 s94, s92, 0
	s_add_u32 s95, s93, 64
	s_lshr_b32 s90, s95, 6
	s_cmp_lt_u32 s90, 16
	s_cbranch_scc1 .Lep2_01_t0
	s_cmp_lt_u32 s90, 18
	s_cbranch_scc1 .Lep2_01_t16
	s_cmp_lt_u32 s90, 20
	s_cbranch_scc1 .Lep2_01_t18
	s_cmp_lt_u32 s90, 36
	s_cbranch_scc1 .Lep2_01_t20
	s_branch .Lep2_01_end

.Lep2_01_mP:
	v_cvt_pk_bf16_f32 v230, v80, v64
	ds_write_b16 v225, v230
	ds_write_b16_d16_hi v225, v230 offset:64
	v_cvt_pk_bf16_f32 v231, v81, v65
	ds_write_b16 v225, v231 offset:144
	ds_write_b16_d16_hi v225, v231 offset:208
	v_cvt_pk_bf16_f32 v232, v82, v66
	ds_write_b16 v225, v232 offset:288
	ds_write_b16_d16_hi v225, v232 offset:352
	v_cvt_pk_bf16_f32 v233, v83, v67
	ds_write_b16 v225, v233 offset:432
	ds_write_b16_d16_hi v225, v233 offset:496
	v_cvt_pk_bf16_f32 v230, v84, v68
	ds_write_b16 v225, v230 offset:1152
	ds_write_b16_d16_hi v225, v230 offset:1216
	v_cvt_pk_bf16_f32 v231, v85, v69
	ds_write_b16 v225, v231 offset:1296
	ds_write_b16_d16_hi v225, v231 offset:1360
	v_cvt_pk_bf16_f32 v232, v86, v70
	ds_write_b16 v225, v232 offset:1440
	ds_write_b16_d16_hi v225, v232 offset:1504
	v_cvt_pk_bf16_f32 v233, v87, v71
	ds_write_b16 v225, v233 offset:1584
	ds_write_b16_d16_hi v225, v233 offset:1648
	v_cvt_pk_bf16_f32 v230, v88, v72
	ds_write_b16 v225, v230 offset:2304
	ds_write_b16_d16_hi v225, v230 offset:2368
	v_cvt_pk_bf16_f32 v231, v89, v73
	ds_write_b16 v225, v231 offset:2448
	ds_write_b16_d16_hi v225, v231 offset:2512
	v_cvt_pk_bf16_f32 v232, v90, v74
	ds_write_b16 v225, v232 offset:2592
	ds_write_b16_d16_hi v225, v232 offset:2656
	v_cvt_pk_bf16_f32 v233, v91, v75
	ds_write_b16 v225, v233 offset:2736
	ds_write_b16_d16_hi v225, v233 offset:2800
	v_cvt_pk_bf16_f32 v230, v92, v76
	ds_write_b16 v225, v230 offset:3456
	ds_write_b16_d16_hi v225, v230 offset:3520
	v_cvt_pk_bf16_f32 v231, v93, v77
	ds_write_b16 v225, v231 offset:3600
	ds_write_b16_d16_hi v225, v231 offset:3664
	v_cvt_pk_bf16_f32 v232, v94, v78
	ds_write_b16 v225, v232 offset:3744
	ds_write_b16_d16_hi v225, v232 offset:3808
	v_cvt_pk_bf16_f32 v233, v95, v79
	ds_write_b16 v225, v233 offset:3888
	ds_write_b16_d16_hi v225, v233 offset:3952
	s_branch .Lep2_01_st
.Lep2_01_mR:
	v_add_u32_e32 v230, s94, v227
	v_lshlrev_b32_e32 v230, 8, v230
	v_add_u32_e32 v236, v230, v224
	v_mov_b32_e32 v237, 0
	s_waitcnt lgkmcnt(0)
	v_lshl_add_u64 v[236:237], s[98:99], 0, v[236:237]
	global_load_dwordx2 v[128:129], v[236:237], off
	global_load_dwordx2 v[130:131], v[236:237], off offset:256
	global_load_dwordx2 v[132:133], v[236:237], off offset:512
	global_load_dwordx2 v[134:135], v[236:237], off offset:768
	global_load_dwordx2 v[136:137], v[236:237], off offset:2048
	global_load_dwordx2 v[138:139], v[236:237], off offset:2304
	global_load_dwordx2 v[140:141], v[236:237], off offset:2560
	global_load_dwordx2 v[142:143], v[236:237], off offset:2816
	v_add_co_u32_e32 v238, vcc, 0x1000, v236
	s_nop 1
	v_addc_co_u32_e32 v239, vcc, 0, v237, vcc
	global_load_dwordx2 v[144:145], v[238:239], off
	global_load_dwordx2 v[146:147], v[238:239], off offset:256
	global_load_dwordx2 v[148:149], v[238:239], off offset:512
	global_load_dwordx2 v[150:151], v[238:239], off offset:768
	global_load_dwordx2 v[152:153], v[238:239], off offset:2048
	global_load_dwordx2 v[154:155], v[238:239], off offset:2304
	global_load_dwordx2 v[156:157], v[238:239], off offset:2560
	global_load_dwordx2 v[158:159], v[238:239], off offset:2816
	s_waitcnt vmcnt(15)
	v_mul_f32_e32 v230, v64, v129
	v_mul_f32_e32 v231, v80, v129
	v_fma_f32 v230, v80, v128, -v230
	v_fma_f32 v231, v64, v128, v231
	v_mul_f32_e32 v230, s88, v230
	v_mul_f32_e32 v231, s88, v231
	v_cvt_pk_bf16_f32 v230, v230, v231
	ds_write_b16 v225, v230
	ds_write_b16_d16_hi v225, v230 offset:64
	s_waitcnt vmcnt(14)
	v_mul_f32_e32 v230, v65, v131
	v_mul_f32_e32 v231, v81, v131
	v_fma_f32 v230, v81, v130, -v230
	v_fma_f32 v231, v65, v130, v231
	v_mul_f32_e32 v230, s88, v230
	v_mul_f32_e32 v231, s88, v231
	v_cvt_pk_bf16_f32 v230, v230, v231
	ds_write_b16 v225, v230 offset:144
	ds_write_b16_d16_hi v225, v230 offset:208
	s_waitcnt vmcnt(13)
	v_mul_f32_e32 v230, v66, v133
	v_mul_f32_e32 v231, v82, v133
	v_fma_f32 v230, v82, v132, -v230
	v_fma_f32 v231, v66, v132, v231
	v_mul_f32_e32 v230, s88, v230
	v_mul_f32_e32 v231, s88, v231
	v_cvt_pk_bf16_f32 v230, v230, v231
	ds_write_b16 v225, v230 offset:288
	ds_write_b16_d16_hi v225, v230 offset:352
	s_waitcnt vmcnt(12)
	v_mul_f32_e32 v230, v67, v135
	v_mul_f32_e32 v231, v83, v135
	v_fma_f32 v230, v83, v134, -v230
	v_fma_f32 v231, v67, v134, v231
	v_mul_f32_e32 v230, s88, v230
	v_mul_f32_e32 v231, s88, v231
	v_cvt_pk_bf16_f32 v230, v230, v231
	ds_write_b16 v225, v230 offset:432
	ds_write_b16_d16_hi v225, v230 offset:496
	s_waitcnt vmcnt(11)
	v_mul_f32_e32 v230, v68, v137
	v_mul_f32_e32 v231, v84, v137
	v_fma_f32 v230, v84, v136, -v230
	v_fma_f32 v231, v68, v136, v231
	v_mul_f32_e32 v230, s88, v230
	v_mul_f32_e32 v231, s88, v231
	v_cvt_pk_bf16_f32 v230, v230, v231
	ds_write_b16 v225, v230 offset:1152
	ds_write_b16_d16_hi v225, v230 offset:1216
	s_waitcnt vmcnt(10)
	v_mul_f32_e32 v230, v69, v139
	v_mul_f32_e32 v231, v85, v139
	v_fma_f32 v230, v85, v138, -v230
	v_fma_f32 v231, v69, v138, v231
	v_mul_f32_e32 v230, s88, v230
	v_mul_f32_e32 v231, s88, v231
	v_cvt_pk_bf16_f32 v230, v230, v231
	ds_write_b16 v225, v230 offset:1296
	ds_write_b16_d16_hi v225, v230 offset:1360
	s_waitcnt vmcnt(9)
	v_mul_f32_e32 v230, v70, v141
	v_mul_f32_e32 v231, v86, v141
	v_fma_f32 v230, v86, v140, -v230
	v_fma_f32 v231, v70, v140, v231
	v_mul_f32_e32 v230, s88, v230
	v_mul_f32_e32 v231, s88, v231
	v_cvt_pk_bf16_f32 v230, v230, v231
	ds_write_b16 v225, v230 offset:1440
	ds_write_b16_d16_hi v225, v230 offset:1504
	s_waitcnt vmcnt(8)
	v_mul_f32_e32 v230, v71, v143
	v_mul_f32_e32 v231, v87, v143
	v_fma_f32 v230, v87, v142, -v230
	v_fma_f32 v231, v71, v142, v231
	v_mul_f32_e32 v230, s88, v230
	v_mul_f32_e32 v231, s88, v231
	v_cvt_pk_bf16_f32 v230, v230, v231
	ds_write_b16 v225, v230 offset:1584
	ds_write_b16_d16_hi v225, v230 offset:1648
	s_waitcnt vmcnt(7)
	v_mul_f32_e32 v230, v72, v145
	v_mul_f32_e32 v231, v88, v145
	v_fma_f32 v230, v88, v144, -v230
	v_fma_f32 v231, v72, v144, v231
	v_mul_f32_e32 v230, s88, v230
	v_mul_f32_e32 v231, s88, v231
	v_cvt_pk_bf16_f32 v230, v230, v231
	ds_write_b16 v225, v230 offset:2304
	ds_write_b16_d16_hi v225, v230 offset:2368
	s_waitcnt vmcnt(6)
	v_mul_f32_e32 v230, v73, v147
	v_mul_f32_e32 v231, v89, v147
	v_fma_f32 v230, v89, v146, -v230
	v_fma_f32 v231, v73, v146, v231
	v_mul_f32_e32 v230, s88, v230
	v_mul_f32_e32 v231, s88, v231
	v_cvt_pk_bf16_f32 v230, v230, v231
	ds_write_b16 v225, v230 offset:2448
	ds_write_b16_d16_hi v225, v230 offset:2512
	s_waitcnt vmcnt(5)
	v_mul_f32_e32 v230, v74, v149
	v_mul_f32_e32 v231, v90, v149
	v_fma_f32 v230, v90, v148, -v230
	v_fma_f32 v231, v74, v148, v231
	v_mul_f32_e32 v230, s88, v230
	v_mul_f32_e32 v231, s88, v231
	v_cvt_pk_bf16_f32 v230, v230, v231
	ds_write_b16 v225, v230 offset:2592
	ds_write_b16_d16_hi v225, v230 offset:2656
	s_waitcnt vmcnt(4)
	v_mul_f32_e32 v230, v75, v151
	v_mul_f32_e32 v231, v91, v151
	v_fma_f32 v230, v91, v150, -v230
	v_fma_f32 v231, v75, v150, v231
	v_mul_f32_e32 v230, s88, v230
	v_mul_f32_e32 v231, s88, v231
	v_cvt_pk_bf16_f32 v230, v230, v231
	ds_write_b16 v225, v230 offset:2736
	ds_write_b16_d16_hi v225, v230 offset:2800
	s_waitcnt vmcnt(3)
	v_mul_f32_e32 v230, v76, v153
	v_mul_f32_e32 v231, v92, v153
	v_fma_f32 v230, v92, v152, -v230
	v_fma_f32 v231, v76, v152, v231
	v_mul_f32_e32 v230, s88, v230
	v_mul_f32_e32 v231, s88, v231
	v_cvt_pk_bf16_f32 v230, v230, v231
	ds_write_b16 v225, v230 offset:3456
	ds_write_b16_d16_hi v225, v230 offset:3520
	s_waitcnt vmcnt(2)
	v_mul_f32_e32 v230, v77, v155
	v_mul_f32_e32 v231, v93, v155
	v_fma_f32 v230, v93, v154, -v230
	v_fma_f32 v231, v77, v154, v231
	v_mul_f32_e32 v230, s88, v230
	v_mul_f32_e32 v231, s88, v231
	v_cvt_pk_bf16_f32 v230, v230, v231
	ds_write_b16 v225, v230 offset:3600
	ds_write_b16_d16_hi v225, v230 offset:3664
	s_waitcnt vmcnt(1)
	v_mul_f32_e32 v230, v78, v157
	v_mul_f32_e32 v231, v94, v157
	v_fma_f32 v230, v94, v156, -v230
	v_fma_f32 v231, v78, v156, v231
	v_mul_f32_e32 v230, s88, v230
	v_mul_f32_e32 v231, s88, v231
	v_cvt_pk_bf16_f32 v230, v230, v231
	ds_write_b16 v225, v230 offset:3744
	ds_write_b16_d16_hi v225, v230 offset:3808
	s_waitcnt vmcnt(0)
	v_mul_f32_e32 v230, v79, v159
	v_mul_f32_e32 v231, v95, v159
	v_fma_f32 v230, v95, v158, -v230
	v_fma_f32 v231, v79, v158, v231
	v_mul_f32_e32 v230, s88, v230
	v_mul_f32_e32 v231, s88, v231
	v_cvt_pk_bf16_f32 v230, v230, v231
	ds_write_b16 v225, v230 offset:3888
	ds_write_b16_d16_hi v225, v230 offset:3952
	s_branch .Lep2_01_st
.Lep2_01_mS:
	v_mul_f32_e32 v230, 0xbfb8aa3b, v80
	v_mul_f32_e32 v231, 0xbfb8aa3b, v64
	v_exp_f32_e32 v230, v230
	v_exp_f32_e32 v231, v231
	v_add_f32_e32 v230, 1.0, v230
	v_add_f32_e32 v231, 1.0, v231
	v_rcp_f32_e32 v230, v230
	v_rcp_f32_e32 v231, v231
	v_mul_f32_e32 v230, v80, v230
	v_mul_f32_e32 v231, v64, v231
	v_cvt_pk_bf16_f32 v230, v230, v231
	ds_write_b16 v225, v230
	ds_write_b16_d16_hi v225, v230 offset:64
	v_mul_f32_e32 v232, 0xbfb8aa3b, v81
	v_mul_f32_e32 v233, 0xbfb8aa3b, v65
	v_exp_f32_e32 v232, v232
	v_exp_f32_e32 v233, v233
	v_add_f32_e32 v232, 1.0, v232
	v_add_f32_e32 v233, 1.0, v233
	v_rcp_f32_e32 v232, v232
	v_rcp_f32_e32 v233, v233
	v_mul_f32_e32 v232, v81, v232
	v_mul_f32_e32 v233, v65, v233
	v_cvt_pk_bf16_f32 v232, v232, v233
	ds_write_b16 v225, v232 offset:144
	ds_write_b16_d16_hi v225, v232 offset:208
	v_mul_f32_e32 v230, 0xbfb8aa3b, v82
	v_mul_f32_e32 v231, 0xbfb8aa3b, v66
	v_exp_f32_e32 v230, v230
	v_exp_f32_e32 v231, v231
	v_add_f32_e32 v230, 1.0, v230
	v_add_f32_e32 v231, 1.0, v231
	v_rcp_f32_e32 v230, v230
	v_rcp_f32_e32 v231, v231
	v_mul_f32_e32 v230, v82, v230
	v_mul_f32_e32 v231, v66, v231
	v_cvt_pk_bf16_f32 v230, v230, v231
	ds_write_b16 v225, v230 offset:288
	ds_write_b16_d16_hi v225, v230 offset:352
	v_mul_f32_e32 v232, 0xbfb8aa3b, v83
	v_mul_f32_e32 v233, 0xbfb8aa3b, v67
	v_exp_f32_e32 v232, v232
	v_exp_f32_e32 v233, v233
	v_add_f32_e32 v232, 1.0, v232
	v_add_f32_e32 v233, 1.0, v233
	v_rcp_f32_e32 v232, v232
	v_rcp_f32_e32 v233, v233
	v_mul_f32_e32 v232, v83, v232
	v_mul_f32_e32 v233, v67, v233
	v_cvt_pk_bf16_f32 v232, v232, v233
	ds_write_b16 v225, v232 offset:432
	ds_write_b16_d16_hi v225, v232 offset:496
	v_mul_f32_e32 v230, 0xbfb8aa3b, v84
	v_mul_f32_e32 v231, 0xbfb8aa3b, v68
	v_exp_f32_e32 v230, v230
	v_exp_f32_e32 v231, v231
	v_add_f32_e32 v230, 1.0, v230
	v_add_f32_e32 v231, 1.0, v231
	v_rcp_f32_e32 v230, v230
	v_rcp_f32_e32 v231, v231
	v_mul_f32_e32 v230, v84, v230
	v_mul_f32_e32 v231, v68, v231
	v_cvt_pk_bf16_f32 v230, v230, v231
	ds_write_b16 v225, v230 offset:1152
	ds_write_b16_d16_hi v225, v230 offset:1216
	v_mul_f32_e32 v232, 0xbfb8aa3b, v85
	v_mul_f32_e32 v233, 0xbfb8aa3b, v69
	v_exp_f32_e32 v232, v232
	v_exp_f32_e32 v233, v233
	v_add_f32_e32 v232, 1.0, v232
	v_add_f32_e32 v233, 1.0, v233
	v_rcp_f32_e32 v232, v232
	v_rcp_f32_e32 v233, v233
	v_mul_f32_e32 v232, v85, v232
	v_mul_f32_e32 v233, v69, v233
	v_cvt_pk_bf16_f32 v232, v232, v233
	ds_write_b16 v225, v232 offset:1296
	ds_write_b16_d16_hi v225, v232 offset:1360
	v_mul_f32_e32 v230, 0xbfb8aa3b, v86
	v_mul_f32_e32 v231, 0xbfb8aa3b, v70
	v_exp_f32_e32 v230, v230
	v_exp_f32_e32 v231, v231
	v_add_f32_e32 v230, 1.0, v230
	v_add_f32_e32 v231, 1.0, v231
	v_rcp_f32_e32 v230, v230
	v_rcp_f32_e32 v231, v231
	v_mul_f32_e32 v230, v86, v230
	v_mul_f32_e32 v231, v70, v231
	v_cvt_pk_bf16_f32 v230, v230, v231
	ds_write_b16 v225, v230 offset:1440
	ds_write_b16_d16_hi v225, v230 offset:1504
	v_mul_f32_e32 v232, 0xbfb8aa3b, v87
	v_mul_f32_e32 v233, 0xbfb8aa3b, v71
	v_exp_f32_e32 v232, v232
	v_exp_f32_e32 v233, v233
	v_add_f32_e32 v232, 1.0, v232
	v_add_f32_e32 v233, 1.0, v233
	v_rcp_f32_e32 v232, v232
	v_rcp_f32_e32 v233, v233
	v_mul_f32_e32 v232, v87, v232
	v_mul_f32_e32 v233, v71, v233
	v_cvt_pk_bf16_f32 v232, v232, v233
	ds_write_b16 v225, v232 offset:1584
	ds_write_b16_d16_hi v225, v232 offset:1648
	v_mul_f32_e32 v230, 0xbfb8aa3b, v88
	v_mul_f32_e32 v231, 0xbfb8aa3b, v72
	v_exp_f32_e32 v230, v230
	v_exp_f32_e32 v231, v231
	v_add_f32_e32 v230, 1.0, v230
	v_add_f32_e32 v231, 1.0, v231
	v_rcp_f32_e32 v230, v230
	v_rcp_f32_e32 v231, v231
	v_mul_f32_e32 v230, v88, v230
	v_mul_f32_e32 v231, v72, v231
	v_cvt_pk_bf16_f32 v230, v230, v231
	ds_write_b16 v225, v230 offset:2304
	ds_write_b16_d16_hi v225, v230 offset:2368
	v_mul_f32_e32 v232, 0xbfb8aa3b, v89
	v_mul_f32_e32 v233, 0xbfb8aa3b, v73
	v_exp_f32_e32 v232, v232
	v_exp_f32_e32 v233, v233
	v_add_f32_e32 v232, 1.0, v232
	v_add_f32_e32 v233, 1.0, v233
	v_rcp_f32_e32 v232, v232
	v_rcp_f32_e32 v233, v233
	v_mul_f32_e32 v232, v89, v232
	v_mul_f32_e32 v233, v73, v233
	v_cvt_pk_bf16_f32 v232, v232, v233
	ds_write_b16 v225, v232 offset:2448
	ds_write_b16_d16_hi v225, v232 offset:2512
	v_mul_f32_e32 v230, 0xbfb8aa3b, v90
	v_mul_f32_e32 v231, 0xbfb8aa3b, v74
	v_exp_f32_e32 v230, v230
	v_exp_f32_e32 v231, v231
	v_add_f32_e32 v230, 1.0, v230
	v_add_f32_e32 v231, 1.0, v231
	v_rcp_f32_e32 v230, v230
	v_rcp_f32_e32 v231, v231
	v_mul_f32_e32 v230, v90, v230
	v_mul_f32_e32 v231, v74, v231
	v_cvt_pk_bf16_f32 v230, v230, v231
	ds_write_b16 v225, v230 offset:2592
	ds_write_b16_d16_hi v225, v230 offset:2656
	v_mul_f32_e32 v232, 0xbfb8aa3b, v91
	v_mul_f32_e32 v233, 0xbfb8aa3b, v75
	v_exp_f32_e32 v232, v232
	v_exp_f32_e32 v233, v233
	v_add_f32_e32 v232, 1.0, v232
	v_add_f32_e32 v233, 1.0, v233
	v_rcp_f32_e32 v232, v232
	v_rcp_f32_e32 v233, v233
	v_mul_f32_e32 v232, v91, v232
	v_mul_f32_e32 v233, v75, v233
	v_cvt_pk_bf16_f32 v232, v232, v233
	ds_write_b16 v225, v232 offset:2736
	ds_write_b16_d16_hi v225, v232 offset:2800
	v_mul_f32_e32 v230, 0xbfb8aa3b, v92
	v_mul_f32_e32 v231, 0xbfb8aa3b, v76
	v_exp_f32_e32 v230, v230
	v_exp_f32_e32 v231, v231
	v_add_f32_e32 v230, 1.0, v230
	v_add_f32_e32 v231, 1.0, v231
	v_rcp_f32_e32 v230, v230
	v_rcp_f32_e32 v231, v231
	v_mul_f32_e32 v230, v92, v230
	v_mul_f32_e32 v231, v76, v231
	v_cvt_pk_bf16_f32 v230, v230, v231
	ds_write_b16 v225, v230 offset:3456
	ds_write_b16_d16_hi v225, v230 offset:3520
	v_mul_f32_e32 v232, 0xbfb8aa3b, v93
	v_mul_f32_e32 v233, 0xbfb8aa3b, v77
	v_exp_f32_e32 v232, v232
	v_exp_f32_e32 v233, v233
	v_add_f32_e32 v232, 1.0, v232
	v_add_f32_e32 v233, 1.0, v233
	v_rcp_f32_e32 v232, v232
	v_rcp_f32_e32 v233, v233
	v_mul_f32_e32 v232, v93, v232
	v_mul_f32_e32 v233, v77, v233
	v_cvt_pk_bf16_f32 v232, v232, v233
	ds_write_b16 v225, v232 offset:3600
	ds_write_b16_d16_hi v225, v232 offset:3664
	v_mul_f32_e32 v230, 0xbfb8aa3b, v94
	v_mul_f32_e32 v231, 0xbfb8aa3b, v78
	v_exp_f32_e32 v230, v230
	v_exp_f32_e32 v231, v231
	v_add_f32_e32 v230, 1.0, v230
	v_add_f32_e32 v231, 1.0, v231
	v_rcp_f32_e32 v230, v230
	v_rcp_f32_e32 v231, v231
	v_mul_f32_e32 v230, v94, v230
	v_mul_f32_e32 v231, v78, v231
	v_cvt_pk_bf16_f32 v230, v230, v231
	ds_write_b16 v225, v230 offset:3744
	ds_write_b16_d16_hi v225, v230 offset:3808
	v_mul_f32_e32 v232, 0xbfb8aa3b, v95
	v_mul_f32_e32 v233, 0xbfb8aa3b, v79
	v_exp_f32_e32 v232, v232
	v_exp_f32_e32 v233, v233
	v_add_f32_e32 v232, 1.0, v232
	v_add_f32_e32 v233, 1.0, v233
	v_rcp_f32_e32 v232, v232
	v_rcp_f32_e32 v233, v233
	v_mul_f32_e32 v232, v95, v232
	v_mul_f32_e32 v233, v79, v233
	v_cvt_pk_bf16_f32 v232, v232, v233
	ds_write_b16 v225, v232 offset:3888
	ds_write_b16_d16_hi v225, v232 offset:3952
	s_branch .Lep2_01_st

.Lep2_01_end:
.Lep2_10:
	s_add_u32 s94, s92, 32
	s_add_u32 s95, s93, 0
	s_lshr_b32 s90, s95, 6
	s_cmp_lt_u32 s90, 16
	s_cbranch_scc1 .Lep2_10_t0
	s_cmp_lt_u32 s90, 18
	s_cbranch_scc1 .Lep2_10_t16
	s_cmp_lt_u32 s90, 20
	s_cbranch_scc1 .Lep2_10_t18
	s_cmp_lt_u32 s90, 36
	s_cbranch_scc1 .Lep2_10_t20
	s_branch .Lep2_10_end

.Lep2_10_mP:
	v_cvt_pk_bf16_f32 v230, v48, v32
	ds_write_b16 v225, v230
	ds_write_b16_d16_hi v225, v230 offset:64
	v_cvt_pk_bf16_f32 v231, v49, v33
	ds_write_b16 v225, v231 offset:144
	ds_write_b16_d16_hi v225, v231 offset:208
	v_cvt_pk_bf16_f32 v232, v50, v34
	ds_write_b16 v225, v232 offset:288
	ds_write_b16_d16_hi v225, v232 offset:352
	v_cvt_pk_bf16_f32 v233, v51, v35
	ds_write_b16 v225, v233 offset:432
	ds_write_b16_d16_hi v225, v233 offset:496
	v_cvt_pk_bf16_f32 v230, v52, v36
	ds_write_b16 v225, v230 offset:1152
	ds_write_b16_d16_hi v225, v230 offset:1216
	v_cvt_pk_bf16_f32 v231, v53, v37
	ds_write_b16 v225, v231 offset:1296
	ds_write_b16_d16_hi v225, v231 offset:1360
	v_cvt_pk_bf16_f32 v232, v54, v38
	ds_write_b16 v225, v232 offset:1440
	ds_write_b16_d16_hi v225, v232 offset:1504
	v_cvt_pk_bf16_f32 v233, v55, v39
	ds_write_b16 v225, v233 offset:1584
	ds_write_b16_d16_hi v225, v233 offset:1648
	v_cvt_pk_bf16_f32 v230, v56, v40
	ds_write_b16 v225, v230 offset:2304
	ds_write_b16_d16_hi v225, v230 offset:2368
	v_cvt_pk_bf16_f32 v231, v57, v41
	ds_write_b16 v225, v231 offset:2448
	ds_write_b16_d16_hi v225, v231 offset:2512
	v_cvt_pk_bf16_f32 v232, v58, v42
	ds_write_b16 v225, v232 offset:2592
	ds_write_b16_d16_hi v225, v232 offset:2656
	v_cvt_pk_bf16_f32 v233, v59, v43
	ds_write_b16 v225, v233 offset:2736
	ds_write_b16_d16_hi v225, v233 offset:2800
	v_cvt_pk_bf16_f32 v230, v60, v44
	ds_write_b16 v225, v230 offset:3456
	ds_write_b16_d16_hi v225, v230 offset:3520
	v_cvt_pk_bf16_f32 v231, v61, v45
	ds_write_b16 v225, v231 offset:3600
	ds_write_b16_d16_hi v225, v231 offset:3664
	v_cvt_pk_bf16_f32 v232, v62, v46
	ds_write_b16 v225, v232 offset:3744
	ds_write_b16_d16_hi v225, v232 offset:3808
	v_cvt_pk_bf16_f32 v233, v63, v47
	ds_write_b16 v225, v233 offset:3888
	ds_write_b16_d16_hi v225, v233 offset:3952
	s_branch .Lep2_10_st
.Lep2_10_mR:
	v_add_u32_e32 v230, s94, v227
	v_lshlrev_b32_e32 v230, 8, v230
	v_add_u32_e32 v236, v230, v224
	v_mov_b32_e32 v237, 0
	s_waitcnt lgkmcnt(0)
	v_lshl_add_u64 v[236:237], s[98:99], 0, v[236:237]
	global_load_dwordx2 v[128:129], v[236:237], off
	global_load_dwordx2 v[130:131], v[236:237], off offset:256
	global_load_dwordx2 v[132:133], v[236:237], off offset:512
	global_load_dwordx2 v[134:135], v[236:237], off offset:768
	global_load_dwordx2 v[136:137], v[236:237], off offset:2048
	global_load_dwordx2 v[138:139], v[236:237], off offset:2304
	global_load_dwordx2 v[140:141], v[236:237], off offset:2560
	global_load_dwordx2 v[142:143], v[236:237], off offset:2816
	v_add_co_u32_e32 v238, vcc, 0x1000, v236
	s_nop 1
	v_addc_co_u32_e32 v239, vcc, 0, v237, vcc
	global_load_dwordx2 v[144:145], v[238:239], off
	global_load_dwordx2 v[146:147], v[238:239], off offset:256
	global_load_dwordx2 v[148:149], v[238:239], off offset:512
	global_load_dwordx2 v[150:151], v[238:239], off offset:768
	global_load_dwordx2 v[152:153], v[238:239], off offset:2048
	global_load_dwordx2 v[154:155], v[238:239], off offset:2304
	global_load_dwordx2 v[156:157], v[238:239], off offset:2560
	global_load_dwordx2 v[158:159], v[238:239], off offset:2816
	s_waitcnt vmcnt(15)
	v_mul_f32_e32 v230, v32, v129
	v_mul_f32_e32 v231, v48, v129
	v_fma_f32 v230, v48, v128, -v230
	v_fma_f32 v231, v32, v128, v231
	v_mul_f32_e32 v230, s88, v230
	v_mul_f32_e32 v231, s88, v231
	v_cvt_pk_bf16_f32 v230, v230, v231
	ds_write_b16 v225, v230
	ds_write_b16_d16_hi v225, v230 offset:64
	s_waitcnt vmcnt(14)
	v_mul_f32_e32 v230, v33, v131
	v_mul_f32_e32 v231, v49, v131
	v_fma_f32 v230, v49, v130, -v230
	v_fma_f32 v231, v33, v130, v231
	v_mul_f32_e32 v230, s88, v230
	v_mul_f32_e32 v231, s88, v231
	v_cvt_pk_bf16_f32 v230, v230, v231
	ds_write_b16 v225, v230 offset:144
	ds_write_b16_d16_hi v225, v230 offset:208
	s_waitcnt vmcnt(13)
	v_mul_f32_e32 v230, v34, v133
	v_mul_f32_e32 v231, v50, v133
	v_fma_f32 v230, v50, v132, -v230
	v_fma_f32 v231, v34, v132, v231
	v_mul_f32_e32 v230, s88, v230
	v_mul_f32_e32 v231, s88, v231
	v_cvt_pk_bf16_f32 v230, v230, v231
	ds_write_b16 v225, v230 offset:288
	ds_write_b16_d16_hi v225, v230 offset:352
	s_waitcnt vmcnt(12)
	v_mul_f32_e32 v230, v35, v135
	v_mul_f32_e32 v231, v51, v135
	v_fma_f32 v230, v51, v134, -v230
	v_fma_f32 v231, v35, v134, v231
	v_mul_f32_e32 v230, s88, v230
	v_mul_f32_e32 v231, s88, v231
	v_cvt_pk_bf16_f32 v230, v230, v231
	ds_write_b16 v225, v230 offset:432
	ds_write_b16_d16_hi v225, v230 offset:496
	s_waitcnt vmcnt(11)
	v_mul_f32_e32 v230, v36, v137
	v_mul_f32_e32 v231, v52, v137
	v_fma_f32 v230, v52, v136, -v230
	v_fma_f32 v231, v36, v136, v231
	v_mul_f32_e32 v230, s88, v230
	v_mul_f32_e32 v231, s88, v231
	v_cvt_pk_bf16_f32 v230, v230, v231
	ds_write_b16 v225, v230 offset:1152
	ds_write_b16_d16_hi v225, v230 offset:1216
	s_waitcnt vmcnt(10)
	v_mul_f32_e32 v230, v37, v139
	v_mul_f32_e32 v231, v53, v139
	v_fma_f32 v230, v53, v138, -v230
	v_fma_f32 v231, v37, v138, v231
	v_mul_f32_e32 v230, s88, v230
	v_mul_f32_e32 v231, s88, v231
	v_cvt_pk_bf16_f32 v230, v230, v231
	ds_write_b16 v225, v230 offset:1296
	ds_write_b16_d16_hi v225, v230 offset:1360
	s_waitcnt vmcnt(9)
	v_mul_f32_e32 v230, v38, v141
	v_mul_f32_e32 v231, v54, v141
	v_fma_f32 v230, v54, v140, -v230
	v_fma_f32 v231, v38, v140, v231
	v_mul_f32_e32 v230, s88, v230
	v_mul_f32_e32 v231, s88, v231
	v_cvt_pk_bf16_f32 v230, v230, v231
	ds_write_b16 v225, v230 offset:1440
	ds_write_b16_d16_hi v225, v230 offset:1504
	s_waitcnt vmcnt(8)
	v_mul_f32_e32 v230, v39, v143
	v_mul_f32_e32 v231, v55, v143
	v_fma_f32 v230, v55, v142, -v230
	v_fma_f32 v231, v39, v142, v231
	v_mul_f32_e32 v230, s88, v230
	v_mul_f32_e32 v231, s88, v231
	v_cvt_pk_bf16_f32 v230, v230, v231
	ds_write_b16 v225, v230 offset:1584
	ds_write_b16_d16_hi v225, v230 offset:1648
	s_waitcnt vmcnt(7)
	v_mul_f32_e32 v230, v40, v145
	v_mul_f32_e32 v231, v56, v145
	v_fma_f32 v230, v56, v144, -v230
	v_fma_f32 v231, v40, v144, v231
	v_mul_f32_e32 v230, s88, v230
	v_mul_f32_e32 v231, s88, v231
	v_cvt_pk_bf16_f32 v230, v230, v231
	ds_write_b16 v225, v230 offset:2304
	ds_write_b16_d16_hi v225, v230 offset:2368
	s_waitcnt vmcnt(6)
	v_mul_f32_e32 v230, v41, v147
	v_mul_f32_e32 v231, v57, v147
	v_fma_f32 v230, v57, v146, -v230
	v_fma_f32 v231, v41, v146, v231
	v_mul_f32_e32 v230, s88, v230
	v_mul_f32_e32 v231, s88, v231
	v_cvt_pk_bf16_f32 v230, v230, v231
	ds_write_b16 v225, v230 offset:2448
	ds_write_b16_d16_hi v225, v230 offset:2512
	s_waitcnt vmcnt(5)
	v_mul_f32_e32 v230, v42, v149
	v_mul_f32_e32 v231, v58, v149
	v_fma_f32 v230, v58, v148, -v230
	v_fma_f32 v231, v42, v148, v231
	v_mul_f32_e32 v230, s88, v230
	v_mul_f32_e32 v231, s88, v231
	v_cvt_pk_bf16_f32 v230, v230, v231
	ds_write_b16 v225, v230 offset:2592
	ds_write_b16_d16_hi v225, v230 offset:2656
	s_waitcnt vmcnt(4)
	v_mul_f32_e32 v230, v43, v151
	v_mul_f32_e32 v231, v59, v151
	v_fma_f32 v230, v59, v150, -v230
	v_fma_f32 v231, v43, v150, v231
	v_mul_f32_e32 v230, s88, v230
	v_mul_f32_e32 v231, s88, v231
	v_cvt_pk_bf16_f32 v230, v230, v231
	ds_write_b16 v225, v230 offset:2736
	ds_write_b16_d16_hi v225, v230 offset:2800
	s_waitcnt vmcnt(3)
	v_mul_f32_e32 v230, v44, v153
	v_mul_f32_e32 v231, v60, v153
	v_fma_f32 v230, v60, v152, -v230
	v_fma_f32 v231, v44, v152, v231
	v_mul_f32_e32 v230, s88, v230
	v_mul_f32_e32 v231, s88, v231
	v_cvt_pk_bf16_f32 v230, v230, v231
	ds_write_b16 v225, v230 offset:3456
	ds_write_b16_d16_hi v225, v230 offset:3520
	s_waitcnt vmcnt(2)
	v_mul_f32_e32 v230, v45, v155
	v_mul_f32_e32 v231, v61, v155
	v_fma_f32 v230, v61, v154, -v230
	v_fma_f32 v231, v45, v154, v231
	v_mul_f32_e32 v230, s88, v230
	v_mul_f32_e32 v231, s88, v231
	v_cvt_pk_bf16_f32 v230, v230, v231
	ds_write_b16 v225, v230 offset:3600
	ds_write_b16_d16_hi v225, v230 offset:3664
	s_waitcnt vmcnt(1)
	v_mul_f32_e32 v230, v46, v157
	v_mul_f32_e32 v231, v62, v157
	v_fma_f32 v230, v62, v156, -v230
	v_fma_f32 v231, v46, v156, v231
	v_mul_f32_e32 v230, s88, v230
	v_mul_f32_e32 v231, s88, v231
	v_cvt_pk_bf16_f32 v230, v230, v231
	ds_write_b16 v225, v230 offset:3744
	ds_write_b16_d16_hi v225, v230 offset:3808
	s_waitcnt vmcnt(0)
	v_mul_f32_e32 v230, v47, v159
	v_mul_f32_e32 v231, v63, v159
	v_fma_f32 v230, v63, v158, -v230
	v_fma_f32 v231, v47, v158, v231
	v_mul_f32_e32 v230, s88, v230
	v_mul_f32_e32 v231, s88, v231
	v_cvt_pk_bf16_f32 v230, v230, v231
	ds_write_b16 v225, v230 offset:3888
	ds_write_b16_d16_hi v225, v230 offset:3952
	s_branch .Lep2_10_st
.Lep2_10_mS:
	v_mul_f32_e32 v230, 0xbfb8aa3b, v48
	v_mul_f32_e32 v231, 0xbfb8aa3b, v32
	v_exp_f32_e32 v230, v230
	v_exp_f32_e32 v231, v231
	v_add_f32_e32 v230, 1.0, v230
	v_add_f32_e32 v231, 1.0, v231
	v_rcp_f32_e32 v230, v230
	v_rcp_f32_e32 v231, v231
	v_mul_f32_e32 v230, v48, v230
	v_mul_f32_e32 v231, v32, v231
	v_cvt_pk_bf16_f32 v230, v230, v231
	ds_write_b16 v225, v230
	ds_write_b16_d16_hi v225, v230 offset:64
	v_mul_f32_e32 v232, 0xbfb8aa3b, v49
	v_mul_f32_e32 v233, 0xbfb8aa3b, v33
	v_exp_f32_e32 v232, v232
	v_exp_f32_e32 v233, v233
	v_add_f32_e32 v232, 1.0, v232
	v_add_f32_e32 v233, 1.0, v233
	v_rcp_f32_e32 v232, v232
	v_rcp_f32_e32 v233, v233
	v_mul_f32_e32 v232, v49, v232
	v_mul_f32_e32 v233, v33, v233
	v_cvt_pk_bf16_f32 v232, v232, v233
	ds_write_b16 v225, v232 offset:144
	ds_write_b16_d16_hi v225, v232 offset:208
	v_mul_f32_e32 v230, 0xbfb8aa3b, v50
	v_mul_f32_e32 v231, 0xbfb8aa3b, v34
	v_exp_f32_e32 v230, v230
	v_exp_f32_e32 v231, v231
	v_add_f32_e32 v230, 1.0, v230
	v_add_f32_e32 v231, 1.0, v231
	v_rcp_f32_e32 v230, v230
	v_rcp_f32_e32 v231, v231
	v_mul_f32_e32 v230, v50, v230
	v_mul_f32_e32 v231, v34, v231
	v_cvt_pk_bf16_f32 v230, v230, v231
	ds_write_b16 v225, v230 offset:288
	ds_write_b16_d16_hi v225, v230 offset:352
	v_mul_f32_e32 v232, 0xbfb8aa3b, v51
	v_mul_f32_e32 v233, 0xbfb8aa3b, v35
	v_exp_f32_e32 v232, v232
	v_exp_f32_e32 v233, v233
	v_add_f32_e32 v232, 1.0, v232
	v_add_f32_e32 v233, 1.0, v233
	v_rcp_f32_e32 v232, v232
	v_rcp_f32_e32 v233, v233
	v_mul_f32_e32 v232, v51, v232
	v_mul_f32_e32 v233, v35, v233
	v_cvt_pk_bf16_f32 v232, v232, v233
	ds_write_b16 v225, v232 offset:432
	ds_write_b16_d16_hi v225, v232 offset:496
	v_mul_f32_e32 v230, 0xbfb8aa3b, v52
	v_mul_f32_e32 v231, 0xbfb8aa3b, v36
	v_exp_f32_e32 v230, v230
	v_exp_f32_e32 v231, v231
	v_add_f32_e32 v230, 1.0, v230
	v_add_f32_e32 v231, 1.0, v231
	v_rcp_f32_e32 v230, v230
	v_rcp_f32_e32 v231, v231
	v_mul_f32_e32 v230, v52, v230
	v_mul_f32_e32 v231, v36, v231
	v_cvt_pk_bf16_f32 v230, v230, v231
	ds_write_b16 v225, v230 offset:1152
	ds_write_b16_d16_hi v225, v230 offset:1216
	v_mul_f32_e32 v232, 0xbfb8aa3b, v53
	v_mul_f32_e32 v233, 0xbfb8aa3b, v37
	v_exp_f32_e32 v232, v232
	v_exp_f32_e32 v233, v233
	v_add_f32_e32 v232, 1.0, v232
	v_add_f32_e32 v233, 1.0, v233
	v_rcp_f32_e32 v232, v232
	v_rcp_f32_e32 v233, v233
	v_mul_f32_e32 v232, v53, v232
	v_mul_f32_e32 v233, v37, v233
	v_cvt_pk_bf16_f32 v232, v232, v233
	ds_write_b16 v225, v232 offset:1296
	ds_write_b16_d16_hi v225, v232 offset:1360
	v_mul_f32_e32 v230, 0xbfb8aa3b, v54
	v_mul_f32_e32 v231, 0xbfb8aa3b, v38
	v_exp_f32_e32 v230, v230
	v_exp_f32_e32 v231, v231
	v_add_f32_e32 v230, 1.0, v230
	v_add_f32_e32 v231, 1.0, v231
	v_rcp_f32_e32 v230, v230
	v_rcp_f32_e32 v231, v231
	v_mul_f32_e32 v230, v54, v230
	v_mul_f32_e32 v231, v38, v231
	v_cvt_pk_bf16_f32 v230, v230, v231
	ds_write_b16 v225, v230 offset:1440
	ds_write_b16_d16_hi v225, v230 offset:1504
	v_mul_f32_e32 v232, 0xbfb8aa3b, v55
	v_mul_f32_e32 v233, 0xbfb8aa3b, v39
	v_exp_f32_e32 v232, v232
	v_exp_f32_e32 v233, v233
	v_add_f32_e32 v232, 1.0, v232
	v_add_f32_e32 v233, 1.0, v233
	v_rcp_f32_e32 v232, v232
	v_rcp_f32_e32 v233, v233
	v_mul_f32_e32 v232, v55, v232
	v_mul_f32_e32 v233, v39, v233
	v_cvt_pk_bf16_f32 v232, v232, v233
	ds_write_b16 v225, v232 offset:1584
	ds_write_b16_d16_hi v225, v232 offset:1648
	v_mul_f32_e32 v230, 0xbfb8aa3b, v56
	v_mul_f32_e32 v231, 0xbfb8aa3b, v40
	v_exp_f32_e32 v230, v230
	v_exp_f32_e32 v231, v231
	v_add_f32_e32 v230, 1.0, v230
	v_add_f32_e32 v231, 1.0, v231
	v_rcp_f32_e32 v230, v230
	v_rcp_f32_e32 v231, v231
	v_mul_f32_e32 v230, v56, v230
	v_mul_f32_e32 v231, v40, v231
	v_cvt_pk_bf16_f32 v230, v230, v231
	ds_write_b16 v225, v230 offset:2304
	ds_write_b16_d16_hi v225, v230 offset:2368
	v_mul_f32_e32 v232, 0xbfb8aa3b, v57
	v_mul_f32_e32 v233, 0xbfb8aa3b, v41
	v_exp_f32_e32 v232, v232
	v_exp_f32_e32 v233, v233
	v_add_f32_e32 v232, 1.0, v232
	v_add_f32_e32 v233, 1.0, v233
	v_rcp_f32_e32 v232, v232
	v_rcp_f32_e32 v233, v233
	v_mul_f32_e32 v232, v57, v232
	v_mul_f32_e32 v233, v41, v233
	v_cvt_pk_bf16_f32 v232, v232, v233
	ds_write_b16 v225, v232 offset:2448
	ds_write_b16_d16_hi v225, v232 offset:2512
	v_mul_f32_e32 v230, 0xbfb8aa3b, v58
	v_mul_f32_e32 v231, 0xbfb8aa3b, v42
	v_exp_f32_e32 v230, v230
	v_exp_f32_e32 v231, v231
	v_add_f32_e32 v230, 1.0, v230
	v_add_f32_e32 v231, 1.0, v231
	v_rcp_f32_e32 v230, v230
	v_rcp_f32_e32 v231, v231
	v_mul_f32_e32 v230, v58, v230
	v_mul_f32_e32 v231, v42, v231
	v_cvt_pk_bf16_f32 v230, v230, v231
	ds_write_b16 v225, v230 offset:2592
	ds_write_b16_d16_hi v225, v230 offset:2656
	v_mul_f32_e32 v232, 0xbfb8aa3b, v59
	v_mul_f32_e32 v233, 0xbfb8aa3b, v43
	v_exp_f32_e32 v232, v232
	v_exp_f32_e32 v233, v233
	v_add_f32_e32 v232, 1.0, v232
	v_add_f32_e32 v233, 1.0, v233
	v_rcp_f32_e32 v232, v232
	v_rcp_f32_e32 v233, v233
	v_mul_f32_e32 v232, v59, v232
	v_mul_f32_e32 v233, v43, v233
	v_cvt_pk_bf16_f32 v232, v232, v233
	ds_write_b16 v225, v232 offset:2736
	ds_write_b16_d16_hi v225, v232 offset:2800
	v_mul_f32_e32 v230, 0xbfb8aa3b, v60
	v_mul_f32_e32 v231, 0xbfb8aa3b, v44
	v_exp_f32_e32 v230, v230
	v_exp_f32_e32 v231, v231
	v_add_f32_e32 v230, 1.0, v230
	v_add_f32_e32 v231, 1.0, v231
	v_rcp_f32_e32 v230, v230
	v_rcp_f32_e32 v231, v231
	v_mul_f32_e32 v230, v60, v230
	v_mul_f32_e32 v231, v44, v231
	v_cvt_pk_bf16_f32 v230, v230, v231
	ds_write_b16 v225, v230 offset:3456
	ds_write_b16_d16_hi v225, v230 offset:3520
	v_mul_f32_e32 v232, 0xbfb8aa3b, v61
	v_mul_f32_e32 v233, 0xbfb8aa3b, v45
	v_exp_f32_e32 v232, v232
	v_exp_f32_e32 v233, v233
	v_add_f32_e32 v232, 1.0, v232
	v_add_f32_e32 v233, 1.0, v233
	v_rcp_f32_e32 v232, v232
	v_rcp_f32_e32 v233, v233
	v_mul_f32_e32 v232, v61, v232
	v_mul_f32_e32 v233, v45, v233
	v_cvt_pk_bf16_f32 v232, v232, v233
	ds_write_b16 v225, v232 offset:3600
	ds_write_b16_d16_hi v225, v232 offset:3664
	v_mul_f32_e32 v230, 0xbfb8aa3b, v62
	v_mul_f32_e32 v231, 0xbfb8aa3b, v46
	v_exp_f32_e32 v230, v230
	v_exp_f32_e32 v231, v231
	v_add_f32_e32 v230, 1.0, v230
	v_add_f32_e32 v231, 1.0, v231
	v_rcp_f32_e32 v230, v230
	v_rcp_f32_e32 v231, v231
	v_mul_f32_e32 v230, v62, v230
	v_mul_f32_e32 v231, v46, v231
	v_cvt_pk_bf16_f32 v230, v230, v231
	ds_write_b16 v225, v230 offset:3744
	ds_write_b16_d16_hi v225, v230 offset:3808
	v_mul_f32_e32 v232, 0xbfb8aa3b, v63
	v_mul_f32_e32 v233, 0xbfb8aa3b, v47
	v_exp_f32_e32 v232, v232
	v_exp_f32_e32 v233, v233
	v_add_f32_e32 v232, 1.0, v232
	v_add_f32_e32 v233, 1.0, v233
	v_rcp_f32_e32 v232, v232
	v_rcp_f32_e32 v233, v233
	v_mul_f32_e32 v232, v63, v232
	v_mul_f32_e32 v233, v47, v233
	v_cvt_pk_bf16_f32 v232, v232, v233
	ds_write_b16 v225, v232 offset:3888
	ds_write_b16_d16_hi v225, v232 offset:3952
	s_branch .Lep2_10_st

.Lep2_10_end:
.Lep2_11:
	s_add_u32 s94, s92, 32
	s_add_u32 s95, s93, 64
	s_lshr_b32 s90, s95, 6
	s_cmp_lt_u32 s90, 16
	s_cbranch_scc1 .Lep2_11_t0
	s_cmp_lt_u32 s90, 18
	s_cbranch_scc1 .Lep2_11_t16
	s_cmp_lt_u32 s90, 20
	s_cbranch_scc1 .Lep2_11_t18
	s_cmp_lt_u32 s90, 36
	s_cbranch_scc1 .Lep2_11_t20
	s_branch .Lep2_11_end

.Lep2_11_mP:
	v_cvt_pk_bf16_f32 v230, v16, v0
	ds_write_b16 v225, v230
	ds_write_b16_d16_hi v225, v230 offset:64
	v_cvt_pk_bf16_f32 v231, v17, v1
	ds_write_b16 v225, v231 offset:144
	ds_write_b16_d16_hi v225, v231 offset:208
	v_cvt_pk_bf16_f32 v232, v18, v2
	ds_write_b16 v225, v232 offset:288
	ds_write_b16_d16_hi v225, v232 offset:352
	v_cvt_pk_bf16_f32 v233, v19, v3
	ds_write_b16 v225, v233 offset:432
	ds_write_b16_d16_hi v225, v233 offset:496
	v_cvt_pk_bf16_f32 v230, v20, v4
	ds_write_b16 v225, v230 offset:1152
	ds_write_b16_d16_hi v225, v230 offset:1216
	v_cvt_pk_bf16_f32 v231, v21, v5
	ds_write_b16 v225, v231 offset:1296
	ds_write_b16_d16_hi v225, v231 offset:1360
	v_cvt_pk_bf16_f32 v232, v22, v6
	ds_write_b16 v225, v232 offset:1440
	ds_write_b16_d16_hi v225, v232 offset:1504
	v_cvt_pk_bf16_f32 v233, v23, v7
	ds_write_b16 v225, v233 offset:1584
	ds_write_b16_d16_hi v225, v233 offset:1648
	v_cvt_pk_bf16_f32 v230, v24, v8
	ds_write_b16 v225, v230 offset:2304
	ds_write_b16_d16_hi v225, v230 offset:2368
	v_cvt_pk_bf16_f32 v231, v25, v9
	ds_write_b16 v225, v231 offset:2448
	ds_write_b16_d16_hi v225, v231 offset:2512
	v_cvt_pk_bf16_f32 v232, v26, v10
	ds_write_b16 v225, v232 offset:2592
	ds_write_b16_d16_hi v225, v232 offset:2656
	v_cvt_pk_bf16_f32 v233, v27, v11
	ds_write_b16 v225, v233 offset:2736
	ds_write_b16_d16_hi v225, v233 offset:2800
	v_cvt_pk_bf16_f32 v230, v28, v12
	ds_write_b16 v225, v230 offset:3456
	ds_write_b16_d16_hi v225, v230 offset:3520
	v_cvt_pk_bf16_f32 v231, v29, v13
	ds_write_b16 v225, v231 offset:3600
	ds_write_b16_d16_hi v225, v231 offset:3664
	v_cvt_pk_bf16_f32 v232, v30, v14
	ds_write_b16 v225, v232 offset:3744
	ds_write_b16_d16_hi v225, v232 offset:3808
	v_cvt_pk_bf16_f32 v233, v31, v15
	ds_write_b16 v225, v233 offset:3888
	ds_write_b16_d16_hi v225, v233 offset:3952
	s_branch .Lep2_11_st
.Lep2_11_mR:
	v_add_u32_e32 v230, s94, v227
	v_lshlrev_b32_e32 v230, 8, v230
	v_add_u32_e32 v236, v230, v224
	v_mov_b32_e32 v237, 0
	s_waitcnt lgkmcnt(0)
	v_lshl_add_u64 v[236:237], s[98:99], 0, v[236:237]
	global_load_dwordx2 v[128:129], v[236:237], off
	global_load_dwordx2 v[130:131], v[236:237], off offset:256
	global_load_dwordx2 v[132:133], v[236:237], off offset:512
	global_load_dwordx2 v[134:135], v[236:237], off offset:768
	global_load_dwordx2 v[136:137], v[236:237], off offset:2048
	global_load_dwordx2 v[138:139], v[236:237], off offset:2304
	global_load_dwordx2 v[140:141], v[236:237], off offset:2560
	global_load_dwordx2 v[142:143], v[236:237], off offset:2816
	v_add_co_u32_e32 v238, vcc, 0x1000, v236
	s_nop 1
	v_addc_co_u32_e32 v239, vcc, 0, v237, vcc
	global_load_dwordx2 v[144:145], v[238:239], off
	global_load_dwordx2 v[146:147], v[238:239], off offset:256
	global_load_dwordx2 v[148:149], v[238:239], off offset:512
	global_load_dwordx2 v[150:151], v[238:239], off offset:768
	global_load_dwordx2 v[152:153], v[238:239], off offset:2048
	global_load_dwordx2 v[154:155], v[238:239], off offset:2304
	global_load_dwordx2 v[156:157], v[238:239], off offset:2560
	global_load_dwordx2 v[158:159], v[238:239], off offset:2816
	s_waitcnt vmcnt(15)
	v_mul_f32_e32 v230, v0, v129
	v_mul_f32_e32 v231, v16, v129
	v_fma_f32 v230, v16, v128, -v230
	v_fma_f32 v231, v0, v128, v231
	v_mul_f32_e32 v230, s88, v230
	v_mul_f32_e32 v231, s88, v231
	v_cvt_pk_bf16_f32 v230, v230, v231
	ds_write_b16 v225, v230
	ds_write_b16_d16_hi v225, v230 offset:64
	s_waitcnt vmcnt(14)
	v_mul_f32_e32 v230, v1, v131
	v_mul_f32_e32 v231, v17, v131
	v_fma_f32 v230, v17, v130, -v230
	v_fma_f32 v231, v1, v130, v231
	v_mul_f32_e32 v230, s88, v230
	v_mul_f32_e32 v231, s88, v231
	v_cvt_pk_bf16_f32 v230, v230, v231
	ds_write_b16 v225, v230 offset:144
	ds_write_b16_d16_hi v225, v230 offset:208
	s_waitcnt vmcnt(13)
	v_mul_f32_e32 v230, v2, v133
	v_mul_f32_e32 v231, v18, v133
	v_fma_f32 v230, v18, v132, -v230
	v_fma_f32 v231, v2, v132, v231
	v_mul_f32_e32 v230, s88, v230
	v_mul_f32_e32 v231, s88, v231
	v_cvt_pk_bf16_f32 v230, v230, v231
	ds_write_b16 v225, v230 offset:288
	ds_write_b16_d16_hi v225, v230 offset:352
	s_waitcnt vmcnt(12)
	v_mul_f32_e32 v230, v3, v135
	v_mul_f32_e32 v231, v19, v135
	v_fma_f32 v230, v19, v134, -v230
	v_fma_f32 v231, v3, v134, v231
	v_mul_f32_e32 v230, s88, v230
	v_mul_f32_e32 v231, s88, v231
	v_cvt_pk_bf16_f32 v230, v230, v231
	ds_write_b16 v225, v230 offset:432
	ds_write_b16_d16_hi v225, v230 offset:496
	s_waitcnt vmcnt(11)
	v_mul_f32_e32 v230, v4, v137
	v_mul_f32_e32 v231, v20, v137
	v_fma_f32 v230, v20, v136, -v230
	v_fma_f32 v231, v4, v136, v231
	v_mul_f32_e32 v230, s88, v230
	v_mul_f32_e32 v231, s88, v231
	v_cvt_pk_bf16_f32 v230, v230, v231
	ds_write_b16 v225, v230 offset:1152
	ds_write_b16_d16_hi v225, v230 offset:1216
	s_waitcnt vmcnt(10)
	v_mul_f32_e32 v230, v5, v139
	v_mul_f32_e32 v231, v21, v139
	v_fma_f32 v230, v21, v138, -v230
	v_fma_f32 v231, v5, v138, v231
	v_mul_f32_e32 v230, s88, v230
	v_mul_f32_e32 v231, s88, v231
	v_cvt_pk_bf16_f32 v230, v230, v231
	ds_write_b16 v225, v230 offset:1296
	ds_write_b16_d16_hi v225, v230 offset:1360
	s_waitcnt vmcnt(9)
	v_mul_f32_e32 v230, v6, v141
	v_mul_f32_e32 v231, v22, v141
	v_fma_f32 v230, v22, v140, -v230
	v_fma_f32 v231, v6, v140, v231
	v_mul_f32_e32 v230, s88, v230
	v_mul_f32_e32 v231, s88, v231
	v_cvt_pk_bf16_f32 v230, v230, v231
	ds_write_b16 v225, v230 offset:1440
	ds_write_b16_d16_hi v225, v230 offset:1504
	s_waitcnt vmcnt(8)
	v_mul_f32_e32 v230, v7, v143
	v_mul_f32_e32 v231, v23, v143
	v_fma_f32 v230, v23, v142, -v230
	v_fma_f32 v231, v7, v142, v231
	v_mul_f32_e32 v230, s88, v230
	v_mul_f32_e32 v231, s88, v231
	v_cvt_pk_bf16_f32 v230, v230, v231
	ds_write_b16 v225, v230 offset:1584
	ds_write_b16_d16_hi v225, v230 offset:1648
	s_waitcnt vmcnt(7)
	v_mul_f32_e32 v230, v8, v145
	v_mul_f32_e32 v231, v24, v145
	v_fma_f32 v230, v24, v144, -v230
	v_fma_f32 v231, v8, v144, v231
	v_mul_f32_e32 v230, s88, v230
	v_mul_f32_e32 v231, s88, v231
	v_cvt_pk_bf16_f32 v230, v230, v231
	ds_write_b16 v225, v230 offset:2304
	ds_write_b16_d16_hi v225, v230 offset:2368
	s_waitcnt vmcnt(6)
	v_mul_f32_e32 v230, v9, v147
	v_mul_f32_e32 v231, v25, v147
	v_fma_f32 v230, v25, v146, -v230
	v_fma_f32 v231, v9, v146, v231
	v_mul_f32_e32 v230, s88, v230
	v_mul_f32_e32 v231, s88, v231
	v_cvt_pk_bf16_f32 v230, v230, v231
	ds_write_b16 v225, v230 offset:2448
	ds_write_b16_d16_hi v225, v230 offset:2512
	s_waitcnt vmcnt(5)
	v_mul_f32_e32 v230, v10, v149
	v_mul_f32_e32 v231, v26, v149
	v_fma_f32 v230, v26, v148, -v230
	v_fma_f32 v231, v10, v148, v231
	v_mul_f32_e32 v230, s88, v230
	v_mul_f32_e32 v231, s88, v231
	v_cvt_pk_bf16_f32 v230, v230, v231
	ds_write_b16 v225, v230 offset:2592
	ds_write_b16_d16_hi v225, v230 offset:2656
	s_waitcnt vmcnt(4)
	v_mul_f32_e32 v230, v11, v151
	v_mul_f32_e32 v231, v27, v151
	v_fma_f32 v230, v27, v150, -v230
	v_fma_f32 v231, v11, v150, v231
	v_mul_f32_e32 v230, s88, v230
	v_mul_f32_e32 v231, s88, v231
	v_cvt_pk_bf16_f32 v230, v230, v231
	ds_write_b16 v225, v230 offset:2736
	ds_write_b16_d16_hi v225, v230 offset:2800
	s_waitcnt vmcnt(3)
	v_mul_f32_e32 v230, v12, v153
	v_mul_f32_e32 v231, v28, v153
	v_fma_f32 v230, v28, v152, -v230
	v_fma_f32 v231, v12, v152, v231
	v_mul_f32_e32 v230, s88, v230
	v_mul_f32_e32 v231, s88, v231
	v_cvt_pk_bf16_f32 v230, v230, v231
	ds_write_b16 v225, v230 offset:3456
	ds_write_b16_d16_hi v225, v230 offset:3520
	s_waitcnt vmcnt(2)
	v_mul_f32_e32 v230, v13, v155
	v_mul_f32_e32 v231, v29, v155
	v_fma_f32 v230, v29, v154, -v230
	v_fma_f32 v231, v13, v154, v231
	v_mul_f32_e32 v230, s88, v230
	v_mul_f32_e32 v231, s88, v231
	v_cvt_pk_bf16_f32 v230, v230, v231
	ds_write_b16 v225, v230 offset:3600
	ds_write_b16_d16_hi v225, v230 offset:3664
	s_waitcnt vmcnt(1)
	v_mul_f32_e32 v230, v14, v157
	v_mul_f32_e32 v231, v30, v157
	v_fma_f32 v230, v30, v156, -v230
	v_fma_f32 v231, v14, v156, v231
	v_mul_f32_e32 v230, s88, v230
	v_mul_f32_e32 v231, s88, v231
	v_cvt_pk_bf16_f32 v230, v230, v231
	ds_write_b16 v225, v230 offset:3744
	ds_write_b16_d16_hi v225, v230 offset:3808
	s_waitcnt vmcnt(0)
	v_mul_f32_e32 v230, v15, v159
	v_mul_f32_e32 v231, v31, v159
	v_fma_f32 v230, v31, v158, -v230
	v_fma_f32 v231, v15, v158, v231
	v_mul_f32_e32 v230, s88, v230
	v_mul_f32_e32 v231, s88, v231
	v_cvt_pk_bf16_f32 v230, v230, v231
	ds_write_b16 v225, v230 offset:3888
	ds_write_b16_d16_hi v225, v230 offset:3952
	s_branch .Lep2_11_st
.Lep2_11_mS:
	v_mul_f32_e32 v230, 0xbfb8aa3b, v16
	v_mul_f32_e32 v231, 0xbfb8aa3b, v0
	v_exp_f32_e32 v230, v230
	v_exp_f32_e32 v231, v231
	v_add_f32_e32 v230, 1.0, v230
	v_add_f32_e32 v231, 1.0, v231
	v_rcp_f32_e32 v230, v230
	v_rcp_f32_e32 v231, v231
	v_mul_f32_e32 v230, v16, v230
	v_mul_f32_e32 v231, v0, v231
	v_cvt_pk_bf16_f32 v230, v230, v231
	ds_write_b16 v225, v230
	ds_write_b16_d16_hi v225, v230 offset:64
	v_mul_f32_e32 v232, 0xbfb8aa3b, v17
	v_mul_f32_e32 v233, 0xbfb8aa3b, v1
	v_exp_f32_e32 v232, v232
	v_exp_f32_e32 v233, v233
	v_add_f32_e32 v232, 1.0, v232
	v_add_f32_e32 v233, 1.0, v233
	v_rcp_f32_e32 v232, v232
	v_rcp_f32_e32 v233, v233
	v_mul_f32_e32 v232, v17, v232
	v_mul_f32_e32 v233, v1, v233
	v_cvt_pk_bf16_f32 v232, v232, v233
	ds_write_b16 v225, v232 offset:144
	ds_write_b16_d16_hi v225, v232 offset:208
	v_mul_f32_e32 v230, 0xbfb8aa3b, v18
	v_mul_f32_e32 v231, 0xbfb8aa3b, v2
	v_exp_f32_e32 v230, v230
	v_exp_f32_e32 v231, v231
	v_add_f32_e32 v230, 1.0, v230
	v_add_f32_e32 v231, 1.0, v231
	v_rcp_f32_e32 v230, v230
	v_rcp_f32_e32 v231, v231
	v_mul_f32_e32 v230, v18, v230
	v_mul_f32_e32 v231, v2, v231
	v_cvt_pk_bf16_f32 v230, v230, v231
	ds_write_b16 v225, v230 offset:288
	ds_write_b16_d16_hi v225, v230 offset:352
	v_mul_f32_e32 v232, 0xbfb8aa3b, v19
	v_mul_f32_e32 v233, 0xbfb8aa3b, v3
	v_exp_f32_e32 v232, v232
	v_exp_f32_e32 v233, v233
	v_add_f32_e32 v232, 1.0, v232
	v_add_f32_e32 v233, 1.0, v233
	v_rcp_f32_e32 v232, v232
	v_rcp_f32_e32 v233, v233
	v_mul_f32_e32 v232, v19, v232
	v_mul_f32_e32 v233, v3, v233
	v_cvt_pk_bf16_f32 v232, v232, v233
	ds_write_b16 v225, v232 offset:432
	ds_write_b16_d16_hi v225, v232 offset:496
	v_mul_f32_e32 v230, 0xbfb8aa3b, v20
	v_mul_f32_e32 v231, 0xbfb8aa3b, v4
	v_exp_f32_e32 v230, v230
	v_exp_f32_e32 v231, v231
	v_add_f32_e32 v230, 1.0, v230
	v_add_f32_e32 v231, 1.0, v231
	v_rcp_f32_e32 v230, v230
	v_rcp_f32_e32 v231, v231
	v_mul_f32_e32 v230, v20, v230
	v_mul_f32_e32 v231, v4, v231
	v_cvt_pk_bf16_f32 v230, v230, v231
	ds_write_b16 v225, v230 offset:1152
	ds_write_b16_d16_hi v225, v230 offset:1216
	v_mul_f32_e32 v232, 0xbfb8aa3b, v21
	v_mul_f32_e32 v233, 0xbfb8aa3b, v5
	v_exp_f32_e32 v232, v232
	v_exp_f32_e32 v233, v233
	v_add_f32_e32 v232, 1.0, v232
	v_add_f32_e32 v233, 1.0, v233
	v_rcp_f32_e32 v232, v232
	v_rcp_f32_e32 v233, v233
	v_mul_f32_e32 v232, v21, v232
	v_mul_f32_e32 v233, v5, v233
	v_cvt_pk_bf16_f32 v232, v232, v233
	ds_write_b16 v225, v232 offset:1296
	ds_write_b16_d16_hi v225, v232 offset:1360
	v_mul_f32_e32 v230, 0xbfb8aa3b, v22
	v_mul_f32_e32 v231, 0xbfb8aa3b, v6
	v_exp_f32_e32 v230, v230
	v_exp_f32_e32 v231, v231
	v_add_f32_e32 v230, 1.0, v230
	v_add_f32_e32 v231, 1.0, v231
	v_rcp_f32_e32 v230, v230
	v_rcp_f32_e32 v231, v231
	v_mul_f32_e32 v230, v22, v230
	v_mul_f32_e32 v231, v6, v231
	v_cvt_pk_bf16_f32 v230, v230, v231
	ds_write_b16 v225, v230 offset:1440
	ds_write_b16_d16_hi v225, v230 offset:1504
	v_mul_f32_e32 v232, 0xbfb8aa3b, v23
	v_mul_f32_e32 v233, 0xbfb8aa3b, v7
	v_exp_f32_e32 v232, v232
	v_exp_f32_e32 v233, v233
	v_add_f32_e32 v232, 1.0, v232
	v_add_f32_e32 v233, 1.0, v233
	v_rcp_f32_e32 v232, v232
	v_rcp_f32_e32 v233, v233
	v_mul_f32_e32 v232, v23, v232
	v_mul_f32_e32 v233, v7, v233
	v_cvt_pk_bf16_f32 v232, v232, v233
	ds_write_b16 v225, v232 offset:1584
	ds_write_b16_d16_hi v225, v232 offset:1648
	v_mul_f32_e32 v230, 0xbfb8aa3b, v24
	v_mul_f32_e32 v231, 0xbfb8aa3b, v8
	v_exp_f32_e32 v230, v230
	v_exp_f32_e32 v231, v231
	v_add_f32_e32 v230, 1.0, v230
	v_add_f32_e32 v231, 1.0, v231
	v_rcp_f32_e32 v230, v230
	v_rcp_f32_e32 v231, v231
	v_mul_f32_e32 v230, v24, v230
	v_mul_f32_e32 v231, v8, v231
	v_cvt_pk_bf16_f32 v230, v230, v231
	ds_write_b16 v225, v230 offset:2304
	ds_write_b16_d16_hi v225, v230 offset:2368
	v_mul_f32_e32 v232, 0xbfb8aa3b, v25
	v_mul_f32_e32 v233, 0xbfb8aa3b, v9
	v_exp_f32_e32 v232, v232
	v_exp_f32_e32 v233, v233
	v_add_f32_e32 v232, 1.0, v232
	v_add_f32_e32 v233, 1.0, v233
	v_rcp_f32_e32 v232, v232
	v_rcp_f32_e32 v233, v233
	v_mul_f32_e32 v232, v25, v232
	v_mul_f32_e32 v233, v9, v233
	v_cvt_pk_bf16_f32 v232, v232, v233
	ds_write_b16 v225, v232 offset:2448
	ds_write_b16_d16_hi v225, v232 offset:2512
	v_mul_f32_e32 v230, 0xbfb8aa3b, v26
	v_mul_f32_e32 v231, 0xbfb8aa3b, v10
	v_exp_f32_e32 v230, v230
	v_exp_f32_e32 v231, v231
	v_add_f32_e32 v230, 1.0, v230
	v_add_f32_e32 v231, 1.0, v231
	v_rcp_f32_e32 v230, v230
	v_rcp_f32_e32 v231, v231
	v_mul_f32_e32 v230, v26, v230
	v_mul_f32_e32 v231, v10, v231
	v_cvt_pk_bf16_f32 v230, v230, v231
	ds_write_b16 v225, v230 offset:2592
	ds_write_b16_d16_hi v225, v230 offset:2656
	v_mul_f32_e32 v232, 0xbfb8aa3b, v27
	v_mul_f32_e32 v233, 0xbfb8aa3b, v11
	v_exp_f32_e32 v232, v232
	v_exp_f32_e32 v233, v233
	v_add_f32_e32 v232, 1.0, v232
	v_add_f32_e32 v233, 1.0, v233
	v_rcp_f32_e32 v232, v232
	v_rcp_f32_e32 v233, v233
	v_mul_f32_e32 v232, v27, v232
	v_mul_f32_e32 v233, v11, v233
	v_cvt_pk_bf16_f32 v232, v232, v233
	ds_write_b16 v225, v232 offset:2736
	ds_write_b16_d16_hi v225, v232 offset:2800
	v_mul_f32_e32 v230, 0xbfb8aa3b, v28
	v_mul_f32_e32 v231, 0xbfb8aa3b, v12
	v_exp_f32_e32 v230, v230
	v_exp_f32_e32 v231, v231
	v_add_f32_e32 v230, 1.0, v230
	v_add_f32_e32 v231, 1.0, v231
	v_rcp_f32_e32 v230, v230
	v_rcp_f32_e32 v231, v231
	v_mul_f32_e32 v230, v28, v230
	v_mul_f32_e32 v231, v12, v231
	v_cvt_pk_bf16_f32 v230, v230, v231
	ds_write_b16 v225, v230 offset:3456
	ds_write_b16_d16_hi v225, v230 offset:3520
	v_mul_f32_e32 v232, 0xbfb8aa3b, v29
	v_mul_f32_e32 v233, 0xbfb8aa3b, v13
	v_exp_f32_e32 v232, v232
	v_exp_f32_e32 v233, v233
	v_add_f32_e32 v232, 1.0, v232
	v_add_f32_e32 v233, 1.0, v233
	v_rcp_f32_e32 v232, v232
	v_rcp_f32_e32 v233, v233
	v_mul_f32_e32 v232, v29, v232
	v_mul_f32_e32 v233, v13, v233
	v_cvt_pk_bf16_f32 v232, v232, v233
	ds_write_b16 v225, v232 offset:3600
	ds_write_b16_d16_hi v225, v232 offset:3664
	v_mul_f32_e32 v230, 0xbfb8aa3b, v30
	v_mul_f32_e32 v231, 0xbfb8aa3b, v14
	v_exp_f32_e32 v230, v230
	v_exp_f32_e32 v231, v231
	v_add_f32_e32 v230, 1.0, v230
	v_add_f32_e32 v231, 1.0, v231
	v_rcp_f32_e32 v230, v230
	v_rcp_f32_e32 v231, v231
	v_mul_f32_e32 v230, v30, v230
	v_mul_f32_e32 v231, v14, v231
	v_cvt_pk_bf16_f32 v230, v230, v231
	ds_write_b16 v225, v230 offset:3744
	ds_write_b16_d16_hi v225, v230 offset:3808
	v_mul_f32_e32 v232, 0xbfb8aa3b, v31
	v_mul_f32_e32 v233, 0xbfb8aa3b, v15
	v_exp_f32_e32 v232, v232
	v_exp_f32_e32 v233, v233
	v_add_f32_e32 v232, 1.0, v232
	v_add_f32_e32 v233, 1.0, v233
	v_rcp_f32_e32 v232, v232
	v_rcp_f32_e32 v233, v233
	v_mul_f32_e32 v232, v31, v232
	v_mul_f32_e32 v233, v15, v233
	v_cvt_pk_bf16_f32 v232, v232, v233
	ds_write_b16 v225, v232 offset:3888
	ds_write_b16_d16_hi v225, v232 offset:3952
	s_branch .Lep2_11_st

.Lep2_11_end:
	s_branch .LBB0_1465
.LBB0_2077:
	s_cmp_lt_i32 s45, 9
	s_cbranch_scc1 .LBB0_2131
	s_waitcnt vmcnt(0)
	v_cmp_eq_u32_e32 vcc, 0, v192
	s_waitcnt lgkmcnt(0)
	s_and_b64 s[4:5], s[46:47], vcc
	s_waitcnt vmcnt(63) expcnt(7) lgkmcnt(15)
	s_barrier
	s_and_saveexec_b64 s[2:3], s[4:5]
	s_cbranch_execz .LBB0_2130
	v_mov_b32_e32 v0, 0x24400
	s_waitcnt vmcnt(0) expcnt(0) lgkmcnt(0)
	ds_read_b32 v2, v0
	v_mov_b32_e32 v0, 0x24404
	ds_read_b32 v0, v0
	s_waitcnt lgkmcnt(1)
	v_cmp_ne_u32_e32 vcc, 0, v2
	s_cbranch_vccnz .LBB0_2094
	s_add_u32 s4, s40, 0x1000
	s_addc_u32 s5, s41, 0
	s_add_u32 s6, s40, 0x1100
	s_addc_u32 s7, s41, 0
	s_add_u32 s8, s40, 0x1200
	s_addc_u32 s9, s41, 0
	s_mul_i32 s18, s43, s33
	s_add_u32 s10, s40, 0x1300
	s_mul_i32 s18, s18, s42
	s_addc_u32 s11, s41, 0
	s_mov_b32 s19, 1
	v_mov_b32_e32 v16, 0
	s_branch .LBB0_2082

.LBB0_2413:
	ds_read_b128 v[128:131], v229
	ds_read_b128 v[136:139], v233
	ds_read_b128 v[132:135], v229 offset:4096
	ds_read_b128 v[140:143], v233 offset:4096
	ds_read_b128 v[144:147], v233 offset:8192
	ds_read_b128 v[148:151], v233 offset:12288
	s_waitcnt lgkmcnt(6)
	v_mfma_f32_32x32x16_bf16 v[112:127], v[202:205], v[212:215], v[112:127]
	v_mfma_f32_32x32x16_bf16 v[48:63], v[206:209], v[212:215], v[48:63]
	v_mfma_f32_32x32x16_bf16 v[96:111], v[202:205], v[216:219], v[96:111]
	v_mfma_f32_32x32x16_bf16 v[32:47], v[206:209], v[216:219], v[32:47]
	v_mfma_f32_32x32x16_bf16 v[80:95], v[202:205], v[220:223], v[80:95]
	v_mfma_f32_32x32x16_bf16 v[16:31], v[206:209], v[220:223], v[16:31]
	v_mfma_f32_32x32x16_bf16 v[64:79], v[202:205], v[224:227], v[64:79]
	v_mfma_f32_32x32x16_bf16 v[0:15], v[206:209], v[224:227], v[0:15]
	ds_read_b128 v[202:205], v230
	ds_read_b128 v[212:215], v234
	ds_read_b128 v[206:209], v230 offset:4096
	ds_read_b128 v[216:219], v234 offset:4096
	ds_read_b128 v[220:223], v234 offset:8192
	ds_read_b128 v[224:227], v234 offset:12288
	s_waitcnt lgkmcnt(6)
	v_mfma_f32_32x32x16_bf16 v[112:127], v[128:131], v[136:139], v[112:127]
	v_mfma_f32_32x32x16_bf16 v[48:63], v[132:135], v[136:139], v[48:63]
	v_mfma_f32_32x32x16_bf16 v[96:111], v[128:131], v[140:143], v[96:111]
	v_mfma_f32_32x32x16_bf16 v[32:47], v[132:135], v[140:143], v[32:47]
	v_mfma_f32_32x32x16_bf16 v[80:95], v[128:131], v[144:147], v[80:95]
	v_mfma_f32_32x32x16_bf16 v[16:31], v[132:135], v[144:147], v[16:31]
	v_mfma_f32_32x32x16_bf16 v[64:79], v[128:131], v[148:151], v[64:79]
	v_mfma_f32_32x32x16_bf16 v[0:15], v[132:135], v[148:151], v[0:15]
	ds_read_b128 v[128:131], v231
	ds_read_b128 v[136:139], v235
	ds_read_b128 v[132:135], v231 offset:4096
	ds_read_b128 v[140:143], v235 offset:4096
	ds_read_b128 v[144:147], v235 offset:8192
	ds_read_b128 v[148:151], v235 offset:12288
	s_waitcnt lgkmcnt(6)
	v_mfma_f32_32x32x16_bf16 v[112:127], v[202:205], v[212:215], v[112:127]
	v_mfma_f32_32x32x16_bf16 v[48:63], v[206:209], v[212:215], v[48:63]
	v_mfma_f32_32x32x16_bf16 v[96:111], v[202:205], v[216:219], v[96:111]
	v_mfma_f32_32x32x16_bf16 v[32:47], v[206:209], v[216:219], v[32:47]
	v_mfma_f32_32x32x16_bf16 v[80:95], v[202:205], v[220:223], v[80:95]
	v_mfma_f32_32x32x16_bf16 v[16:31], v[206:209], v[220:223], v[16:31]
	v_mfma_f32_32x32x16_bf16 v[64:79], v[202:205], v[224:227], v[64:79]
	v_mfma_f32_32x32x16_bf16 v[0:15], v[206:209], v[224:227], v[0:15]
	s_waitcnt vmcnt(0) lgkmcnt(0)
	s_barrier
	v_xor_b32_e32 v228, 0x10000, v228
	v_xor_b32_e32 v232, 0x10000, v232
	v_mfma_f32_32x32x16_bf16 v[112:127], v[128:131], v[136:139], v[112:127]
	v_xor_b32_e32 v229, 0x10000, v229
	v_xor_b32_e32 v233, 0x10000, v233
	v_mfma_f32_32x32x16_bf16 v[48:63], v[132:135], v[136:139], v[48:63]
	v_xor_b32_e32 v230, 0x10000, v230
	v_xor_b32_e32 v234, 0x10000, v234
	v_mfma_f32_32x32x16_bf16 v[96:111], v[128:131], v[140:143], v[96:111]
	v_xor_b32_e32 v231, 0x10000, v231
	v_xor_b32_e32 v235, 0x10000, v235
	v_mfma_f32_32x32x16_bf16 v[32:47], v[132:135], v[140:143], v[32:47]
	v_mfma_f32_32x32x16_bf16 v[80:95], v[128:131], v[144:147], v[80:95]
	v_mfma_f32_32x32x16_bf16 v[16:31], v[132:135], v[144:147], v[16:31]
	v_mfma_f32_32x32x16_bf16 v[64:79], v[128:131], v[148:151], v[64:79]
	v_mfma_f32_32x32x16_bf16 v[0:15], v[132:135], v[148:151], v[0:15]
	v_mbcnt_hi_u32_b32 v226, -1, v210
	v_and_b32_e32 v227, 31, v226
	v_lshrrev_b32_e32 v228, 5, v226
	v_lshlrev_b32_e32 v220, 3, v227
	v_lshlrev_b32_e32 v223, 2, v228
	s_lshr_b32 s90, s70, 6
	s_mul_i32 s91, s90, 0x1200
	s_add_u32 s91, s91, 0x12000
	v_mul_u32_u24_e32 v229, 0x240, v228
	v_lshl_add_u32 v229, v227, 1, v229
	v_add_u32_e32 v221, s91, v229
	v_lshrrev_b32_e32 v224, 3, v226
	v_and_b32_e32 v230, 7, v226
	v_lshlrev_b32_e32 v225, 4, v230
	v_mul_u32_u24_e32 v229, 0x90, v224
	v_add3_u32 v222, v229, v225, s91
	s_mul_i32 s92, s5, 15
	s_sub_u32 s93, s4, s92
	s_lshl_b32 s93, s93, 8
	s_lshl_b32 s92, s5, 8
	s_lshr_b32 s94, s90, 1
	s_lshl_b32 s94, s94, 6
	s_add_u32 s92, s92, s94
	s_and_b32 s94, s90, 1
	s_lshl_b32 s94, s94, 7
	s_add_u32 s93, s93, s94
	s_load_dwordx2 s[98:99], s[0:1], 0x148
.Lep4_00:
	s_add_u32 s94, s92, 0
	s_add_u32 s95, s93, 0
	s_lshr_b32 s90, s95, 6
	s_cmp_lt_u32 s90, 16
	s_cbranch_scc1 .Lep4_00_t0
	s_cmp_lt_u32 s90, 20
	s_cbranch_scc1 .Lep4_00_t16
	s_cmp_lt_u32 s90, 24
	s_cbranch_scc1 .Lep4_00_t20
	s_cmp_lt_u32 s90, 28
	s_cbranch_scc1 .Lep4_00_t24
	s_cmp_lt_u32 s90, 32
	s_cbranch_scc1 .Lep4_00_t28
	s_cmp_lt_u32 s90, 36
	s_cbranch_scc1 .Lep4_00_t32
	s_cmp_lt_u32 s90, 40
	s_cbranch_scc1 .Lep4_00_t36
	s_cmp_lt_u32 s90, 56
	s_cbranch_scc1 .Lep4_00_t40
	s_cmp_lt_u32 s90, 57
	s_cbranch_scc1 .Lep4_00_t56
	s_branch .Lep4_00_end

.Lep4_00_t16:
	s_load_dwordx2 s[96:97], s[0:1], 0x1a8
	s_mov_b32 s89, 512
	s_sub_u32 s91, s95, 1024
	s_lshl_b32 s91, s91, 1
	s_branch .Lep4_00_mP
.Lep4_00_t20:
	s_load_dwordx2 s[96:97], s[0:1], 0x1b0
	s_mov_b32 s89, 512
	s_sub_u32 s91, s95, 1280
	s_lshl_b32 s91, s91, 1
	s_branch .Lep4_00_mP
.Lep4_00_t24:
	s_load_dwordx2 s[96:97], s[0:1], 0x1b8
	s_mov_b32 s89, 512
	s_sub_u32 s91, s95, 1536
	s_lshl_b32 s91, s91, 1
	s_mov_b32 s88, 1.0
	s_branch .Lep4_00_mR
.Lep4_00_t28:
	s_load_dwordx2 s[96:97], s[0:1], 0x1c0
	s_mov_b32 s89, 512
	s_sub_u32 s91, s95, 1792
	s_lshl_b32 s91, s91, 1
	s_branch .Lep4_00_mP
.Lep4_00_t32:
	s_load_dwordx2 s[96:97], s[0:1], 0x1c8
	s_mov_b32 s89, 512
	s_sub_u32 s91, s95, 2048
	s_lshl_b32 s91, s91, 1
	s_mov_b32 s88, 1.0
	s_branch .Lep4_00_mR
.Lep4_00_t36:
	s_load_dwordx2 s[96:97], s[0:1], 0x1d0
	s_mov_b32 s89, 512
	s_sub_u32 s91, s95, 2304
	s_lshl_b32 s91, s91, 1
	s_branch .Lep4_00_mP
.Lep4_00_t40:
	s_load_dwordx2 s[96:97], s[0:1], 0x160
	s_mov_b32 s89, 2048
	s_sub_u32 s91, s95, 2560
	s_lshl_b32 s91, s91, 1
	s_branch .Lep4_00_mS
.Lep4_00_t56:
	s_load_dwordx2 s[96:97], s[0:1], 0x1d8
	s_mov_b32 s89, 96
	s_sub_u32 s91, s95, 3584
	s_lshl_b32 s91, s91, 1
	s_branch .Lep4_00_mG
.Lep4_00_mG:
	v_mul_f32_e32 v226, 0xbfb8aa3b, v112
	v_mul_f32_e32 v227, 0xbfb8aa3b, v96
	v_exp_f32_e32 v226, v226
	v_exp_f32_e32 v227, v227
	v_add_f32_e32 v226, 1.0, v226
	v_add_f32_e32 v227, 1.0, v227
	v_rcp_f32_e32 v226, v226
	v_rcp_f32_e32 v227, v227
	s_nop 0
	v_cvt_pk_bf16_f32 v226, v226, v227
	ds_write_b16 v221, v226
	ds_write_b16_d16_hi v221, v226 offset:64
	v_mul_f32_e32 v228, 0xbfb8aa3b, v113
	v_mul_f32_e32 v229, 0xbfb8aa3b, v97
	v_exp_f32_e32 v228, v228
	v_exp_f32_e32 v229, v229
	v_add_f32_e32 v228, 1.0, v228
	v_add_f32_e32 v229, 1.0, v229
	v_rcp_f32_e32 v228, v228
	v_rcp_f32_e32 v229, v229
	s_nop 0
	v_cvt_pk_bf16_f32 v228, v228, v229
	ds_write_b16 v221, v228 offset:144
	ds_write_b16_d16_hi v221, v228 offset:208
	v_mul_f32_e32 v226, 0xbfb8aa3b, v114
	v_mul_f32_e32 v227, 0xbfb8aa3b, v98
	v_exp_f32_e32 v226, v226
	v_exp_f32_e32 v227, v227
	v_add_f32_e32 v226, 1.0, v226
	v_add_f32_e32 v227, 1.0, v227
	v_rcp_f32_e32 v226, v226
	v_rcp_f32_e32 v227, v227
	s_nop 0
	v_cvt_pk_bf16_f32 v226, v226, v227
	ds_write_b16 v221, v226 offset:288
	ds_write_b16_d16_hi v221, v226 offset:352
	v_mul_f32_e32 v228, 0xbfb8aa3b, v115
	v_mul_f32_e32 v229, 0xbfb8aa3b, v99
	v_exp_f32_e32 v228, v228
	v_exp_f32_e32 v229, v229
	v_add_f32_e32 v228, 1.0, v228
	v_add_f32_e32 v229, 1.0, v229
	v_rcp_f32_e32 v228, v228
	v_rcp_f32_e32 v229, v229
	s_nop 0
	v_cvt_pk_bf16_f32 v228, v228, v229
	ds_write_b16 v221, v228 offset:432
	ds_write_b16_d16_hi v221, v228 offset:496
	v_mul_f32_e32 v226, 0xbfb8aa3b, v116
	v_mul_f32_e32 v227, 0xbfb8aa3b, v100
	v_exp_f32_e32 v226, v226
	v_exp_f32_e32 v227, v227
	v_add_f32_e32 v226, 1.0, v226
	v_add_f32_e32 v227, 1.0, v227
	v_rcp_f32_e32 v226, v226
	v_rcp_f32_e32 v227, v227
	s_nop 0
	v_cvt_pk_bf16_f32 v226, v226, v227
	ds_write_b16 v221, v226 offset:1152
	ds_write_b16_d16_hi v221, v226 offset:1216
	v_mul_f32_e32 v228, 0xbfb8aa3b, v117
	v_mul_f32_e32 v229, 0xbfb8aa3b, v101
	v_exp_f32_e32 v228, v228
	v_exp_f32_e32 v229, v229
	v_add_f32_e32 v228, 1.0, v228
	v_add_f32_e32 v229, 1.0, v229
	v_rcp_f32_e32 v228, v228
	v_rcp_f32_e32 v229, v229
	s_nop 0
	v_cvt_pk_bf16_f32 v228, v228, v229
	ds_write_b16 v221, v228 offset:1296
	ds_write_b16_d16_hi v221, v228 offset:1360
	v_mul_f32_e32 v226, 0xbfb8aa3b, v118
	v_mul_f32_e32 v227, 0xbfb8aa3b, v102
	v_exp_f32_e32 v226, v226
	v_exp_f32_e32 v227, v227
	v_add_f32_e32 v226, 1.0, v226
	v_add_f32_e32 v227, 1.0, v227
	v_rcp_f32_e32 v226, v226
	v_rcp_f32_e32 v227, v227
	s_nop 0
	v_cvt_pk_bf16_f32 v226, v226, v227
	ds_write_b16 v221, v226 offset:1440
	ds_write_b16_d16_hi v221, v226 offset:1504
	v_mul_f32_e32 v228, 0xbfb8aa3b, v119
	v_mul_f32_e32 v229, 0xbfb8aa3b, v103
	v_exp_f32_e32 v228, v228
	v_exp_f32_e32 v229, v229
	v_add_f32_e32 v228, 1.0, v228
	v_add_f32_e32 v229, 1.0, v229
	v_rcp_f32_e32 v228, v228
	v_rcp_f32_e32 v229, v229
	s_nop 0
	v_cvt_pk_bf16_f32 v228, v228, v229
	ds_write_b16 v221, v228 offset:1584
	ds_write_b16_d16_hi v221, v228 offset:1648
	v_mul_f32_e32 v226, 0xbfb8aa3b, v120
	v_mul_f32_e32 v227, 0xbfb8aa3b, v104
	v_exp_f32_e32 v226, v226
	v_exp_f32_e32 v227, v227
	v_add_f32_e32 v226, 1.0, v226
	v_add_f32_e32 v227, 1.0, v227
	v_rcp_f32_e32 v226, v226
	v_rcp_f32_e32 v227, v227
	s_nop 0
	v_cvt_pk_bf16_f32 v226, v226, v227
	ds_write_b16 v221, v226 offset:2304
	ds_write_b16_d16_hi v221, v226 offset:2368
	v_mul_f32_e32 v228, 0xbfb8aa3b, v121
	v_mul_f32_e32 v229, 0xbfb8aa3b, v105
	v_exp_f32_e32 v228, v228
	v_exp_f32_e32 v229, v229
	v_add_f32_e32 v228, 1.0, v228
	v_add_f32_e32 v229, 1.0, v229
	v_rcp_f32_e32 v228, v228
	v_rcp_f32_e32 v229, v229
	s_nop 0
	v_cvt_pk_bf16_f32 v228, v228, v229
	ds_write_b16 v221, v228 offset:2448
	ds_write_b16_d16_hi v221, v228 offset:2512
	v_mul_f32_e32 v226, 0xbfb8aa3b, v122
	v_mul_f32_e32 v227, 0xbfb8aa3b, v106
	v_exp_f32_e32 v226, v226
	v_exp_f32_e32 v227, v227
	v_add_f32_e32 v226, 1.0, v226
	v_add_f32_e32 v227, 1.0, v227
	v_rcp_f32_e32 v226, v226
	v_rcp_f32_e32 v227, v227
	s_nop 0
	v_cvt_pk_bf16_f32 v226, v226, v227
	ds_write_b16 v221, v226 offset:2592
	ds_write_b16_d16_hi v221, v226 offset:2656
	v_mul_f32_e32 v228, 0xbfb8aa3b, v123
	v_mul_f32_e32 v229, 0xbfb8aa3b, v107
	v_exp_f32_e32 v228, v228
	v_exp_f32_e32 v229, v229
	v_add_f32_e32 v228, 1.0, v228
	v_add_f32_e32 v229, 1.0, v229
	v_rcp_f32_e32 v228, v228
	v_rcp_f32_e32 v229, v229
	s_nop 0
	v_cvt_pk_bf16_f32 v228, v228, v229
	ds_write_b16 v221, v228 offset:2736
	ds_write_b16_d16_hi v221, v228 offset:2800
	v_mul_f32_e32 v226, 0xbfb8aa3b, v124
	v_mul_f32_e32 v227, 0xbfb8aa3b, v108
	v_exp_f32_e32 v226, v226
	v_exp_f32_e32 v227, v227
	v_add_f32_e32 v226, 1.0, v226
	v_add_f32_e32 v227, 1.0, v227
	v_rcp_f32_e32 v226, v226
	v_rcp_f32_e32 v227, v227
	s_nop 0
	v_cvt_pk_bf16_f32 v226, v226, v227
	ds_write_b16 v221, v226 offset:3456
	ds_write_b16_d16_hi v221, v226 offset:3520
	v_mul_f32_e32 v228, 0xbfb8aa3b, v125
	v_mul_f32_e32 v229, 0xbfb8aa3b, v109
	v_exp_f32_e32 v228, v228
	v_exp_f32_e32 v229, v229
	v_add_f32_e32 v228, 1.0, v228
	v_add_f32_e32 v229, 1.0, v229
	v_rcp_f32_e32 v228, v228
	v_rcp_f32_e32 v229, v229
	s_nop 0
	v_cvt_pk_bf16_f32 v228, v228, v229
	ds_write_b16 v221, v228 offset:3600
	ds_write_b16_d16_hi v221, v228 offset:3664
	v_mul_f32_e32 v226, 0xbfb8aa3b, v126
	v_mul_f32_e32 v227, 0xbfb8aa3b, v110
	v_exp_f32_e32 v226, v226
	v_exp_f32_e32 v227, v227
	v_add_f32_e32 v226, 1.0, v226
	v_add_f32_e32 v227, 1.0, v227
	v_rcp_f32_e32 v226, v226
	v_rcp_f32_e32 v227, v227
	s_nop 0
	v_cvt_pk_bf16_f32 v226, v226, v227
	ds_write_b16 v221, v226 offset:3744
	ds_write_b16_d16_hi v221, v226 offset:3808
	v_mul_f32_e32 v228, 0xbfb8aa3b, v127
	v_mul_f32_e32 v229, 0xbfb8aa3b, v111
	v_exp_f32_e32 v228, v228
	v_exp_f32_e32 v229, v229
	v_add_f32_e32 v228, 1.0, v228
	v_add_f32_e32 v229, 1.0, v229
	v_rcp_f32_e32 v228, v228
	v_rcp_f32_e32 v229, v229
	s_nop 0
	v_cvt_pk_bf16_f32 v228, v228, v229
	ds_write_b16 v221, v228 offset:3888
	ds_write_b16_d16_hi v221, v228 offset:3952
	s_branch .Lep4_00_st
.Lep4_00_mP:
	v_cvt_pk_bf16_f32 v226, v112, v96
	ds_write_b16 v221, v226
	ds_write_b16_d16_hi v221, v226 offset:64
	v_cvt_pk_bf16_f32 v227, v113, v97
	ds_write_b16 v221, v227 offset:144
	ds_write_b16_d16_hi v221, v227 offset:208
	v_cvt_pk_bf16_f32 v228, v114, v98
	ds_write_b16 v221, v228 offset:288
	ds_write_b16_d16_hi v221, v228 offset:352
	v_cvt_pk_bf16_f32 v229, v115, v99
	ds_write_b16 v221, v229 offset:432
	ds_write_b16_d16_hi v221, v229 offset:496
	v_cvt_pk_bf16_f32 v226, v116, v100
	ds_write_b16 v221, v226 offset:1152
	ds_write_b16_d16_hi v221, v226 offset:1216
	v_cvt_pk_bf16_f32 v227, v117, v101
	ds_write_b16 v221, v227 offset:1296
	ds_write_b16_d16_hi v221, v227 offset:1360
	v_cvt_pk_bf16_f32 v228, v118, v102
	ds_write_b16 v221, v228 offset:1440
	ds_write_b16_d16_hi v221, v228 offset:1504
	v_cvt_pk_bf16_f32 v229, v119, v103
	ds_write_b16 v221, v229 offset:1584
	ds_write_b16_d16_hi v221, v229 offset:1648
	v_cvt_pk_bf16_f32 v226, v120, v104
	ds_write_b16 v221, v226 offset:2304
	ds_write_b16_d16_hi v221, v226 offset:2368
	v_cvt_pk_bf16_f32 v227, v121, v105
	ds_write_b16 v221, v227 offset:2448
	ds_write_b16_d16_hi v221, v227 offset:2512
	v_cvt_pk_bf16_f32 v228, v122, v106
	ds_write_b16 v221, v228 offset:2592
	ds_write_b16_d16_hi v221, v228 offset:2656
	v_cvt_pk_bf16_f32 v229, v123, v107
	ds_write_b16 v221, v229 offset:2736
	ds_write_b16_d16_hi v221, v229 offset:2800
	v_cvt_pk_bf16_f32 v226, v124, v108
	ds_write_b16 v221, v226 offset:3456
	ds_write_b16_d16_hi v221, v226 offset:3520
	v_cvt_pk_bf16_f32 v227, v125, v109
	ds_write_b16 v221, v227 offset:3600
	ds_write_b16_d16_hi v221, v227 offset:3664
	v_cvt_pk_bf16_f32 v228, v126, v110
	ds_write_b16 v221, v228 offset:3744
	ds_write_b16_d16_hi v221, v228 offset:3808
	v_cvt_pk_bf16_f32 v229, v127, v111
	ds_write_b16 v221, v229 offset:3888
	ds_write_b16_d16_hi v221, v229 offset:3952
	s_branch .Lep4_00_st
.Lep4_00_mR:
	v_add_u32_e32 v226, s94, v223
	v_lshlrev_b32_e32 v226, 8, v226
	v_add_u32_e32 v232, v226, v220
	v_mov_b32_e32 v233, 0
	s_waitcnt lgkmcnt(0)
	v_lshl_add_u64 v[232:233], s[98:99], 0, v[232:233]
	global_load_dwordx2 v[128:129], v[232:233], off
	global_load_dwordx2 v[130:131], v[232:233], off offset:256
	global_load_dwordx2 v[132:133], v[232:233], off offset:512
	global_load_dwordx2 v[134:135], v[232:233], off offset:768
	global_load_dwordx2 v[136:137], v[232:233], off offset:2048
	global_load_dwordx2 v[138:139], v[232:233], off offset:2304
	global_load_dwordx2 v[140:141], v[232:233], off offset:2560
	global_load_dwordx2 v[142:143], v[232:233], off offset:2816
	v_add_co_u32_e32 v234, vcc, 0x1000, v232
	s_nop 1
	v_addc_co_u32_e32 v235, vcc, 0, v233, vcc
	global_load_dwordx2 v[144:145], v[234:235], off
	global_load_dwordx2 v[146:147], v[234:235], off offset:256
	global_load_dwordx2 v[148:149], v[234:235], off offset:512
	global_load_dwordx2 v[150:151], v[234:235], off offset:768
	global_load_dwordx2 v[152:153], v[234:235], off offset:2048
	global_load_dwordx2 v[154:155], v[234:235], off offset:2304
	global_load_dwordx2 v[156:157], v[234:235], off offset:2560
	global_load_dwordx2 v[158:159], v[234:235], off offset:2816
	s_waitcnt vmcnt(15)
	v_mul_f32_e32 v226, v96, v129
	v_mul_f32_e32 v227, v112, v129
	v_fma_f32 v226, v112, v128, -v226
	v_fma_f32 v227, v96, v128, v227
	v_mul_f32_e32 v226, s88, v226
	v_mul_f32_e32 v227, s88, v227
	v_cvt_pk_bf16_f32 v226, v226, v227
	ds_write_b16 v221, v226
	ds_write_b16_d16_hi v221, v226 offset:64
	s_waitcnt vmcnt(14)
	v_mul_f32_e32 v226, v97, v131
	v_mul_f32_e32 v227, v113, v131
	v_fma_f32 v226, v113, v130, -v226
	v_fma_f32 v227, v97, v130, v227
	v_mul_f32_e32 v226, s88, v226
	v_mul_f32_e32 v227, s88, v227
	v_cvt_pk_bf16_f32 v226, v226, v227
	ds_write_b16 v221, v226 offset:144
	ds_write_b16_d16_hi v221, v226 offset:208
	s_waitcnt vmcnt(13)
	v_mul_f32_e32 v226, v98, v133
	v_mul_f32_e32 v227, v114, v133
	v_fma_f32 v226, v114, v132, -v226
	v_fma_f32 v227, v98, v132, v227
	v_mul_f32_e32 v226, s88, v226
	v_mul_f32_e32 v227, s88, v227
	v_cvt_pk_bf16_f32 v226, v226, v227
	ds_write_b16 v221, v226 offset:288
	ds_write_b16_d16_hi v221, v226 offset:352
	s_waitcnt vmcnt(12)
	v_mul_f32_e32 v226, v99, v135
	v_mul_f32_e32 v227, v115, v135
	v_fma_f32 v226, v115, v134, -v226
	v_fma_f32 v227, v99, v134, v227
	v_mul_f32_e32 v226, s88, v226
	v_mul_f32_e32 v227, s88, v227
	v_cvt_pk_bf16_f32 v226, v226, v227
	ds_write_b16 v221, v226 offset:432
	ds_write_b16_d16_hi v221, v226 offset:496
	s_waitcnt vmcnt(11)
	v_mul_f32_e32 v226, v100, v137
	v_mul_f32_e32 v227, v116, v137
	v_fma_f32 v226, v116, v136, -v226
	v_fma_f32 v227, v100, v136, v227
	v_mul_f32_e32 v226, s88, v226
	v_mul_f32_e32 v227, s88, v227
	v_cvt_pk_bf16_f32 v226, v226, v227
	ds_write_b16 v221, v226 offset:1152
	ds_write_b16_d16_hi v221, v226 offset:1216
	s_waitcnt vmcnt(10)
	v_mul_f32_e32 v226, v101, v139
	v_mul_f32_e32 v227, v117, v139
	v_fma_f32 v226, v117, v138, -v226
	v_fma_f32 v227, v101, v138, v227
	v_mul_f32_e32 v226, s88, v226
	v_mul_f32_e32 v227, s88, v227
	v_cvt_pk_bf16_f32 v226, v226, v227
	ds_write_b16 v221, v226 offset:1296
	ds_write_b16_d16_hi v221, v226 offset:1360
	s_waitcnt vmcnt(9)
	v_mul_f32_e32 v226, v102, v141
	v_mul_f32_e32 v227, v118, v141
	v_fma_f32 v226, v118, v140, -v226
	v_fma_f32 v227, v102, v140, v227
	v_mul_f32_e32 v226, s88, v226
	v_mul_f32_e32 v227, s88, v227
	v_cvt_pk_bf16_f32 v226, v226, v227
	ds_write_b16 v221, v226 offset:1440
	ds_write_b16_d16_hi v221, v226 offset:1504
	s_waitcnt vmcnt(8)
	v_mul_f32_e32 v226, v103, v143
	v_mul_f32_e32 v227, v119, v143
	v_fma_f32 v226, v119, v142, -v226
	v_fma_f32 v227, v103, v142, v227
	v_mul_f32_e32 v226, s88, v226
	v_mul_f32_e32 v227, s88, v227
	v_cvt_pk_bf16_f32 v226, v226, v227
	ds_write_b16 v221, v226 offset:1584
	ds_write_b16_d16_hi v221, v226 offset:1648
	s_waitcnt vmcnt(7)
	v_mul_f32_e32 v226, v104, v145
	v_mul_f32_e32 v227, v120, v145
	v_fma_f32 v226, v120, v144, -v226
	v_fma_f32 v227, v104, v144, v227
	v_mul_f32_e32 v226, s88, v226
	v_mul_f32_e32 v227, s88, v227
	v_cvt_pk_bf16_f32 v226, v226, v227
	ds_write_b16 v221, v226 offset:2304
	ds_write_b16_d16_hi v221, v226 offset:2368
	s_waitcnt vmcnt(6)
	v_mul_f32_e32 v226, v105, v147
	v_mul_f32_e32 v227, v121, v147
	v_fma_f32 v226, v121, v146, -v226
	v_fma_f32 v227, v105, v146, v227
	v_mul_f32_e32 v226, s88, v226
	v_mul_f32_e32 v227, s88, v227
	v_cvt_pk_bf16_f32 v226, v226, v227
	ds_write_b16 v221, v226 offset:2448
	ds_write_b16_d16_hi v221, v226 offset:2512
	s_waitcnt vmcnt(5)
	v_mul_f32_e32 v226, v106, v149
	v_mul_f32_e32 v227, v122, v149
	v_fma_f32 v226, v122, v148, -v226
	v_fma_f32 v227, v106, v148, v227
	v_mul_f32_e32 v226, s88, v226
	v_mul_f32_e32 v227, s88, v227
	v_cvt_pk_bf16_f32 v226, v226, v227
	ds_write_b16 v221, v226 offset:2592
	ds_write_b16_d16_hi v221, v226 offset:2656
	s_waitcnt vmcnt(4)
	v_mul_f32_e32 v226, v107, v151
	v_mul_f32_e32 v227, v123, v151
	v_fma_f32 v226, v123, v150, -v226
	v_fma_f32 v227, v107, v150, v227
	v_mul_f32_e32 v226, s88, v226
	v_mul_f32_e32 v227, s88, v227
	v_cvt_pk_bf16_f32 v226, v226, v227
	ds_write_b16 v221, v226 offset:2736
	ds_write_b16_d16_hi v221, v226 offset:2800
	s_waitcnt vmcnt(3)
	v_mul_f32_e32 v226, v108, v153
	v_mul_f32_e32 v227, v124, v153
	v_fma_f32 v226, v124, v152, -v226
	v_fma_f32 v227, v108, v152, v227
	v_mul_f32_e32 v226, s88, v226
	v_mul_f32_e32 v227, s88, v227
	v_cvt_pk_bf16_f32 v226, v226, v227
	ds_write_b16 v221, v226 offset:3456
	ds_write_b16_d16_hi v221, v226 offset:3520
	s_waitcnt vmcnt(2)
	v_mul_f32_e32 v226, v109, v155
	v_mul_f32_e32 v227, v125, v155
	v_fma_f32 v226, v125, v154, -v226
	v_fma_f32 v227, v109, v154, v227
	v_mul_f32_e32 v226, s88, v226
	v_mul_f32_e32 v227, s88, v227
	v_cvt_pk_bf16_f32 v226, v226, v227
	ds_write_b16 v221, v226 offset:3600
	ds_write_b16_d16_hi v221, v226 offset:3664
	s_waitcnt vmcnt(1)
	v_mul_f32_e32 v226, v110, v157
	v_mul_f32_e32 v227, v126, v157
	v_fma_f32 v226, v126, v156, -v226
	v_fma_f32 v227, v110, v156, v227
	v_mul_f32_e32 v226, s88, v226
	v_mul_f32_e32 v227, s88, v227
	v_cvt_pk_bf16_f32 v226, v226, v227
	ds_write_b16 v221, v226 offset:3744
	ds_write_b16_d16_hi v221, v226 offset:3808
	s_waitcnt vmcnt(0)
	v_mul_f32_e32 v226, v111, v159
	v_mul_f32_e32 v227, v127, v159
	v_fma_f32 v226, v127, v158, -v226
	v_fma_f32 v227, v111, v158, v227
	v_mul_f32_e32 v226, s88, v226
	v_mul_f32_e32 v227, s88, v227
	v_cvt_pk_bf16_f32 v226, v226, v227
	ds_write_b16 v221, v226 offset:3888
	ds_write_b16_d16_hi v221, v226 offset:3952
	s_branch .Lep4_00_st
.Lep4_00_mS:
	v_mul_f32_e32 v226, 0xbfb8aa3b, v112
	v_mul_f32_e32 v227, 0xbfb8aa3b, v96
	v_exp_f32_e32 v226, v226
	v_exp_f32_e32 v227, v227
	v_add_f32_e32 v226, 1.0, v226
	v_add_f32_e32 v227, 1.0, v227
	v_rcp_f32_e32 v226, v226
	v_rcp_f32_e32 v227, v227
	v_mul_f32_e32 v226, v112, v226
	v_mul_f32_e32 v227, v96, v227
	v_cvt_pk_bf16_f32 v226, v226, v227
	ds_write_b16 v221, v226
	ds_write_b16_d16_hi v221, v226 offset:64
	v_mul_f32_e32 v228, 0xbfb8aa3b, v113
	v_mul_f32_e32 v229, 0xbfb8aa3b, v97
	v_exp_f32_e32 v228, v228
	v_exp_f32_e32 v229, v229
	v_add_f32_e32 v228, 1.0, v228
	v_add_f32_e32 v229, 1.0, v229
	v_rcp_f32_e32 v228, v228
	v_rcp_f32_e32 v229, v229
	v_mul_f32_e32 v228, v113, v228
	v_mul_f32_e32 v229, v97, v229
	v_cvt_pk_bf16_f32 v228, v228, v229
	ds_write_b16 v221, v228 offset:144
	ds_write_b16_d16_hi v221, v228 offset:208
	v_mul_f32_e32 v226, 0xbfb8aa3b, v114
	v_mul_f32_e32 v227, 0xbfb8aa3b, v98
	v_exp_f32_e32 v226, v226
	v_exp_f32_e32 v227, v227
	v_add_f32_e32 v226, 1.0, v226
	v_add_f32_e32 v227, 1.0, v227
	v_rcp_f32_e32 v226, v226
	v_rcp_f32_e32 v227, v227
	v_mul_f32_e32 v226, v114, v226
	v_mul_f32_e32 v227, v98, v227
	v_cvt_pk_bf16_f32 v226, v226, v227
	ds_write_b16 v221, v226 offset:288
	ds_write_b16_d16_hi v221, v226 offset:352
	v_mul_f32_e32 v228, 0xbfb8aa3b, v115
	v_mul_f32_e32 v229, 0xbfb8aa3b, v99
	v_exp_f32_e32 v228, v228
	v_exp_f32_e32 v229, v229
	v_add_f32_e32 v228, 1.0, v228
	v_add_f32_e32 v229, 1.0, v229
	v_rcp_f32_e32 v228, v228
	v_rcp_f32_e32 v229, v229
	v_mul_f32_e32 v228, v115, v228
	v_mul_f32_e32 v229, v99, v229
	v_cvt_pk_bf16_f32 v228, v228, v229
	ds_write_b16 v221, v228 offset:432
	ds_write_b16_d16_hi v221, v228 offset:496
	v_mul_f32_e32 v226, 0xbfb8aa3b, v116
	v_mul_f32_e32 v227, 0xbfb8aa3b, v100
	v_exp_f32_e32 v226, v226
	v_exp_f32_e32 v227, v227
	v_add_f32_e32 v226, 1.0, v226
	v_add_f32_e32 v227, 1.0, v227
	v_rcp_f32_e32 v226, v226
	v_rcp_f32_e32 v227, v227
	v_mul_f32_e32 v226, v116, v226
	v_mul_f32_e32 v227, v100, v227
	v_cvt_pk_bf16_f32 v226, v226, v227
	ds_write_b16 v221, v226 offset:1152
	ds_write_b16_d16_hi v221, v226 offset:1216
	v_mul_f32_e32 v228, 0xbfb8aa3b, v117
	v_mul_f32_e32 v229, 0xbfb8aa3b, v101
	v_exp_f32_e32 v228, v228
	v_exp_f32_e32 v229, v229
	v_add_f32_e32 v228, 1.0, v228
	v_add_f32_e32 v229, 1.0, v229
	v_rcp_f32_e32 v228, v228
	v_rcp_f32_e32 v229, v229
	v_mul_f32_e32 v228, v117, v228
	v_mul_f32_e32 v229, v101, v229
	v_cvt_pk_bf16_f32 v228, v228, v229
	ds_write_b16 v221, v228 offset:1296
	ds_write_b16_d16_hi v221, v228 offset:1360
	v_mul_f32_e32 v226, 0xbfb8aa3b, v118
	v_mul_f32_e32 v227, 0xbfb8aa3b, v102
	v_exp_f32_e32 v226, v226
	v_exp_f32_e32 v227, v227
	v_add_f32_e32 v226, 1.0, v226
	v_add_f32_e32 v227, 1.0, v227
	v_rcp_f32_e32 v226, v226
	v_rcp_f32_e32 v227, v227
	v_mul_f32_e32 v226, v118, v226
	v_mul_f32_e32 v227, v102, v227
	v_cvt_pk_bf16_f32 v226, v226, v227
	ds_write_b16 v221, v226 offset:1440
	ds_write_b16_d16_hi v221, v226 offset:1504
	v_mul_f32_e32 v228, 0xbfb8aa3b, v119
	v_mul_f32_e32 v229, 0xbfb8aa3b, v103
	v_exp_f32_e32 v228, v228
	v_exp_f32_e32 v229, v229
	v_add_f32_e32 v228, 1.0, v228
	v_add_f32_e32 v229, 1.0, v229
	v_rcp_f32_e32 v228, v228
	v_rcp_f32_e32 v229, v229
	v_mul_f32_e32 v228, v119, v228
	v_mul_f32_e32 v229, v103, v229
	v_cvt_pk_bf16_f32 v228, v228, v229
	ds_write_b16 v221, v228 offset:1584
	ds_write_b16_d16_hi v221, v228 offset:1648
	v_mul_f32_e32 v226, 0xbfb8aa3b, v120
	v_mul_f32_e32 v227, 0xbfb8aa3b, v104
	v_exp_f32_e32 v226, v226
	v_exp_f32_e32 v227, v227
	v_add_f32_e32 v226, 1.0, v226
	v_add_f32_e32 v227, 1.0, v227
	v_rcp_f32_e32 v226, v226
	v_rcp_f32_e32 v227, v227
	v_mul_f32_e32 v226, v120, v226
	v_mul_f32_e32 v227, v104, v227
	v_cvt_pk_bf16_f32 v226, v226, v227
	ds_write_b16 v221, v226 offset:2304
	ds_write_b16_d16_hi v221, v226 offset:2368
	v_mul_f32_e32 v228, 0xbfb8aa3b, v121
	v_mul_f32_e32 v229, 0xbfb8aa3b, v105
	v_exp_f32_e32 v228, v228
	v_exp_f32_e32 v229, v229
	v_add_f32_e32 v228, 1.0, v228
	v_add_f32_e32 v229, 1.0, v229
	v_rcp_f32_e32 v228, v228
	v_rcp_f32_e32 v229, v229
	v_mul_f32_e32 v228, v121, v228
	v_mul_f32_e32 v229, v105, v229
	v_cvt_pk_bf16_f32 v228, v228, v229
	ds_write_b16 v221, v228 offset:2448
	ds_write_b16_d16_hi v221, v228 offset:2512
	v_mul_f32_e32 v226, 0xbfb8aa3b, v122
	v_mul_f32_e32 v227, 0xbfb8aa3b, v106
	v_exp_f32_e32 v226, v226
	v_exp_f32_e32 v227, v227
	v_add_f32_e32 v226, 1.0, v226
	v_add_f32_e32 v227, 1.0, v227
	v_rcp_f32_e32 v226, v226
	v_rcp_f32_e32 v227, v227
	v_mul_f32_e32 v226, v122, v226
	v_mul_f32_e32 v227, v106, v227
	v_cvt_pk_bf16_f32 v226, v226, v227
	ds_write_b16 v221, v226 offset:2592
	ds_write_b16_d16_hi v221, v226 offset:2656
	v_mul_f32_e32 v228, 0xbfb8aa3b, v123
	v_mul_f32_e32 v229, 0xbfb8aa3b, v107
	v_exp_f32_e32 v228, v228
	v_exp_f32_e32 v229, v229
	v_add_f32_e32 v228, 1.0, v228
	v_add_f32_e32 v229, 1.0, v229
	v_rcp_f32_e32 v228, v228
	v_rcp_f32_e32 v229, v229
	v_mul_f32_e32 v228, v123, v228
	v_mul_f32_e32 v229, v107, v229
	v_cvt_pk_bf16_f32 v228, v228, v229
	ds_write_b16 v221, v228 offset:2736
	ds_write_b16_d16_hi v221, v228 offset:2800
	v_mul_f32_e32 v226, 0xbfb8aa3b, v124
	v_mul_f32_e32 v227, 0xbfb8aa3b, v108
	v_exp_f32_e32 v226, v226
	v_exp_f32_e32 v227, v227
	v_add_f32_e32 v226, 1.0, v226
	v_add_f32_e32 v227, 1.0, v227
	v_rcp_f32_e32 v226, v226
	v_rcp_f32_e32 v227, v227
	v_mul_f32_e32 v226, v124, v226
	v_mul_f32_e32 v227, v108, v227
	v_cvt_pk_bf16_f32 v226, v226, v227
	ds_write_b16 v221, v226 offset:3456
	ds_write_b16_d16_hi v221, v226 offset:3520
	v_mul_f32_e32 v228, 0xbfb8aa3b, v125
	v_mul_f32_e32 v229, 0xbfb8aa3b, v109
	v_exp_f32_e32 v228, v228
	v_exp_f32_e32 v229, v229
	v_add_f32_e32 v228, 1.0, v228
	v_add_f32_e32 v229, 1.0, v229
	v_rcp_f32_e32 v228, v228
	v_rcp_f32_e32 v229, v229
	v_mul_f32_e32 v228, v125, v228
	v_mul_f32_e32 v229, v109, v229
	v_cvt_pk_bf16_f32 v228, v228, v229
	ds_write_b16 v221, v228 offset:3600
	ds_write_b16_d16_hi v221, v228 offset:3664
	v_mul_f32_e32 v226, 0xbfb8aa3b, v126
	v_mul_f32_e32 v227, 0xbfb8aa3b, v110
	v_exp_f32_e32 v226, v226
	v_exp_f32_e32 v227, v227
	v_add_f32_e32 v226, 1.0, v226
	v_add_f32_e32 v227, 1.0, v227
	v_rcp_f32_e32 v226, v226
	v_rcp_f32_e32 v227, v227
	v_mul_f32_e32 v226, v126, v226
	v_mul_f32_e32 v227, v110, v227
	v_cvt_pk_bf16_f32 v226, v226, v227
	ds_write_b16 v221, v226 offset:3744
	ds_write_b16_d16_hi v221, v226 offset:3808
	v_mul_f32_e32 v228, 0xbfb8aa3b, v127
	v_mul_f32_e32 v229, 0xbfb8aa3b, v111
	v_exp_f32_e32 v228, v228
	v_exp_f32_e32 v229, v229
	v_add_f32_e32 v228, 1.0, v228
	v_add_f32_e32 v229, 1.0, v229
	v_rcp_f32_e32 v228, v228
	v_rcp_f32_e32 v229, v229
	v_mul_f32_e32 v228, v127, v228
	v_mul_f32_e32 v229, v111, v229
	v_cvt_pk_bf16_f32 v228, v228, v229
	ds_write_b16 v221, v228 offset:3888
	ds_write_b16_d16_hi v221, v228 offset:3952
	s_branch .Lep4_00_st
.Lep4_00_st:
	v_add_u32_e32 v230, s94, v224
	s_waitcnt lgkmcnt(0)
	ds_read_b128 v[202:205], v222
	ds_read_b128 v[206:209], v222 offset:1152
	ds_read_b128 v[212:215], v222 offset:2304
	ds_read_b128 v[216:219], v222 offset:3456
	s_cmp_eq_u32 s89, 96
	s_cbranch_scc0 .Lep4_00_full
	v_cmp_gt_u32_e32 vcc, 0x60, v225
	s_and_b64 exec, exec, vcc
.Lep4_00_full:
	v_add_u32_e32 v226, 0, v230
	v_mul_lo_u32 v226, v226, s89
	v_add3_u32 v226, v226, v225, s91
	v_add_u32_e32 v227, 8, v230
	v_mul_lo_u32 v227, v227, s89
	v_add3_u32 v227, v227, v225, s91
	v_add_u32_e32 v228, 16, v230
	v_mul_lo_u32 v228, v228, s89
	v_add3_u32 v228, v228, v225, s91
	v_add_u32_e32 v229, 24, v230
	v_mul_lo_u32 v229, v229, s89
	v_add3_u32 v229, v229, v225, s91
	s_waitcnt lgkmcnt(3)
	global_store_dwordx4 v226, v[202:205], s[96:97]
	s_waitcnt lgkmcnt(2)
	global_store_dwordx4 v227, v[206:209], s[96:97]
	s_waitcnt lgkmcnt(1)
	global_store_dwordx4 v228, v[212:215], s[96:97]
	s_waitcnt lgkmcnt(0)
	global_store_dwordx4 v229, v[216:219], s[96:97]
	s_mov_b64 exec, -1
.Lep4_00_end:
.Lep4_01:
	s_add_u32 s94, s92, 0
	s_add_u32 s95, s93, 64
	s_lshr_b32 s90, s95, 6
	s_cmp_lt_u32 s90, 16
	s_cbranch_scc1 .Lep4_01_t0
	s_cmp_lt_u32 s90, 20
	s_cbranch_scc1 .Lep4_01_t16
	s_cmp_lt_u32 s90, 24
	s_cbranch_scc1 .Lep4_01_t20
	s_cmp_lt_u32 s90, 28
	s_cbranch_scc1 .Lep4_01_t24
	s_cmp_lt_u32 s90, 32
	s_cbranch_scc1 .Lep4_01_t28
	s_cmp_lt_u32 s90, 36
	s_cbranch_scc1 .Lep4_01_t32
	s_cmp_lt_u32 s90, 40
	s_cbranch_scc1 .Lep4_01_t36
	s_cmp_lt_u32 s90, 56
	s_cbranch_scc1 .Lep4_01_t40
	s_cmp_lt_u32 s90, 57
	s_cbranch_scc1 .Lep4_01_t56
	s_branch .Lep4_01_end

.Lep4_01_mG:
	v_mul_f32_e32 v226, 0xbfb8aa3b, v80
	v_mul_f32_e32 v227, 0xbfb8aa3b, v64
	v_exp_f32_e32 v226, v226
	v_exp_f32_e32 v227, v227
	v_add_f32_e32 v226, 1.0, v226
	v_add_f32_e32 v227, 1.0, v227
	v_rcp_f32_e32 v226, v226
	v_rcp_f32_e32 v227, v227
	s_nop 0
	v_cvt_pk_bf16_f32 v226, v226, v227
	ds_write_b16 v221, v226
	ds_write_b16_d16_hi v221, v226 offset:64
	v_mul_f32_e32 v228, 0xbfb8aa3b, v81
	v_mul_f32_e32 v229, 0xbfb8aa3b, v65
	v_exp_f32_e32 v228, v228
	v_exp_f32_e32 v229, v229
	v_add_f32_e32 v228, 1.0, v228
	v_add_f32_e32 v229, 1.0, v229
	v_rcp_f32_e32 v228, v228
	v_rcp_f32_e32 v229, v229
	s_nop 0
	v_cvt_pk_bf16_f32 v228, v228, v229
	ds_write_b16 v221, v228 offset:144
	ds_write_b16_d16_hi v221, v228 offset:208
	v_mul_f32_e32 v226, 0xbfb8aa3b, v82
	v_mul_f32_e32 v227, 0xbfb8aa3b, v66
	v_exp_f32_e32 v226, v226
	v_exp_f32_e32 v227, v227
	v_add_f32_e32 v226, 1.0, v226
	v_add_f32_e32 v227, 1.0, v227
	v_rcp_f32_e32 v226, v226
	v_rcp_f32_e32 v227, v227
	s_nop 0
	v_cvt_pk_bf16_f32 v226, v226, v227
	ds_write_b16 v221, v226 offset:288
	ds_write_b16_d16_hi v221, v226 offset:352
	v_mul_f32_e32 v228, 0xbfb8aa3b, v83
	v_mul_f32_e32 v229, 0xbfb8aa3b, v67
	v_exp_f32_e32 v228, v228
	v_exp_f32_e32 v229, v229
	v_add_f32_e32 v228, 1.0, v228
	v_add_f32_e32 v229, 1.0, v229
	v_rcp_f32_e32 v228, v228
	v_rcp_f32_e32 v229, v229
	s_nop 0
	v_cvt_pk_bf16_f32 v228, v228, v229
	ds_write_b16 v221, v228 offset:432
	ds_write_b16_d16_hi v221, v228 offset:496
	v_mul_f32_e32 v226, 0xbfb8aa3b, v84
	v_mul_f32_e32 v227, 0xbfb8aa3b, v68
	v_exp_f32_e32 v226, v226
	v_exp_f32_e32 v227, v227
	v_add_f32_e32 v226, 1.0, v226
	v_add_f32_e32 v227, 1.0, v227
	v_rcp_f32_e32 v226, v226
	v_rcp_f32_e32 v227, v227
	s_nop 0
	v_cvt_pk_bf16_f32 v226, v226, v227
	ds_write_b16 v221, v226 offset:1152
	ds_write_b16_d16_hi v221, v226 offset:1216
	v_mul_f32_e32 v228, 0xbfb8aa3b, v85
	v_mul_f32_e32 v229, 0xbfb8aa3b, v69
	v_exp_f32_e32 v228, v228
	v_exp_f32_e32 v229, v229
	v_add_f32_e32 v228, 1.0, v228
	v_add_f32_e32 v229, 1.0, v229
	v_rcp_f32_e32 v228, v228
	v_rcp_f32_e32 v229, v229
	s_nop 0
	v_cvt_pk_bf16_f32 v228, v228, v229
	ds_write_b16 v221, v228 offset:1296
	ds_write_b16_d16_hi v221, v228 offset:1360
	v_mul_f32_e32 v226, 0xbfb8aa3b, v86
	v_mul_f32_e32 v227, 0xbfb8aa3b, v70
	v_exp_f32_e32 v226, v226
	v_exp_f32_e32 v227, v227
	v_add_f32_e32 v226, 1.0, v226
	v_add_f32_e32 v227, 1.0, v227
	v_rcp_f32_e32 v226, v226
	v_rcp_f32_e32 v227, v227
	s_nop 0
	v_cvt_pk_bf16_f32 v226, v226, v227
	ds_write_b16 v221, v226 offset:1440
	ds_write_b16_d16_hi v221, v226 offset:1504
	v_mul_f32_e32 v228, 0xbfb8aa3b, v87
	v_mul_f32_e32 v229, 0xbfb8aa3b, v71
	v_exp_f32_e32 v228, v228
	v_exp_f32_e32 v229, v229
	v_add_f32_e32 v228, 1.0, v228
	v_add_f32_e32 v229, 1.0, v229
	v_rcp_f32_e32 v228, v228
	v_rcp_f32_e32 v229, v229
	s_nop 0
	v_cvt_pk_bf16_f32 v228, v228, v229
	ds_write_b16 v221, v228 offset:1584
	ds_write_b16_d16_hi v221, v228 offset:1648
	v_mul_f32_e32 v226, 0xbfb8aa3b, v88
	v_mul_f32_e32 v227, 0xbfb8aa3b, v72
	v_exp_f32_e32 v226, v226
	v_exp_f32_e32 v227, v227
	v_add_f32_e32 v226, 1.0, v226
	v_add_f32_e32 v227, 1.0, v227
	v_rcp_f32_e32 v226, v226
	v_rcp_f32_e32 v227, v227
	s_nop 0
	v_cvt_pk_bf16_f32 v226, v226, v227
	ds_write_b16 v221, v226 offset:2304
	ds_write_b16_d16_hi v221, v226 offset:2368
	v_mul_f32_e32 v228, 0xbfb8aa3b, v89
	v_mul_f32_e32 v229, 0xbfb8aa3b, v73
	v_exp_f32_e32 v228, v228
	v_exp_f32_e32 v229, v229
	v_add_f32_e32 v228, 1.0, v228
	v_add_f32_e32 v229, 1.0, v229
	v_rcp_f32_e32 v228, v228
	v_rcp_f32_e32 v229, v229
	s_nop 0
	v_cvt_pk_bf16_f32 v228, v228, v229
	ds_write_b16 v221, v228 offset:2448
	ds_write_b16_d16_hi v221, v228 offset:2512
	v_mul_f32_e32 v226, 0xbfb8aa3b, v90
	v_mul_f32_e32 v227, 0xbfb8aa3b, v74
	v_exp_f32_e32 v226, v226
	v_exp_f32_e32 v227, v227
	v_add_f32_e32 v226, 1.0, v226
	v_add_f32_e32 v227, 1.0, v227
	v_rcp_f32_e32 v226, v226
	v_rcp_f32_e32 v227, v227
	s_nop 0
	v_cvt_pk_bf16_f32 v226, v226, v227
	ds_write_b16 v221, v226 offset:2592
	ds_write_b16_d16_hi v221, v226 offset:2656
	v_mul_f32_e32 v228, 0xbfb8aa3b, v91
	v_mul_f32_e32 v229, 0xbfb8aa3b, v75
	v_exp_f32_e32 v228, v228
	v_exp_f32_e32 v229, v229
	v_add_f32_e32 v228, 1.0, v228
	v_add_f32_e32 v229, 1.0, v229
	v_rcp_f32_e32 v228, v228
	v_rcp_f32_e32 v229, v229
	s_nop 0
	v_cvt_pk_bf16_f32 v228, v228, v229
	ds_write_b16 v221, v228 offset:2736
	ds_write_b16_d16_hi v221, v228 offset:2800
	v_mul_f32_e32 v226, 0xbfb8aa3b, v92
	v_mul_f32_e32 v227, 0xbfb8aa3b, v76
	v_exp_f32_e32 v226, v226
	v_exp_f32_e32 v227, v227
	v_add_f32_e32 v226, 1.0, v226
	v_add_f32_e32 v227, 1.0, v227
	v_rcp_f32_e32 v226, v226
	v_rcp_f32_e32 v227, v227
	s_nop 0
	v_cvt_pk_bf16_f32 v226, v226, v227
	ds_write_b16 v221, v226 offset:3456
	ds_write_b16_d16_hi v221, v226 offset:3520
	v_mul_f32_e32 v228, 0xbfb8aa3b, v93
	v_mul_f32_e32 v229, 0xbfb8aa3b, v77
	v_exp_f32_e32 v228, v228
	v_exp_f32_e32 v229, v229
	v_add_f32_e32 v228, 1.0, v228
	v_add_f32_e32 v229, 1.0, v229
	v_rcp_f32_e32 v228, v228
	v_rcp_f32_e32 v229, v229
	s_nop 0
	v_cvt_pk_bf16_f32 v228, v228, v229
	ds_write_b16 v221, v228 offset:3600
	ds_write_b16_d16_hi v221, v228 offset:3664
	v_mul_f32_e32 v226, 0xbfb8aa3b, v94
	v_mul_f32_e32 v227, 0xbfb8aa3b, v78
	v_exp_f32_e32 v226, v226
	v_exp_f32_e32 v227, v227
	v_add_f32_e32 v226, 1.0, v226
	v_add_f32_e32 v227, 1.0, v227
	v_rcp_f32_e32 v226, v226
	v_rcp_f32_e32 v227, v227
	s_nop 0
	v_cvt_pk_bf16_f32 v226, v226, v227
	ds_write_b16 v221, v226 offset:3744
	ds_write_b16_d16_hi v221, v226 offset:3808
	v_mul_f32_e32 v228, 0xbfb8aa3b, v95
	v_mul_f32_e32 v229, 0xbfb8aa3b, v79
	v_exp_f32_e32 v228, v228
	v_exp_f32_e32 v229, v229
	v_add_f32_e32 v228, 1.0, v228
	v_add_f32_e32 v229, 1.0, v229
	v_rcp_f32_e32 v228, v228
	v_rcp_f32_e32 v229, v229
	s_nop 0
	v_cvt_pk_bf16_f32 v228, v228, v229
	ds_write_b16 v221, v228 offset:3888
	ds_write_b16_d16_hi v221, v228 offset:3952
	s_branch .Lep4_01_st
.Lep4_01_mP:
	v_cvt_pk_bf16_f32 v226, v80, v64
	ds_write_b16 v221, v226
	ds_write_b16_d16_hi v221, v226 offset:64
	v_cvt_pk_bf16_f32 v227, v81, v65
	ds_write_b16 v221, v227 offset:144
	ds_write_b16_d16_hi v221, v227 offset:208
	v_cvt_pk_bf16_f32 v228, v82, v66
	ds_write_b16 v221, v228 offset:288
	ds_write_b16_d16_hi v221, v228 offset:352
	v_cvt_pk_bf16_f32 v229, v83, v67
	ds_write_b16 v221, v229 offset:432
	ds_write_b16_d16_hi v221, v229 offset:496
	v_cvt_pk_bf16_f32 v226, v84, v68
	ds_write_b16 v221, v226 offset:1152
	ds_write_b16_d16_hi v221, v226 offset:1216
	v_cvt_pk_bf16_f32 v227, v85, v69
	ds_write_b16 v221, v227 offset:1296
	ds_write_b16_d16_hi v221, v227 offset:1360
	v_cvt_pk_bf16_f32 v228, v86, v70
	ds_write_b16 v221, v228 offset:1440
	ds_write_b16_d16_hi v221, v228 offset:1504
	v_cvt_pk_bf16_f32 v229, v87, v71
	ds_write_b16 v221, v229 offset:1584
	ds_write_b16_d16_hi v221, v229 offset:1648
	v_cvt_pk_bf16_f32 v226, v88, v72
	ds_write_b16 v221, v226 offset:2304
	ds_write_b16_d16_hi v221, v226 offset:2368
	v_cvt_pk_bf16_f32 v227, v89, v73
	ds_write_b16 v221, v227 offset:2448
	ds_write_b16_d16_hi v221, v227 offset:2512
	v_cvt_pk_bf16_f32 v228, v90, v74
	ds_write_b16 v221, v228 offset:2592
	ds_write_b16_d16_hi v221, v228 offset:2656
	v_cvt_pk_bf16_f32 v229, v91, v75
	ds_write_b16 v221, v229 offset:2736
	ds_write_b16_d16_hi v221, v229 offset:2800
	v_cvt_pk_bf16_f32 v226, v92, v76
	ds_write_b16 v221, v226 offset:3456
	ds_write_b16_d16_hi v221, v226 offset:3520
	v_cvt_pk_bf16_f32 v227, v93, v77
	ds_write_b16 v221, v227 offset:3600
	ds_write_b16_d16_hi v221, v227 offset:3664
	v_cvt_pk_bf16_f32 v228, v94, v78
	ds_write_b16 v221, v228 offset:3744
	ds_write_b16_d16_hi v221, v228 offset:3808
	v_cvt_pk_bf16_f32 v229, v95, v79
	ds_write_b16 v221, v229 offset:3888
	ds_write_b16_d16_hi v221, v229 offset:3952
	s_branch .Lep4_01_st
.Lep4_01_mR:
	v_add_u32_e32 v226, s94, v223
	v_lshlrev_b32_e32 v226, 8, v226
	v_add_u32_e32 v232, v226, v220
	v_mov_b32_e32 v233, 0
	s_waitcnt lgkmcnt(0)
	v_lshl_add_u64 v[232:233], s[98:99], 0, v[232:233]
	global_load_dwordx2 v[128:129], v[232:233], off
	global_load_dwordx2 v[130:131], v[232:233], off offset:256
	global_load_dwordx2 v[132:133], v[232:233], off offset:512
	global_load_dwordx2 v[134:135], v[232:233], off offset:768
	global_load_dwordx2 v[136:137], v[232:233], off offset:2048
	global_load_dwordx2 v[138:139], v[232:233], off offset:2304
	global_load_dwordx2 v[140:141], v[232:233], off offset:2560
	global_load_dwordx2 v[142:143], v[232:233], off offset:2816
	v_add_co_u32_e32 v234, vcc, 0x1000, v232
	s_nop 1
	v_addc_co_u32_e32 v235, vcc, 0, v233, vcc
	global_load_dwordx2 v[144:145], v[234:235], off
	global_load_dwordx2 v[146:147], v[234:235], off offset:256
	global_load_dwordx2 v[148:149], v[234:235], off offset:512
	global_load_dwordx2 v[150:151], v[234:235], off offset:768
	global_load_dwordx2 v[152:153], v[234:235], off offset:2048
	global_load_dwordx2 v[154:155], v[234:235], off offset:2304
	global_load_dwordx2 v[156:157], v[234:235], off offset:2560
	global_load_dwordx2 v[158:159], v[234:235], off offset:2816
	s_waitcnt vmcnt(15)
	v_mul_f32_e32 v226, v64, v129
	v_mul_f32_e32 v227, v80, v129
	v_fma_f32 v226, v80, v128, -v226
	v_fma_f32 v227, v64, v128, v227
	v_mul_f32_e32 v226, s88, v226
	v_mul_f32_e32 v227, s88, v227
	v_cvt_pk_bf16_f32 v226, v226, v227
	ds_write_b16 v221, v226
	ds_write_b16_d16_hi v221, v226 offset:64
	s_waitcnt vmcnt(14)
	v_mul_f32_e32 v226, v65, v131
	v_mul_f32_e32 v227, v81, v131
	v_fma_f32 v226, v81, v130, -v226
	v_fma_f32 v227, v65, v130, v227
	v_mul_f32_e32 v226, s88, v226
	v_mul_f32_e32 v227, s88, v227
	v_cvt_pk_bf16_f32 v226, v226, v227
	ds_write_b16 v221, v226 offset:144
	ds_write_b16_d16_hi v221, v226 offset:208
	s_waitcnt vmcnt(13)
	v_mul_f32_e32 v226, v66, v133
	v_mul_f32_e32 v227, v82, v133
	v_fma_f32 v226, v82, v132, -v226
	v_fma_f32 v227, v66, v132, v227
	v_mul_f32_e32 v226, s88, v226
	v_mul_f32_e32 v227, s88, v227
	v_cvt_pk_bf16_f32 v226, v226, v227
	ds_write_b16 v221, v226 offset:288
	ds_write_b16_d16_hi v221, v226 offset:352
	s_waitcnt vmcnt(12)
	v_mul_f32_e32 v226, v67, v135
	v_mul_f32_e32 v227, v83, v135
	v_fma_f32 v226, v83, v134, -v226
	v_fma_f32 v227, v67, v134, v227
	v_mul_f32_e32 v226, s88, v226
	v_mul_f32_e32 v227, s88, v227
	v_cvt_pk_bf16_f32 v226, v226, v227
	ds_write_b16 v221, v226 offset:432
	ds_write_b16_d16_hi v221, v226 offset:496
	s_waitcnt vmcnt(11)
	v_mul_f32_e32 v226, v68, v137
	v_mul_f32_e32 v227, v84, v137
	v_fma_f32 v226, v84, v136, -v226
	v_fma_f32 v227, v68, v136, v227
	v_mul_f32_e32 v226, s88, v226
	v_mul_f32_e32 v227, s88, v227
	v_cvt_pk_bf16_f32 v226, v226, v227
	ds_write_b16 v221, v226 offset:1152
	ds_write_b16_d16_hi v221, v226 offset:1216
	s_waitcnt vmcnt(10)
	v_mul_f32_e32 v226, v69, v139
	v_mul_f32_e32 v227, v85, v139
	v_fma_f32 v226, v85, v138, -v226
	v_fma_f32 v227, v69, v138, v227
	v_mul_f32_e32 v226, s88, v226
	v_mul_f32_e32 v227, s88, v227
	v_cvt_pk_bf16_f32 v226, v226, v227
	ds_write_b16 v221, v226 offset:1296
	ds_write_b16_d16_hi v221, v226 offset:1360
	s_waitcnt vmcnt(9)
	v_mul_f32_e32 v226, v70, v141
	v_mul_f32_e32 v227, v86, v141
	v_fma_f32 v226, v86, v140, -v226
	v_fma_f32 v227, v70, v140, v227
	v_mul_f32_e32 v226, s88, v226
	v_mul_f32_e32 v227, s88, v227
	v_cvt_pk_bf16_f32 v226, v226, v227
	ds_write_b16 v221, v226 offset:1440
	ds_write_b16_d16_hi v221, v226 offset:1504
	s_waitcnt vmcnt(8)
	v_mul_f32_e32 v226, v71, v143
	v_mul_f32_e32 v227, v87, v143
	v_fma_f32 v226, v87, v142, -v226
	v_fma_f32 v227, v71, v142, v227
	v_mul_f32_e32 v226, s88, v226
	v_mul_f32_e32 v227, s88, v227
	v_cvt_pk_bf16_f32 v226, v226, v227
	ds_write_b16 v221, v226 offset:1584
	ds_write_b16_d16_hi v221, v226 offset:1648
	s_waitcnt vmcnt(7)
	v_mul_f32_e32 v226, v72, v145
	v_mul_f32_e32 v227, v88, v145
	v_fma_f32 v226, v88, v144, -v226
	v_fma_f32 v227, v72, v144, v227
	v_mul_f32_e32 v226, s88, v226
	v_mul_f32_e32 v227, s88, v227
	v_cvt_pk_bf16_f32 v226, v226, v227
	ds_write_b16 v221, v226 offset:2304
	ds_write_b16_d16_hi v221, v226 offset:2368
	s_waitcnt vmcnt(6)
	v_mul_f32_e32 v226, v73, v147
	v_mul_f32_e32 v227, v89, v147
	v_fma_f32 v226, v89, v146, -v226
	v_fma_f32 v227, v73, v146, v227
	v_mul_f32_e32 v226, s88, v226
	v_mul_f32_e32 v227, s88, v227
	v_cvt_pk_bf16_f32 v226, v226, v227
	ds_write_b16 v221, v226 offset:2448
	ds_write_b16_d16_hi v221, v226 offset:2512
	s_waitcnt vmcnt(5)
	v_mul_f32_e32 v226, v74, v149
	v_mul_f32_e32 v227, v90, v149
	v_fma_f32 v226, v90, v148, -v226
	v_fma_f32 v227, v74, v148, v227
	v_mul_f32_e32 v226, s88, v226
	v_mul_f32_e32 v227, s88, v227
	v_cvt_pk_bf16_f32 v226, v226, v227
	ds_write_b16 v221, v226 offset:2592
	ds_write_b16_d16_hi v221, v226 offset:2656
	s_waitcnt vmcnt(4)
	v_mul_f32_e32 v226, v75, v151
	v_mul_f32_e32 v227, v91, v151
	v_fma_f32 v226, v91, v150, -v226
	v_fma_f32 v227, v75, v150, v227
	v_mul_f32_e32 v226, s88, v226
	v_mul_f32_e32 v227, s88, v227
	v_cvt_pk_bf16_f32 v226, v226, v227
	ds_write_b16 v221, v226 offset:2736
	ds_write_b16_d16_hi v221, v226 offset:2800
	s_waitcnt vmcnt(3)
	v_mul_f32_e32 v226, v76, v153
	v_mul_f32_e32 v227, v92, v153
	v_fma_f32 v226, v92, v152, -v226
	v_fma_f32 v227, v76, v152, v227
	v_mul_f32_e32 v226, s88, v226
	v_mul_f32_e32 v227, s88, v227
	v_cvt_pk_bf16_f32 v226, v226, v227
	ds_write_b16 v221, v226 offset:3456
	ds_write_b16_d16_hi v221, v226 offset:3520
	s_waitcnt vmcnt(2)
	v_mul_f32_e32 v226, v77, v155
	v_mul_f32_e32 v227, v93, v155
	v_fma_f32 v226, v93, v154, -v226
	v_fma_f32 v227, v77, v154, v227
	v_mul_f32_e32 v226, s88, v226
	v_mul_f32_e32 v227, s88, v227
	v_cvt_pk_bf16_f32 v226, v226, v227
	ds_write_b16 v221, v226 offset:3600
	ds_write_b16_d16_hi v221, v226 offset:3664
	s_waitcnt vmcnt(1)
	v_mul_f32_e32 v226, v78, v157
	v_mul_f32_e32 v227, v94, v157
	v_fma_f32 v226, v94, v156, -v226
	v_fma_f32 v227, v78, v156, v227
	v_mul_f32_e32 v226, s88, v226
	v_mul_f32_e32 v227, s88, v227
	v_cvt_pk_bf16_f32 v226, v226, v227
	ds_write_b16 v221, v226 offset:3744
	ds_write_b16_d16_hi v221, v226 offset:3808
	s_waitcnt vmcnt(0)
	v_mul_f32_e32 v226, v79, v159
	v_mul_f32_e32 v227, v95, v159
	v_fma_f32 v226, v95, v158, -v226
	v_fma_f32 v227, v79, v158, v227
	v_mul_f32_e32 v226, s88, v226
	v_mul_f32_e32 v227, s88, v227
	v_cvt_pk_bf16_f32 v226, v226, v227
	ds_write_b16 v221, v226 offset:3888
	ds_write_b16_d16_hi v221, v226 offset:3952
	s_branch .Lep4_01_st
.Lep4_01_mS:
	v_mul_f32_e32 v226, 0xbfb8aa3b, v80
	v_mul_f32_e32 v227, 0xbfb8aa3b, v64
	v_exp_f32_e32 v226, v226
	v_exp_f32_e32 v227, v227
	v_add_f32_e32 v226, 1.0, v226
	v_add_f32_e32 v227, 1.0, v227
	v_rcp_f32_e32 v226, v226
	v_rcp_f32_e32 v227, v227
	v_mul_f32_e32 v226, v80, v226
	v_mul_f32_e32 v227, v64, v227
	v_cvt_pk_bf16_f32 v226, v226, v227
	ds_write_b16 v221, v226
	ds_write_b16_d16_hi v221, v226 offset:64
	v_mul_f32_e32 v228, 0xbfb8aa3b, v81
	v_mul_f32_e32 v229, 0xbfb8aa3b, v65
	v_exp_f32_e32 v228, v228
	v_exp_f32_e32 v229, v229
	v_add_f32_e32 v228, 1.0, v228
	v_add_f32_e32 v229, 1.0, v229
	v_rcp_f32_e32 v228, v228
	v_rcp_f32_e32 v229, v229
	v_mul_f32_e32 v228, v81, v228
	v_mul_f32_e32 v229, v65, v229
	v_cvt_pk_bf16_f32 v228, v228, v229
	ds_write_b16 v221, v228 offset:144
	ds_write_b16_d16_hi v221, v228 offset:208
	v_mul_f32_e32 v226, 0xbfb8aa3b, v82
	v_mul_f32_e32 v227, 0xbfb8aa3b, v66
	v_exp_f32_e32 v226, v226
	v_exp_f32_e32 v227, v227
	v_add_f32_e32 v226, 1.0, v226
	v_add_f32_e32 v227, 1.0, v227
	v_rcp_f32_e32 v226, v226
	v_rcp_f32_e32 v227, v227
	v_mul_f32_e32 v226, v82, v226
	v_mul_f32_e32 v227, v66, v227
	v_cvt_pk_bf16_f32 v226, v226, v227
	ds_write_b16 v221, v226 offset:288
	ds_write_b16_d16_hi v221, v226 offset:352
	v_mul_f32_e32 v228, 0xbfb8aa3b, v83
	v_mul_f32_e32 v229, 0xbfb8aa3b, v67
	v_exp_f32_e32 v228, v228
	v_exp_f32_e32 v229, v229
	v_add_f32_e32 v228, 1.0, v228
	v_add_f32_e32 v229, 1.0, v229
	v_rcp_f32_e32 v228, v228
	v_rcp_f32_e32 v229, v229
	v_mul_f32_e32 v228, v83, v228
	v_mul_f32_e32 v229, v67, v229
	v_cvt_pk_bf16_f32 v228, v228, v229
	ds_write_b16 v221, v228 offset:432
	ds_write_b16_d16_hi v221, v228 offset:496
	v_mul_f32_e32 v226, 0xbfb8aa3b, v84
	v_mul_f32_e32 v227, 0xbfb8aa3b, v68
	v_exp_f32_e32 v226, v226
	v_exp_f32_e32 v227, v227
	v_add_f32_e32 v226, 1.0, v226
	v_add_f32_e32 v227, 1.0, v227
	v_rcp_f32_e32 v226, v226
	v_rcp_f32_e32 v227, v227
	v_mul_f32_e32 v226, v84, v226
	v_mul_f32_e32 v227, v68, v227
	v_cvt_pk_bf16_f32 v226, v226, v227
	ds_write_b16 v221, v226 offset:1152
	ds_write_b16_d16_hi v221, v226 offset:1216
	v_mul_f32_e32 v228, 0xbfb8aa3b, v85
	v_mul_f32_e32 v229, 0xbfb8aa3b, v69
	v_exp_f32_e32 v228, v228
	v_exp_f32_e32 v229, v229
	v_add_f32_e32 v228, 1.0, v228
	v_add_f32_e32 v229, 1.0, v229
	v_rcp_f32_e32 v228, v228
	v_rcp_f32_e32 v229, v229
	v_mul_f32_e32 v228, v85, v228
	v_mul_f32_e32 v229, v69, v229
	v_cvt_pk_bf16_f32 v228, v228, v229
	ds_write_b16 v221, v228 offset:1296
	ds_write_b16_d16_hi v221, v228 offset:1360
	v_mul_f32_e32 v226, 0xbfb8aa3b, v86
	v_mul_f32_e32 v227, 0xbfb8aa3b, v70
	v_exp_f32_e32 v226, v226
	v_exp_f32_e32 v227, v227
	v_add_f32_e32 v226, 1.0, v226
	v_add_f32_e32 v227, 1.0, v227
	v_rcp_f32_e32 v226, v226
	v_rcp_f32_e32 v227, v227
	v_mul_f32_e32 v226, v86, v226
	v_mul_f32_e32 v227, v70, v227
	v_cvt_pk_bf16_f32 v226, v226, v227
	ds_write_b16 v221, v226 offset:1440
	ds_write_b16_d16_hi v221, v226 offset:1504
	v_mul_f32_e32 v228, 0xbfb8aa3b, v87
	v_mul_f32_e32 v229, 0xbfb8aa3b, v71
	v_exp_f32_e32 v228, v228
	v_exp_f32_e32 v229, v229
	v_add_f32_e32 v228, 1.0, v228
	v_add_f32_e32 v229, 1.0, v229
	v_rcp_f32_e32 v228, v228
	v_rcp_f32_e32 v229, v229
	v_mul_f32_e32 v228, v87, v228
	v_mul_f32_e32 v229, v71, v229
	v_cvt_pk_bf16_f32 v228, v228, v229
	ds_write_b16 v221, v228 offset:1584
	ds_write_b16_d16_hi v221, v228 offset:1648
	v_mul_f32_e32 v226, 0xbfb8aa3b, v88
	v_mul_f32_e32 v227, 0xbfb8aa3b, v72
	v_exp_f32_e32 v226, v226
	v_exp_f32_e32 v227, v227
	v_add_f32_e32 v226, 1.0, v226
	v_add_f32_e32 v227, 1.0, v227
	v_rcp_f32_e32 v226, v226
	v_rcp_f32_e32 v227, v227
	v_mul_f32_e32 v226, v88, v226
	v_mul_f32_e32 v227, v72, v227
	v_cvt_pk_bf16_f32 v226, v226, v227
	ds_write_b16 v221, v226 offset:2304
	ds_write_b16_d16_hi v221, v226 offset:2368
	v_mul_f32_e32 v228, 0xbfb8aa3b, v89
	v_mul_f32_e32 v229, 0xbfb8aa3b, v73
	v_exp_f32_e32 v228, v228
	v_exp_f32_e32 v229, v229
	v_add_f32_e32 v228, 1.0, v228
	v_add_f32_e32 v229, 1.0, v229
	v_rcp_f32_e32 v228, v228
	v_rcp_f32_e32 v229, v229
	v_mul_f32_e32 v228, v89, v228
	v_mul_f32_e32 v229, v73, v229
	v_cvt_pk_bf16_f32 v228, v228, v229
	ds_write_b16 v221, v228 offset:2448
	ds_write_b16_d16_hi v221, v228 offset:2512
	v_mul_f32_e32 v226, 0xbfb8aa3b, v90
	v_mul_f32_e32 v227, 0xbfb8aa3b, v74
	v_exp_f32_e32 v226, v226
	v_exp_f32_e32 v227, v227
	v_add_f32_e32 v226, 1.0, v226
	v_add_f32_e32 v227, 1.0, v227
	v_rcp_f32_e32 v226, v226
	v_rcp_f32_e32 v227, v227
	v_mul_f32_e32 v226, v90, v226
	v_mul_f32_e32 v227, v74, v227
	v_cvt_pk_bf16_f32 v226, v226, v227
	ds_write_b16 v221, v226 offset:2592
	ds_write_b16_d16_hi v221, v226 offset:2656
	v_mul_f32_e32 v228, 0xbfb8aa3b, v91
	v_mul_f32_e32 v229, 0xbfb8aa3b, v75
	v_exp_f32_e32 v228, v228
	v_exp_f32_e32 v229, v229
	v_add_f32_e32 v228, 1.0, v228
	v_add_f32_e32 v229, 1.0, v229
	v_rcp_f32_e32 v228, v228
	v_rcp_f32_e32 v229, v229
	v_mul_f32_e32 v228, v91, v228
	v_mul_f32_e32 v229, v75, v229
	v_cvt_pk_bf16_f32 v228, v228, v229
	ds_write_b16 v221, v228 offset:2736
	ds_write_b16_d16_hi v221, v228 offset:2800
	v_mul_f32_e32 v226, 0xbfb8aa3b, v92
	v_mul_f32_e32 v227, 0xbfb8aa3b, v76
	v_exp_f32_e32 v226, v226
	v_exp_f32_e32 v227, v227
	v_add_f32_e32 v226, 1.0, v226
	v_add_f32_e32 v227, 1.0, v227
	v_rcp_f32_e32 v226, v226
	v_rcp_f32_e32 v227, v227
	v_mul_f32_e32 v226, v92, v226
	v_mul_f32_e32 v227, v76, v227
	v_cvt_pk_bf16_f32 v226, v226, v227
	ds_write_b16 v221, v226 offset:3456
	ds_write_b16_d16_hi v221, v226 offset:3520
	v_mul_f32_e32 v228, 0xbfb8aa3b, v93
	v_mul_f32_e32 v229, 0xbfb8aa3b, v77
	v_exp_f32_e32 v228, v228
	v_exp_f32_e32 v229, v229
	v_add_f32_e32 v228, 1.0, v228
	v_add_f32_e32 v229, 1.0, v229
	v_rcp_f32_e32 v228, v228
	v_rcp_f32_e32 v229, v229
	v_mul_f32_e32 v228, v93, v228
	v_mul_f32_e32 v229, v77, v229
	v_cvt_pk_bf16_f32 v228, v228, v229
	ds_write_b16 v221, v228 offset:3600
	ds_write_b16_d16_hi v221, v228 offset:3664
	v_mul_f32_e32 v226, 0xbfb8aa3b, v94
	v_mul_f32_e32 v227, 0xbfb8aa3b, v78
	v_exp_f32_e32 v226, v226
	v_exp_f32_e32 v227, v227
	v_add_f32_e32 v226, 1.0, v226
	v_add_f32_e32 v227, 1.0, v227
	v_rcp_f32_e32 v226, v226
	v_rcp_f32_e32 v227, v227
	v_mul_f32_e32 v226, v94, v226
	v_mul_f32_e32 v227, v78, v227
	v_cvt_pk_bf16_f32 v226, v226, v227
	ds_write_b16 v221, v226 offset:3744
	ds_write_b16_d16_hi v221, v226 offset:3808
	v_mul_f32_e32 v228, 0xbfb8aa3b, v95
	v_mul_f32_e32 v229, 0xbfb8aa3b, v79
	v_exp_f32_e32 v228, v228
	v_exp_f32_e32 v229, v229
	v_add_f32_e32 v228, 1.0, v228
	v_add_f32_e32 v229, 1.0, v229
	v_rcp_f32_e32 v228, v228
	v_rcp_f32_e32 v229, v229
	v_mul_f32_e32 v228, v95, v228
	v_mul_f32_e32 v229, v79, v229
	v_cvt_pk_bf16_f32 v228, v228, v229
	ds_write_b16 v221, v228 offset:3888
	ds_write_b16_d16_hi v221, v228 offset:3952
	s_branch .Lep4_01_st

.Lep4_01_end:
.Lep4_10:
	s_add_u32 s94, s92, 32
	s_add_u32 s95, s93, 0
	s_lshr_b32 s90, s95, 6
	s_cmp_lt_u32 s90, 16
	s_cbranch_scc1 .Lep4_10_t0
	s_cmp_lt_u32 s90, 20
	s_cbranch_scc1 .Lep4_10_t16
	s_cmp_lt_u32 s90, 24
	s_cbranch_scc1 .Lep4_10_t20
	s_cmp_lt_u32 s90, 28
	s_cbranch_scc1 .Lep4_10_t24
	s_cmp_lt_u32 s90, 32
	s_cbranch_scc1 .Lep4_10_t28
	s_cmp_lt_u32 s90, 36
	s_cbranch_scc1 .Lep4_10_t32
	s_cmp_lt_u32 s90, 40
	s_cbranch_scc1 .Lep4_10_t36
	s_cmp_lt_u32 s90, 56
	s_cbranch_scc1 .Lep4_10_t40
	s_cmp_lt_u32 s90, 57
	s_cbranch_scc1 .Lep4_10_t56
	s_branch .Lep4_10_end

.Lep4_10_mG:
	v_mul_f32_e32 v226, 0xbfb8aa3b, v48
	v_mul_f32_e32 v227, 0xbfb8aa3b, v32
	v_exp_f32_e32 v226, v226
	v_exp_f32_e32 v227, v227
	v_add_f32_e32 v226, 1.0, v226
	v_add_f32_e32 v227, 1.0, v227
	v_rcp_f32_e32 v226, v226
	v_rcp_f32_e32 v227, v227
	s_nop 0
	v_cvt_pk_bf16_f32 v226, v226, v227
	ds_write_b16 v221, v226
	ds_write_b16_d16_hi v221, v226 offset:64
	v_mul_f32_e32 v228, 0xbfb8aa3b, v49
	v_mul_f32_e32 v229, 0xbfb8aa3b, v33
	v_exp_f32_e32 v228, v228
	v_exp_f32_e32 v229, v229
	v_add_f32_e32 v228, 1.0, v228
	v_add_f32_e32 v229, 1.0, v229
	v_rcp_f32_e32 v228, v228
	v_rcp_f32_e32 v229, v229
	s_nop 0
	v_cvt_pk_bf16_f32 v228, v228, v229
	ds_write_b16 v221, v228 offset:144
	ds_write_b16_d16_hi v221, v228 offset:208
	v_mul_f32_e32 v226, 0xbfb8aa3b, v50
	v_mul_f32_e32 v227, 0xbfb8aa3b, v34
	v_exp_f32_e32 v226, v226
	v_exp_f32_e32 v227, v227
	v_add_f32_e32 v226, 1.0, v226
	v_add_f32_e32 v227, 1.0, v227
	v_rcp_f32_e32 v226, v226
	v_rcp_f32_e32 v227, v227
	s_nop 0
	v_cvt_pk_bf16_f32 v226, v226, v227
	ds_write_b16 v221, v226 offset:288
	ds_write_b16_d16_hi v221, v226 offset:352
	v_mul_f32_e32 v228, 0xbfb8aa3b, v51
	v_mul_f32_e32 v229, 0xbfb8aa3b, v35
	v_exp_f32_e32 v228, v228
	v_exp_f32_e32 v229, v229
	v_add_f32_e32 v228, 1.0, v228
	v_add_f32_e32 v229, 1.0, v229
	v_rcp_f32_e32 v228, v228
	v_rcp_f32_e32 v229, v229
	s_nop 0
	v_cvt_pk_bf16_f32 v228, v228, v229
	ds_write_b16 v221, v228 offset:432
	ds_write_b16_d16_hi v221, v228 offset:496
	v_mul_f32_e32 v226, 0xbfb8aa3b, v52
	v_mul_f32_e32 v227, 0xbfb8aa3b, v36
	v_exp_f32_e32 v226, v226
	v_exp_f32_e32 v227, v227
	v_add_f32_e32 v226, 1.0, v226
	v_add_f32_e32 v227, 1.0, v227
	v_rcp_f32_e32 v226, v226
	v_rcp_f32_e32 v227, v227
	s_nop 0
	v_cvt_pk_bf16_f32 v226, v226, v227
	ds_write_b16 v221, v226 offset:1152
	ds_write_b16_d16_hi v221, v226 offset:1216
	v_mul_f32_e32 v228, 0xbfb8aa3b, v53
	v_mul_f32_e32 v229, 0xbfb8aa3b, v37
	v_exp_f32_e32 v228, v228
	v_exp_f32_e32 v229, v229
	v_add_f32_e32 v228, 1.0, v228
	v_add_f32_e32 v229, 1.0, v229
	v_rcp_f32_e32 v228, v228
	v_rcp_f32_e32 v229, v229
	s_nop 0
	v_cvt_pk_bf16_f32 v228, v228, v229
	ds_write_b16 v221, v228 offset:1296
	ds_write_b16_d16_hi v221, v228 offset:1360
	v_mul_f32_e32 v226, 0xbfb8aa3b, v54
	v_mul_f32_e32 v227, 0xbfb8aa3b, v38
	v_exp_f32_e32 v226, v226
	v_exp_f32_e32 v227, v227
	v_add_f32_e32 v226, 1.0, v226
	v_add_f32_e32 v227, 1.0, v227
	v_rcp_f32_e32 v226, v226
	v_rcp_f32_e32 v227, v227
	s_nop 0
	v_cvt_pk_bf16_f32 v226, v226, v227
	ds_write_b16 v221, v226 offset:1440
	ds_write_b16_d16_hi v221, v226 offset:1504
	v_mul_f32_e32 v228, 0xbfb8aa3b, v55
	v_mul_f32_e32 v229, 0xbfb8aa3b, v39
	v_exp_f32_e32 v228, v228
	v_exp_f32_e32 v229, v229
	v_add_f32_e32 v228, 1.0, v228
	v_add_f32_e32 v229, 1.0, v229
	v_rcp_f32_e32 v228, v228
	v_rcp_f32_e32 v229, v229
	s_nop 0
	v_cvt_pk_bf16_f32 v228, v228, v229
	ds_write_b16 v221, v228 offset:1584
	ds_write_b16_d16_hi v221, v228 offset:1648
	v_mul_f32_e32 v226, 0xbfb8aa3b, v56
	v_mul_f32_e32 v227, 0xbfb8aa3b, v40
	v_exp_f32_e32 v226, v226
	v_exp_f32_e32 v227, v227
	v_add_f32_e32 v226, 1.0, v226
	v_add_f32_e32 v227, 1.0, v227
	v_rcp_f32_e32 v226, v226
	v_rcp_f32_e32 v227, v227
	s_nop 0
	v_cvt_pk_bf16_f32 v226, v226, v227
	ds_write_b16 v221, v226 offset:2304
	ds_write_b16_d16_hi v221, v226 offset:2368
	v_mul_f32_e32 v228, 0xbfb8aa3b, v57
	v_mul_f32_e32 v229, 0xbfb8aa3b, v41
	v_exp_f32_e32 v228, v228
	v_exp_f32_e32 v229, v229
	v_add_f32_e32 v228, 1.0, v228
	v_add_f32_e32 v229, 1.0, v229
	v_rcp_f32_e32 v228, v228
	v_rcp_f32_e32 v229, v229
	s_nop 0
	v_cvt_pk_bf16_f32 v228, v228, v229
	ds_write_b16 v221, v228 offset:2448
	ds_write_b16_d16_hi v221, v228 offset:2512
	v_mul_f32_e32 v226, 0xbfb8aa3b, v58
	v_mul_f32_e32 v227, 0xbfb8aa3b, v42
	v_exp_f32_e32 v226, v226
	v_exp_f32_e32 v227, v227
	v_add_f32_e32 v226, 1.0, v226
	v_add_f32_e32 v227, 1.0, v227
	v_rcp_f32_e32 v226, v226
	v_rcp_f32_e32 v227, v227
	s_nop 0
	v_cvt_pk_bf16_f32 v226, v226, v227
	ds_write_b16 v221, v226 offset:2592
	ds_write_b16_d16_hi v221, v226 offset:2656
	v_mul_f32_e32 v228, 0xbfb8aa3b, v59
	v_mul_f32_e32 v229, 0xbfb8aa3b, v43
	v_exp_f32_e32 v228, v228
	v_exp_f32_e32 v229, v229
	v_add_f32_e32 v228, 1.0, v228
	v_add_f32_e32 v229, 1.0, v229
	v_rcp_f32_e32 v228, v228
	v_rcp_f32_e32 v229, v229
	s_nop 0
	v_cvt_pk_bf16_f32 v228, v228, v229
	ds_write_b16 v221, v228 offset:2736
	ds_write_b16_d16_hi v221, v228 offset:2800
	v_mul_f32_e32 v226, 0xbfb8aa3b, v60
	v_mul_f32_e32 v227, 0xbfb8aa3b, v44
	v_exp_f32_e32 v226, v226
	v_exp_f32_e32 v227, v227
	v_add_f32_e32 v226, 1.0, v226
	v_add_f32_e32 v227, 1.0, v227
	v_rcp_f32_e32 v226, v226
	v_rcp_f32_e32 v227, v227
	s_nop 0
	v_cvt_pk_bf16_f32 v226, v226, v227
	ds_write_b16 v221, v226 offset:3456
	ds_write_b16_d16_hi v221, v226 offset:3520
	v_mul_f32_e32 v228, 0xbfb8aa3b, v61
	v_mul_f32_e32 v229, 0xbfb8aa3b, v45
	v_exp_f32_e32 v228, v228
	v_exp_f32_e32 v229, v229
	v_add_f32_e32 v228, 1.0, v228
	v_add_f32_e32 v229, 1.0, v229
	v_rcp_f32_e32 v228, v228
	v_rcp_f32_e32 v229, v229
	s_nop 0
	v_cvt_pk_bf16_f32 v228, v228, v229
	ds_write_b16 v221, v228 offset:3600
	ds_write_b16_d16_hi v221, v228 offset:3664
	v_mul_f32_e32 v226, 0xbfb8aa3b, v62
	v_mul_f32_e32 v227, 0xbfb8aa3b, v46
	v_exp_f32_e32 v226, v226
	v_exp_f32_e32 v227, v227
	v_add_f32_e32 v226, 1.0, v226
	v_add_f32_e32 v227, 1.0, v227
	v_rcp_f32_e32 v226, v226
	v_rcp_f32_e32 v227, v227
	s_nop 0
	v_cvt_pk_bf16_f32 v226, v226, v227
	ds_write_b16 v221, v226 offset:3744
	ds_write_b16_d16_hi v221, v226 offset:3808
	v_mul_f32_e32 v228, 0xbfb8aa3b, v63
	v_mul_f32_e32 v229, 0xbfb8aa3b, v47
	v_exp_f32_e32 v228, v228
	v_exp_f32_e32 v229, v229
	v_add_f32_e32 v228, 1.0, v228
	v_add_f32_e32 v229, 1.0, v229
	v_rcp_f32_e32 v228, v228
	v_rcp_f32_e32 v229, v229
	s_nop 0
	v_cvt_pk_bf16_f32 v228, v228, v229
	ds_write_b16 v221, v228 offset:3888
	ds_write_b16_d16_hi v221, v228 offset:3952
	s_branch .Lep4_10_st
.Lep4_10_mP:
	v_cvt_pk_bf16_f32 v226, v48, v32
	ds_write_b16 v221, v226
	ds_write_b16_d16_hi v221, v226 offset:64
	v_cvt_pk_bf16_f32 v227, v49, v33
	ds_write_b16 v221, v227 offset:144
	ds_write_b16_d16_hi v221, v227 offset:208
	v_cvt_pk_bf16_f32 v228, v50, v34
	ds_write_b16 v221, v228 offset:288
	ds_write_b16_d16_hi v221, v228 offset:352
	v_cvt_pk_bf16_f32 v229, v51, v35
	ds_write_b16 v221, v229 offset:432
	ds_write_b16_d16_hi v221, v229 offset:496
	v_cvt_pk_bf16_f32 v226, v52, v36
	ds_write_b16 v221, v226 offset:1152
	ds_write_b16_d16_hi v221, v226 offset:1216
	v_cvt_pk_bf16_f32 v227, v53, v37
	ds_write_b16 v221, v227 offset:1296
	ds_write_b16_d16_hi v221, v227 offset:1360
	v_cvt_pk_bf16_f32 v228, v54, v38
	ds_write_b16 v221, v228 offset:1440
	ds_write_b16_d16_hi v221, v228 offset:1504
	v_cvt_pk_bf16_f32 v229, v55, v39
	ds_write_b16 v221, v229 offset:1584
	ds_write_b16_d16_hi v221, v229 offset:1648
	v_cvt_pk_bf16_f32 v226, v56, v40
	ds_write_b16 v221, v226 offset:2304
	ds_write_b16_d16_hi v221, v226 offset:2368
	v_cvt_pk_bf16_f32 v227, v57, v41
	ds_write_b16 v221, v227 offset:2448
	ds_write_b16_d16_hi v221, v227 offset:2512
	v_cvt_pk_bf16_f32 v228, v58, v42
	ds_write_b16 v221, v228 offset:2592
	ds_write_b16_d16_hi v221, v228 offset:2656
	v_cvt_pk_bf16_f32 v229, v59, v43
	ds_write_b16 v221, v229 offset:2736
	ds_write_b16_d16_hi v221, v229 offset:2800
	v_cvt_pk_bf16_f32 v226, v60, v44
	ds_write_b16 v221, v226 offset:3456
	ds_write_b16_d16_hi v221, v226 offset:3520
	v_cvt_pk_bf16_f32 v227, v61, v45
	ds_write_b16 v221, v227 offset:3600
	ds_write_b16_d16_hi v221, v227 offset:3664
	v_cvt_pk_bf16_f32 v228, v62, v46
	ds_write_b16 v221, v228 offset:3744
	ds_write_b16_d16_hi v221, v228 offset:3808
	v_cvt_pk_bf16_f32 v229, v63, v47
	ds_write_b16 v221, v229 offset:3888
	ds_write_b16_d16_hi v221, v229 offset:3952
	s_branch .Lep4_10_st
.Lep4_10_mR:
	v_add_u32_e32 v226, s94, v223
	v_lshlrev_b32_e32 v226, 8, v226
	v_add_u32_e32 v232, v226, v220
	v_mov_b32_e32 v233, 0
	s_waitcnt lgkmcnt(0)
	v_lshl_add_u64 v[232:233], s[98:99], 0, v[232:233]
	global_load_dwordx2 v[128:129], v[232:233], off
	global_load_dwordx2 v[130:131], v[232:233], off offset:256
	global_load_dwordx2 v[132:133], v[232:233], off offset:512
	global_load_dwordx2 v[134:135], v[232:233], off offset:768
	global_load_dwordx2 v[136:137], v[232:233], off offset:2048
	global_load_dwordx2 v[138:139], v[232:233], off offset:2304
	global_load_dwordx2 v[140:141], v[232:233], off offset:2560
	global_load_dwordx2 v[142:143], v[232:233], off offset:2816
	v_add_co_u32_e32 v234, vcc, 0x1000, v232
	s_nop 1
	v_addc_co_u32_e32 v235, vcc, 0, v233, vcc
	global_load_dwordx2 v[144:145], v[234:235], off
	global_load_dwordx2 v[146:147], v[234:235], off offset:256
	global_load_dwordx2 v[148:149], v[234:235], off offset:512
	global_load_dwordx2 v[150:151], v[234:235], off offset:768
	global_load_dwordx2 v[152:153], v[234:235], off offset:2048
	global_load_dwordx2 v[154:155], v[234:235], off offset:2304
	global_load_dwordx2 v[156:157], v[234:235], off offset:2560
	global_load_dwordx2 v[158:159], v[234:235], off offset:2816
	s_waitcnt vmcnt(15)
	v_mul_f32_e32 v226, v32, v129
	v_mul_f32_e32 v227, v48, v129
	v_fma_f32 v226, v48, v128, -v226
	v_fma_f32 v227, v32, v128, v227
	v_mul_f32_e32 v226, s88, v226
	v_mul_f32_e32 v227, s88, v227
	v_cvt_pk_bf16_f32 v226, v226, v227
	ds_write_b16 v221, v226
	ds_write_b16_d16_hi v221, v226 offset:64
	s_waitcnt vmcnt(14)
	v_mul_f32_e32 v226, v33, v131
	v_mul_f32_e32 v227, v49, v131
	v_fma_f32 v226, v49, v130, -v226
	v_fma_f32 v227, v33, v130, v227
	v_mul_f32_e32 v226, s88, v226
	v_mul_f32_e32 v227, s88, v227
	v_cvt_pk_bf16_f32 v226, v226, v227
	ds_write_b16 v221, v226 offset:144
	ds_write_b16_d16_hi v221, v226 offset:208
	s_waitcnt vmcnt(13)
	v_mul_f32_e32 v226, v34, v133
	v_mul_f32_e32 v227, v50, v133
	v_fma_f32 v226, v50, v132, -v226
	v_fma_f32 v227, v34, v132, v227
	v_mul_f32_e32 v226, s88, v226
	v_mul_f32_e32 v227, s88, v227
	v_cvt_pk_bf16_f32 v226, v226, v227
	ds_write_b16 v221, v226 offset:288
	ds_write_b16_d16_hi v221, v226 offset:352
	s_waitcnt vmcnt(12)
	v_mul_f32_e32 v226, v35, v135
	v_mul_f32_e32 v227, v51, v135
	v_fma_f32 v226, v51, v134, -v226
	v_fma_f32 v227, v35, v134, v227
	v_mul_f32_e32 v226, s88, v226
	v_mul_f32_e32 v227, s88, v227
	v_cvt_pk_bf16_f32 v226, v226, v227
	ds_write_b16 v221, v226 offset:432
	ds_write_b16_d16_hi v221, v226 offset:496
	s_waitcnt vmcnt(11)
	v_mul_f32_e32 v226, v36, v137
	v_mul_f32_e32 v227, v52, v137
	v_fma_f32 v226, v52, v136, -v226
	v_fma_f32 v227, v36, v136, v227
	v_mul_f32_e32 v226, s88, v226
	v_mul_f32_e32 v227, s88, v227
	v_cvt_pk_bf16_f32 v226, v226, v227
	ds_write_b16 v221, v226 offset:1152
	ds_write_b16_d16_hi v221, v226 offset:1216
	s_waitcnt vmcnt(10)
	v_mul_f32_e32 v226, v37, v139
	v_mul_f32_e32 v227, v53, v139
	v_fma_f32 v226, v53, v138, -v226
	v_fma_f32 v227, v37, v138, v227
	v_mul_f32_e32 v226, s88, v226
	v_mul_f32_e32 v227, s88, v227
	v_cvt_pk_bf16_f32 v226, v226, v227
	ds_write_b16 v221, v226 offset:1296
	ds_write_b16_d16_hi v221, v226 offset:1360
	s_waitcnt vmcnt(9)
	v_mul_f32_e32 v226, v38, v141
	v_mul_f32_e32 v227, v54, v141
	v_fma_f32 v226, v54, v140, -v226
	v_fma_f32 v227, v38, v140, v227
	v_mul_f32_e32 v226, s88, v226
	v_mul_f32_e32 v227, s88, v227
	v_cvt_pk_bf16_f32 v226, v226, v227
	ds_write_b16 v221, v226 offset:1440
	ds_write_b16_d16_hi v221, v226 offset:1504
	s_waitcnt vmcnt(8)
	v_mul_f32_e32 v226, v39, v143
	v_mul_f32_e32 v227, v55, v143
	v_fma_f32 v226, v55, v142, -v226
	v_fma_f32 v227, v39, v142, v227
	v_mul_f32_e32 v226, s88, v226
	v_mul_f32_e32 v227, s88, v227
	v_cvt_pk_bf16_f32 v226, v226, v227
	ds_write_b16 v221, v226 offset:1584
	ds_write_b16_d16_hi v221, v226 offset:1648
	s_waitcnt vmcnt(7)
	v_mul_f32_e32 v226, v40, v145
	v_mul_f32_e32 v227, v56, v145
	v_fma_f32 v226, v56, v144, -v226
	v_fma_f32 v227, v40, v144, v227
	v_mul_f32_e32 v226, s88, v226
	v_mul_f32_e32 v227, s88, v227
	v_cvt_pk_bf16_f32 v226, v226, v227
	ds_write_b16 v221, v226 offset:2304
	ds_write_b16_d16_hi v221, v226 offset:2368
	s_waitcnt vmcnt(6)
	v_mul_f32_e32 v226, v41, v147
	v_mul_f32_e32 v227, v57, v147
	v_fma_f32 v226, v57, v146, -v226
	v_fma_f32 v227, v41, v146, v227
	v_mul_f32_e32 v226, s88, v226
	v_mul_f32_e32 v227, s88, v227
	v_cvt_pk_bf16_f32 v226, v226, v227
	ds_write_b16 v221, v226 offset:2448
	ds_write_b16_d16_hi v221, v226 offset:2512
	s_waitcnt vmcnt(5)
	v_mul_f32_e32 v226, v42, v149
	v_mul_f32_e32 v227, v58, v149
	v_fma_f32 v226, v58, v148, -v226
	v_fma_f32 v227, v42, v148, v227
	v_mul_f32_e32 v226, s88, v226
	v_mul_f32_e32 v227, s88, v227
	v_cvt_pk_bf16_f32 v226, v226, v227
	ds_write_b16 v221, v226 offset:2592
	ds_write_b16_d16_hi v221, v226 offset:2656
	s_waitcnt vmcnt(4)
	v_mul_f32_e32 v226, v43, v151
	v_mul_f32_e32 v227, v59, v151
	v_fma_f32 v226, v59, v150, -v226
	v_fma_f32 v227, v43, v150, v227
	v_mul_f32_e32 v226, s88, v226
	v_mul_f32_e32 v227, s88, v227
	v_cvt_pk_bf16_f32 v226, v226, v227
	ds_write_b16 v221, v226 offset:2736
	ds_write_b16_d16_hi v221, v226 offset:2800
	s_waitcnt vmcnt(3)
	v_mul_f32_e32 v226, v44, v153
	v_mul_f32_e32 v227, v60, v153
	v_fma_f32 v226, v60, v152, -v226
	v_fma_f32 v227, v44, v152, v227
	v_mul_f32_e32 v226, s88, v226
	v_mul_f32_e32 v227, s88, v227
	v_cvt_pk_bf16_f32 v226, v226, v227
	ds_write_b16 v221, v226 offset:3456
	ds_write_b16_d16_hi v221, v226 offset:3520
	s_waitcnt vmcnt(2)
	v_mul_f32_e32 v226, v45, v155
	v_mul_f32_e32 v227, v61, v155
	v_fma_f32 v226, v61, v154, -v226
	v_fma_f32 v227, v45, v154, v227
	v_mul_f32_e32 v226, s88, v226
	v_mul_f32_e32 v227, s88, v227
	v_cvt_pk_bf16_f32 v226, v226, v227
	ds_write_b16 v221, v226 offset:3600
	ds_write_b16_d16_hi v221, v226 offset:3664
	s_waitcnt vmcnt(1)
	v_mul_f32_e32 v226, v46, v157
	v_mul_f32_e32 v227, v62, v157
	v_fma_f32 v226, v62, v156, -v226
	v_fma_f32 v227, v46, v156, v227
	v_mul_f32_e32 v226, s88, v226
	v_mul_f32_e32 v227, s88, v227
	v_cvt_pk_bf16_f32 v226, v226, v227
	ds_write_b16 v221, v226 offset:3744
	ds_write_b16_d16_hi v221, v226 offset:3808
	s_waitcnt vmcnt(0)
	v_mul_f32_e32 v226, v47, v159
	v_mul_f32_e32 v227, v63, v159
	v_fma_f32 v226, v63, v158, -v226
	v_fma_f32 v227, v47, v158, v227
	v_mul_f32_e32 v226, s88, v226
	v_mul_f32_e32 v227, s88, v227
	v_cvt_pk_bf16_f32 v226, v226, v227
	ds_write_b16 v221, v226 offset:3888
	ds_write_b16_d16_hi v221, v226 offset:3952
	s_branch .Lep4_10_st
.Lep4_10_mS:
	v_mul_f32_e32 v226, 0xbfb8aa3b, v48
	v_mul_f32_e32 v227, 0xbfb8aa3b, v32
	v_exp_f32_e32 v226, v226
	v_exp_f32_e32 v227, v227
	v_add_f32_e32 v226, 1.0, v226
	v_add_f32_e32 v227, 1.0, v227
	v_rcp_f32_e32 v226, v226
	v_rcp_f32_e32 v227, v227
	v_mul_f32_e32 v226, v48, v226
	v_mul_f32_e32 v227, v32, v227
	v_cvt_pk_bf16_f32 v226, v226, v227
	ds_write_b16 v221, v226
	ds_write_b16_d16_hi v221, v226 offset:64
	v_mul_f32_e32 v228, 0xbfb8aa3b, v49
	v_mul_f32_e32 v229, 0xbfb8aa3b, v33
	v_exp_f32_e32 v228, v228
	v_exp_f32_e32 v229, v229
	v_add_f32_e32 v228, 1.0, v228
	v_add_f32_e32 v229, 1.0, v229
	v_rcp_f32_e32 v228, v228
	v_rcp_f32_e32 v229, v229
	v_mul_f32_e32 v228, v49, v228
	v_mul_f32_e32 v229, v33, v229
	v_cvt_pk_bf16_f32 v228, v228, v229
	ds_write_b16 v221, v228 offset:144
	ds_write_b16_d16_hi v221, v228 offset:208
	v_mul_f32_e32 v226, 0xbfb8aa3b, v50
	v_mul_f32_e32 v227, 0xbfb8aa3b, v34
	v_exp_f32_e32 v226, v226
	v_exp_f32_e32 v227, v227
	v_add_f32_e32 v226, 1.0, v226
	v_add_f32_e32 v227, 1.0, v227
	v_rcp_f32_e32 v226, v226
	v_rcp_f32_e32 v227, v227
	v_mul_f32_e32 v226, v50, v226
	v_mul_f32_e32 v227, v34, v227
	v_cvt_pk_bf16_f32 v226, v226, v227
	ds_write_b16 v221, v226 offset:288
	ds_write_b16_d16_hi v221, v226 offset:352
	v_mul_f32_e32 v228, 0xbfb8aa3b, v51
	v_mul_f32_e32 v229, 0xbfb8aa3b, v35
	v_exp_f32_e32 v228, v228
	v_exp_f32_e32 v229, v229
	v_add_f32_e32 v228, 1.0, v228
	v_add_f32_e32 v229, 1.0, v229
	v_rcp_f32_e32 v228, v228
	v_rcp_f32_e32 v229, v229
	v_mul_f32_e32 v228, v51, v228
	v_mul_f32_e32 v229, v35, v229
	v_cvt_pk_bf16_f32 v228, v228, v229
	ds_write_b16 v221, v228 offset:432
	ds_write_b16_d16_hi v221, v228 offset:496
	v_mul_f32_e32 v226, 0xbfb8aa3b, v52
	v_mul_f32_e32 v227, 0xbfb8aa3b, v36
	v_exp_f32_e32 v226, v226
	v_exp_f32_e32 v227, v227
	v_add_f32_e32 v226, 1.0, v226
	v_add_f32_e32 v227, 1.0, v227
	v_rcp_f32_e32 v226, v226
	v_rcp_f32_e32 v227, v227
	v_mul_f32_e32 v226, v52, v226
	v_mul_f32_e32 v227, v36, v227
	v_cvt_pk_bf16_f32 v226, v226, v227
	ds_write_b16 v221, v226 offset:1152
	ds_write_b16_d16_hi v221, v226 offset:1216
	v_mul_f32_e32 v228, 0xbfb8aa3b, v53
	v_mul_f32_e32 v229, 0xbfb8aa3b, v37
	v_exp_f32_e32 v228, v228
	v_exp_f32_e32 v229, v229
	v_add_f32_e32 v228, 1.0, v228
	v_add_f32_e32 v229, 1.0, v229
	v_rcp_f32_e32 v228, v228
	v_rcp_f32_e32 v229, v229
	v_mul_f32_e32 v228, v53, v228
	v_mul_f32_e32 v229, v37, v229
	v_cvt_pk_bf16_f32 v228, v228, v229
	ds_write_b16 v221, v228 offset:1296
	ds_write_b16_d16_hi v221, v228 offset:1360
	v_mul_f32_e32 v226, 0xbfb8aa3b, v54
	v_mul_f32_e32 v227, 0xbfb8aa3b, v38
	v_exp_f32_e32 v226, v226
	v_exp_f32_e32 v227, v227
	v_add_f32_e32 v226, 1.0, v226
	v_add_f32_e32 v227, 1.0, v227
	v_rcp_f32_e32 v226, v226
	v_rcp_f32_e32 v227, v227
	v_mul_f32_e32 v226, v54, v226
	v_mul_f32_e32 v227, v38, v227
	v_cvt_pk_bf16_f32 v226, v226, v227
	ds_write_b16 v221, v226 offset:1440
	ds_write_b16_d16_hi v221, v226 offset:1504
	v_mul_f32_e32 v228, 0xbfb8aa3b, v55
	v_mul_f32_e32 v229, 0xbfb8aa3b, v39
	v_exp_f32_e32 v228, v228
	v_exp_f32_e32 v229, v229
	v_add_f32_e32 v228, 1.0, v228
	v_add_f32_e32 v229, 1.0, v229
	v_rcp_f32_e32 v228, v228
	v_rcp_f32_e32 v229, v229
	v_mul_f32_e32 v228, v55, v228
	v_mul_f32_e32 v229, v39, v229
	v_cvt_pk_bf16_f32 v228, v228, v229
	ds_write_b16 v221, v228 offset:1584
	ds_write_b16_d16_hi v221, v228 offset:1648
	v_mul_f32_e32 v226, 0xbfb8aa3b, v56
	v_mul_f32_e32 v227, 0xbfb8aa3b, v40
	v_exp_f32_e32 v226, v226
	v_exp_f32_e32 v227, v227
	v_add_f32_e32 v226, 1.0, v226
	v_add_f32_e32 v227, 1.0, v227
	v_rcp_f32_e32 v226, v226
	v_rcp_f32_e32 v227, v227
	v_mul_f32_e32 v226, v56, v226
	v_mul_f32_e32 v227, v40, v227
	v_cvt_pk_bf16_f32 v226, v226, v227
	ds_write_b16 v221, v226 offset:2304
	ds_write_b16_d16_hi v221, v226 offset:2368
	v_mul_f32_e32 v228, 0xbfb8aa3b, v57
	v_mul_f32_e32 v229, 0xbfb8aa3b, v41
	v_exp_f32_e32 v228, v228
	v_exp_f32_e32 v229, v229
	v_add_f32_e32 v228, 1.0, v228
	v_add_f32_e32 v229, 1.0, v229
	v_rcp_f32_e32 v228, v228
	v_rcp_f32_e32 v229, v229
	v_mul_f32_e32 v228, v57, v228
	v_mul_f32_e32 v229, v41, v229
	v_cvt_pk_bf16_f32 v228, v228, v229
	ds_write_b16 v221, v228 offset:2448
	ds_write_b16_d16_hi v221, v228 offset:2512
	v_mul_f32_e32 v226, 0xbfb8aa3b, v58
	v_mul_f32_e32 v227, 0xbfb8aa3b, v42
	v_exp_f32_e32 v226, v226
	v_exp_f32_e32 v227, v227
	v_add_f32_e32 v226, 1.0, v226
	v_add_f32_e32 v227, 1.0, v227
	v_rcp_f32_e32 v226, v226
	v_rcp_f32_e32 v227, v227
	v_mul_f32_e32 v226, v58, v226
	v_mul_f32_e32 v227, v42, v227
	v_cvt_pk_bf16_f32 v226, v226, v227
	ds_write_b16 v221, v226 offset:2592
	ds_write_b16_d16_hi v221, v226 offset:2656
	v_mul_f32_e32 v228, 0xbfb8aa3b, v59
	v_mul_f32_e32 v229, 0xbfb8aa3b, v43
	v_exp_f32_e32 v228, v228
	v_exp_f32_e32 v229, v229
	v_add_f32_e32 v228, 1.0, v228
	v_add_f32_e32 v229, 1.0, v229
	v_rcp_f32_e32 v228, v228
	v_rcp_f32_e32 v229, v229
	v_mul_f32_e32 v228, v59, v228
	v_mul_f32_e32 v229, v43, v229
	v_cvt_pk_bf16_f32 v228, v228, v229
	ds_write_b16 v221, v228 offset:2736
	ds_write_b16_d16_hi v221, v228 offset:2800
	v_mul_f32_e32 v226, 0xbfb8aa3b, v60
	v_mul_f32_e32 v227, 0xbfb8aa3b, v44
	v_exp_f32_e32 v226, v226
	v_exp_f32_e32 v227, v227
	v_add_f32_e32 v226, 1.0, v226
	v_add_f32_e32 v227, 1.0, v227
	v_rcp_f32_e32 v226, v226
	v_rcp_f32_e32 v227, v227
	v_mul_f32_e32 v226, v60, v226
	v_mul_f32_e32 v227, v44, v227
	v_cvt_pk_bf16_f32 v226, v226, v227
	ds_write_b16 v221, v226 offset:3456
	ds_write_b16_d16_hi v221, v226 offset:3520
	v_mul_f32_e32 v228, 0xbfb8aa3b, v61
	v_mul_f32_e32 v229, 0xbfb8aa3b, v45
	v_exp_f32_e32 v228, v228
	v_exp_f32_e32 v229, v229
	v_add_f32_e32 v228, 1.0, v228
	v_add_f32_e32 v229, 1.0, v229
	v_rcp_f32_e32 v228, v228
	v_rcp_f32_e32 v229, v229
	v_mul_f32_e32 v228, v61, v228
	v_mul_f32_e32 v229, v45, v229
	v_cvt_pk_bf16_f32 v228, v228, v229
	ds_write_b16 v221, v228 offset:3600
	ds_write_b16_d16_hi v221, v228 offset:3664
	v_mul_f32_e32 v226, 0xbfb8aa3b, v62
	v_mul_f32_e32 v227, 0xbfb8aa3b, v46
	v_exp_f32_e32 v226, v226
	v_exp_f32_e32 v227, v227
	v_add_f32_e32 v226, 1.0, v226
	v_add_f32_e32 v227, 1.0, v227
	v_rcp_f32_e32 v226, v226
	v_rcp_f32_e32 v227, v227
	v_mul_f32_e32 v226, v62, v226
	v_mul_f32_e32 v227, v46, v227
	v_cvt_pk_bf16_f32 v226, v226, v227
	ds_write_b16 v221, v226 offset:3744
	ds_write_b16_d16_hi v221, v226 offset:3808
	v_mul_f32_e32 v228, 0xbfb8aa3b, v63
	v_mul_f32_e32 v229, 0xbfb8aa3b, v47
	v_exp_f32_e32 v228, v228
	v_exp_f32_e32 v229, v229
	v_add_f32_e32 v228, 1.0, v228
	v_add_f32_e32 v229, 1.0, v229
	v_rcp_f32_e32 v228, v228
	v_rcp_f32_e32 v229, v229
	v_mul_f32_e32 v228, v63, v228
	v_mul_f32_e32 v229, v47, v229
	v_cvt_pk_bf16_f32 v228, v228, v229
	ds_write_b16 v221, v228 offset:3888
	ds_write_b16_d16_hi v221, v228 offset:3952
	s_branch .Lep4_10_st

.Lep4_10_end:
.Lep4_11:
	s_add_u32 s94, s92, 32
	s_add_u32 s95, s93, 64
	s_lshr_b32 s90, s95, 6
	s_cmp_lt_u32 s90, 16
	s_cbranch_scc1 .Lep4_11_t0
	s_cmp_lt_u32 s90, 20
	s_cbranch_scc1 .Lep4_11_t16
	s_cmp_lt_u32 s90, 24
	s_cbranch_scc1 .Lep4_11_t20
	s_cmp_lt_u32 s90, 28
	s_cbranch_scc1 .Lep4_11_t24
	s_cmp_lt_u32 s90, 32
	s_cbranch_scc1 .Lep4_11_t28
	s_cmp_lt_u32 s90, 36
	s_cbranch_scc1 .Lep4_11_t32
	s_cmp_lt_u32 s90, 40
	s_cbranch_scc1 .Lep4_11_t36
	s_cmp_lt_u32 s90, 56
	s_cbranch_scc1 .Lep4_11_t40
	s_cmp_lt_u32 s90, 57
	s_cbranch_scc1 .Lep4_11_t56
	s_branch .Lep4_11_end

.Lep4_11_mG:
	v_mul_f32_e32 v226, 0xbfb8aa3b, v16
	v_mul_f32_e32 v227, 0xbfb8aa3b, v0
	v_exp_f32_e32 v226, v226
	v_exp_f32_e32 v227, v227
	v_add_f32_e32 v226, 1.0, v226
	v_add_f32_e32 v227, 1.0, v227
	v_rcp_f32_e32 v226, v226
	v_rcp_f32_e32 v227, v227
	s_nop 0
	v_cvt_pk_bf16_f32 v226, v226, v227
	ds_write_b16 v221, v226
	ds_write_b16_d16_hi v221, v226 offset:64
	v_mul_f32_e32 v228, 0xbfb8aa3b, v17
	v_mul_f32_e32 v229, 0xbfb8aa3b, v1
	v_exp_f32_e32 v228, v228
	v_exp_f32_e32 v229, v229
	v_add_f32_e32 v228, 1.0, v228
	v_add_f32_e32 v229, 1.0, v229
	v_rcp_f32_e32 v228, v228
	v_rcp_f32_e32 v229, v229
	s_nop 0
	v_cvt_pk_bf16_f32 v228, v228, v229
	ds_write_b16 v221, v228 offset:144
	ds_write_b16_d16_hi v221, v228 offset:208
	v_mul_f32_e32 v226, 0xbfb8aa3b, v18
	v_mul_f32_e32 v227, 0xbfb8aa3b, v2
	v_exp_f32_e32 v226, v226
	v_exp_f32_e32 v227, v227
	v_add_f32_e32 v226, 1.0, v226
	v_add_f32_e32 v227, 1.0, v227
	v_rcp_f32_e32 v226, v226
	v_rcp_f32_e32 v227, v227
	s_nop 0
	v_cvt_pk_bf16_f32 v226, v226, v227
	ds_write_b16 v221, v226 offset:288
	ds_write_b16_d16_hi v221, v226 offset:352
	v_mul_f32_e32 v228, 0xbfb8aa3b, v19
	v_mul_f32_e32 v229, 0xbfb8aa3b, v3
	v_exp_f32_e32 v228, v228
	v_exp_f32_e32 v229, v229
	v_add_f32_e32 v228, 1.0, v228
	v_add_f32_e32 v229, 1.0, v229
	v_rcp_f32_e32 v228, v228
	v_rcp_f32_e32 v229, v229
	s_nop 0
	v_cvt_pk_bf16_f32 v228, v228, v229
	ds_write_b16 v221, v228 offset:432
	ds_write_b16_d16_hi v221, v228 offset:496
	v_mul_f32_e32 v226, 0xbfb8aa3b, v20
	v_mul_f32_e32 v227, 0xbfb8aa3b, v4
	v_exp_f32_e32 v226, v226
	v_exp_f32_e32 v227, v227
	v_add_f32_e32 v226, 1.0, v226
	v_add_f32_e32 v227, 1.0, v227
	v_rcp_f32_e32 v226, v226
	v_rcp_f32_e32 v227, v227
	s_nop 0
	v_cvt_pk_bf16_f32 v226, v226, v227
	ds_write_b16 v221, v226 offset:1152
	ds_write_b16_d16_hi v221, v226 offset:1216
	v_mul_f32_e32 v228, 0xbfb8aa3b, v21
	v_mul_f32_e32 v229, 0xbfb8aa3b, v5
	v_exp_f32_e32 v228, v228
	v_exp_f32_e32 v229, v229
	v_add_f32_e32 v228, 1.0, v228
	v_add_f32_e32 v229, 1.0, v229
	v_rcp_f32_e32 v228, v228
	v_rcp_f32_e32 v229, v229
	s_nop 0
	v_cvt_pk_bf16_f32 v228, v228, v229
	ds_write_b16 v221, v228 offset:1296
	ds_write_b16_d16_hi v221, v228 offset:1360
	v_mul_f32_e32 v226, 0xbfb8aa3b, v22
	v_mul_f32_e32 v227, 0xbfb8aa3b, v6
	v_exp_f32_e32 v226, v226
	v_exp_f32_e32 v227, v227
	v_add_f32_e32 v226, 1.0, v226
	v_add_f32_e32 v227, 1.0, v227
	v_rcp_f32_e32 v226, v226
	v_rcp_f32_e32 v227, v227
	s_nop 0
	v_cvt_pk_bf16_f32 v226, v226, v227
	ds_write_b16 v221, v226 offset:1440
	ds_write_b16_d16_hi v221, v226 offset:1504
	v_mul_f32_e32 v228, 0xbfb8aa3b, v23
	v_mul_f32_e32 v229, 0xbfb8aa3b, v7
	v_exp_f32_e32 v228, v228
	v_exp_f32_e32 v229, v229
	v_add_f32_e32 v228, 1.0, v228
	v_add_f32_e32 v229, 1.0, v229
	v_rcp_f32_e32 v228, v228
	v_rcp_f32_e32 v229, v229
	s_nop 0
	v_cvt_pk_bf16_f32 v228, v228, v229
	ds_write_b16 v221, v228 offset:1584
	ds_write_b16_d16_hi v221, v228 offset:1648
	v_mul_f32_e32 v226, 0xbfb8aa3b, v24
	v_mul_f32_e32 v227, 0xbfb8aa3b, v8
	v_exp_f32_e32 v226, v226
	v_exp_f32_e32 v227, v227
	v_add_f32_e32 v226, 1.0, v226
	v_add_f32_e32 v227, 1.0, v227
	v_rcp_f32_e32 v226, v226
	v_rcp_f32_e32 v227, v227
	s_nop 0
	v_cvt_pk_bf16_f32 v226, v226, v227
	ds_write_b16 v221, v226 offset:2304
	ds_write_b16_d16_hi v221, v226 offset:2368
	v_mul_f32_e32 v228, 0xbfb8aa3b, v25
	v_mul_f32_e32 v229, 0xbfb8aa3b, v9
	v_exp_f32_e32 v228, v228
	v_exp_f32_e32 v229, v229
	v_add_f32_e32 v228, 1.0, v228
	v_add_f32_e32 v229, 1.0, v229
	v_rcp_f32_e32 v228, v228
	v_rcp_f32_e32 v229, v229
	s_nop 0
	v_cvt_pk_bf16_f32 v228, v228, v229
	ds_write_b16 v221, v228 offset:2448
	ds_write_b16_d16_hi v221, v228 offset:2512
	v_mul_f32_e32 v226, 0xbfb8aa3b, v26
	v_mul_f32_e32 v227, 0xbfb8aa3b, v10
	v_exp_f32_e32 v226, v226
	v_exp_f32_e32 v227, v227
	v_add_f32_e32 v226, 1.0, v226
	v_add_f32_e32 v227, 1.0, v227
	v_rcp_f32_e32 v226, v226
	v_rcp_f32_e32 v227, v227
	s_nop 0
	v_cvt_pk_bf16_f32 v226, v226, v227
	ds_write_b16 v221, v226 offset:2592
	ds_write_b16_d16_hi v221, v226 offset:2656
	v_mul_f32_e32 v228, 0xbfb8aa3b, v27
	v_mul_f32_e32 v229, 0xbfb8aa3b, v11
	v_exp_f32_e32 v228, v228
	v_exp_f32_e32 v229, v229
	v_add_f32_e32 v228, 1.0, v228
	v_add_f32_e32 v229, 1.0, v229
	v_rcp_f32_e32 v228, v228
	v_rcp_f32_e32 v229, v229
	s_nop 0
	v_cvt_pk_bf16_f32 v228, v228, v229
	ds_write_b16 v221, v228 offset:2736
	ds_write_b16_d16_hi v221, v228 offset:2800
	v_mul_f32_e32 v226, 0xbfb8aa3b, v28
	v_mul_f32_e32 v227, 0xbfb8aa3b, v12
	v_exp_f32_e32 v226, v226
	v_exp_f32_e32 v227, v227
	v_add_f32_e32 v226, 1.0, v226
	v_add_f32_e32 v227, 1.0, v227
	v_rcp_f32_e32 v226, v226
	v_rcp_f32_e32 v227, v227
	s_nop 0
	v_cvt_pk_bf16_f32 v226, v226, v227
	ds_write_b16 v221, v226 offset:3456
	ds_write_b16_d16_hi v221, v226 offset:3520
	v_mul_f32_e32 v228, 0xbfb8aa3b, v29
	v_mul_f32_e32 v229, 0xbfb8aa3b, v13
	v_exp_f32_e32 v228, v228
	v_exp_f32_e32 v229, v229
	v_add_f32_e32 v228, 1.0, v228
	v_add_f32_e32 v229, 1.0, v229
	v_rcp_f32_e32 v228, v228
	v_rcp_f32_e32 v229, v229
	s_nop 0
	v_cvt_pk_bf16_f32 v228, v228, v229
	ds_write_b16 v221, v228 offset:3600
	ds_write_b16_d16_hi v221, v228 offset:3664
	v_mul_f32_e32 v226, 0xbfb8aa3b, v30
	v_mul_f32_e32 v227, 0xbfb8aa3b, v14
	v_exp_f32_e32 v226, v226
	v_exp_f32_e32 v227, v227
	v_add_f32_e32 v226, 1.0, v226
	v_add_f32_e32 v227, 1.0, v227
	v_rcp_f32_e32 v226, v226
	v_rcp_f32_e32 v227, v227
	s_nop 0
	v_cvt_pk_bf16_f32 v226, v226, v227
	ds_write_b16 v221, v226 offset:3744
	ds_write_b16_d16_hi v221, v226 offset:3808
	v_mul_f32_e32 v228, 0xbfb8aa3b, v31
	v_mul_f32_e32 v229, 0xbfb8aa3b, v15
	v_exp_f32_e32 v228, v228
	v_exp_f32_e32 v229, v229
	v_add_f32_e32 v228, 1.0, v228
	v_add_f32_e32 v229, 1.0, v229
	v_rcp_f32_e32 v228, v228
	v_rcp_f32_e32 v229, v229
	s_nop 0
	v_cvt_pk_bf16_f32 v228, v228, v229
	ds_write_b16 v221, v228 offset:3888
	ds_write_b16_d16_hi v221, v228 offset:3952
	s_branch .Lep4_11_st
.Lep4_11_mP:
	v_cvt_pk_bf16_f32 v226, v16, v0
	ds_write_b16 v221, v226
	ds_write_b16_d16_hi v221, v226 offset:64
	v_cvt_pk_bf16_f32 v227, v17, v1
	ds_write_b16 v221, v227 offset:144
	ds_write_b16_d16_hi v221, v227 offset:208
	v_cvt_pk_bf16_f32 v228, v18, v2
	ds_write_b16 v221, v228 offset:288
	ds_write_b16_d16_hi v221, v228 offset:352
	v_cvt_pk_bf16_f32 v229, v19, v3
	ds_write_b16 v221, v229 offset:432
	ds_write_b16_d16_hi v221, v229 offset:496
	v_cvt_pk_bf16_f32 v226, v20, v4
	ds_write_b16 v221, v226 offset:1152
	ds_write_b16_d16_hi v221, v226 offset:1216
	v_cvt_pk_bf16_f32 v227, v21, v5
	ds_write_b16 v221, v227 offset:1296
	ds_write_b16_d16_hi v221, v227 offset:1360
	v_cvt_pk_bf16_f32 v228, v22, v6
	ds_write_b16 v221, v228 offset:1440
	ds_write_b16_d16_hi v221, v228 offset:1504
	v_cvt_pk_bf16_f32 v229, v23, v7
	ds_write_b16 v221, v229 offset:1584
	ds_write_b16_d16_hi v221, v229 offset:1648
	v_cvt_pk_bf16_f32 v226, v24, v8
	ds_write_b16 v221, v226 offset:2304
	ds_write_b16_d16_hi v221, v226 offset:2368
	v_cvt_pk_bf16_f32 v227, v25, v9
	ds_write_b16 v221, v227 offset:2448
	ds_write_b16_d16_hi v221, v227 offset:2512
	v_cvt_pk_bf16_f32 v228, v26, v10
	ds_write_b16 v221, v228 offset:2592
	ds_write_b16_d16_hi v221, v228 offset:2656
	v_cvt_pk_bf16_f32 v229, v27, v11
	ds_write_b16 v221, v229 offset:2736
	ds_write_b16_d16_hi v221, v229 offset:2800
	v_cvt_pk_bf16_f32 v226, v28, v12
	ds_write_b16 v221, v226 offset:3456
	ds_write_b16_d16_hi v221, v226 offset:3520
	v_cvt_pk_bf16_f32 v227, v29, v13
	ds_write_b16 v221, v227 offset:3600
	ds_write_b16_d16_hi v221, v227 offset:3664
	v_cvt_pk_bf16_f32 v228, v30, v14
	ds_write_b16 v221, v228 offset:3744
	ds_write_b16_d16_hi v221, v228 offset:3808
	v_cvt_pk_bf16_f32 v229, v31, v15
	ds_write_b16 v221, v229 offset:3888
	ds_write_b16_d16_hi v221, v229 offset:3952
	s_branch .Lep4_11_st
.Lep4_11_mR:
	v_add_u32_e32 v226, s94, v223
	v_lshlrev_b32_e32 v226, 8, v226
	v_add_u32_e32 v232, v226, v220
	v_mov_b32_e32 v233, 0
	s_waitcnt lgkmcnt(0)
	v_lshl_add_u64 v[232:233], s[98:99], 0, v[232:233]
	global_load_dwordx2 v[128:129], v[232:233], off
	global_load_dwordx2 v[130:131], v[232:233], off offset:256
	global_load_dwordx2 v[132:133], v[232:233], off offset:512
	global_load_dwordx2 v[134:135], v[232:233], off offset:768
	global_load_dwordx2 v[136:137], v[232:233], off offset:2048
	global_load_dwordx2 v[138:139], v[232:233], off offset:2304
	global_load_dwordx2 v[140:141], v[232:233], off offset:2560
	global_load_dwordx2 v[142:143], v[232:233], off offset:2816
	v_add_co_u32_e32 v234, vcc, 0x1000, v232
	s_nop 1
	v_addc_co_u32_e32 v235, vcc, 0, v233, vcc
	global_load_dwordx2 v[144:145], v[234:235], off
	global_load_dwordx2 v[146:147], v[234:235], off offset:256
	global_load_dwordx2 v[148:149], v[234:235], off offset:512
	global_load_dwordx2 v[150:151], v[234:235], off offset:768
	global_load_dwordx2 v[152:153], v[234:235], off offset:2048
	global_load_dwordx2 v[154:155], v[234:235], off offset:2304
	global_load_dwordx2 v[156:157], v[234:235], off offset:2560
	global_load_dwordx2 v[158:159], v[234:235], off offset:2816
	s_waitcnt vmcnt(15)
	v_mul_f32_e32 v226, v0, v129
	v_mul_f32_e32 v227, v16, v129
	v_fma_f32 v226, v16, v128, -v226
	v_fma_f32 v227, v0, v128, v227
	v_mul_f32_e32 v226, s88, v226
	v_mul_f32_e32 v227, s88, v227
	v_cvt_pk_bf16_f32 v226, v226, v227
	ds_write_b16 v221, v226
	ds_write_b16_d16_hi v221, v226 offset:64
	s_waitcnt vmcnt(14)
	v_mul_f32_e32 v226, v1, v131
	v_mul_f32_e32 v227, v17, v131
	v_fma_f32 v226, v17, v130, -v226
	v_fma_f32 v227, v1, v130, v227
	v_mul_f32_e32 v226, s88, v226
	v_mul_f32_e32 v227, s88, v227
	v_cvt_pk_bf16_f32 v226, v226, v227
	ds_write_b16 v221, v226 offset:144
	ds_write_b16_d16_hi v221, v226 offset:208
	s_waitcnt vmcnt(13)
	v_mul_f32_e32 v226, v2, v133
	v_mul_f32_e32 v227, v18, v133
	v_fma_f32 v226, v18, v132, -v226
	v_fma_f32 v227, v2, v132, v227
	v_mul_f32_e32 v226, s88, v226
	v_mul_f32_e32 v227, s88, v227
	v_cvt_pk_bf16_f32 v226, v226, v227
	ds_write_b16 v221, v226 offset:288
	ds_write_b16_d16_hi v221, v226 offset:352
	s_waitcnt vmcnt(12)
	v_mul_f32_e32 v226, v3, v135
	v_mul_f32_e32 v227, v19, v135
	v_fma_f32 v226, v19, v134, -v226
	v_fma_f32 v227, v3, v134, v227
	v_mul_f32_e32 v226, s88, v226
	v_mul_f32_e32 v227, s88, v227
	v_cvt_pk_bf16_f32 v226, v226, v227
	ds_write_b16 v221, v226 offset:432
	ds_write_b16_d16_hi v221, v226 offset:496
	s_waitcnt vmcnt(11)
	v_mul_f32_e32 v226, v4, v137
	v_mul_f32_e32 v227, v20, v137
	v_fma_f32 v226, v20, v136, -v226
	v_fma_f32 v227, v4, v136, v227
	v_mul_f32_e32 v226, s88, v226
	v_mul_f32_e32 v227, s88, v227
	v_cvt_pk_bf16_f32 v226, v226, v227
	ds_write_b16 v221, v226 offset:1152
	ds_write_b16_d16_hi v221, v226 offset:1216
	s_waitcnt vmcnt(10)
	v_mul_f32_e32 v226, v5, v139
	v_mul_f32_e32 v227, v21, v139
	v_fma_f32 v226, v21, v138, -v226
	v_fma_f32 v227, v5, v138, v227
	v_mul_f32_e32 v226, s88, v226
	v_mul_f32_e32 v227, s88, v227
	v_cvt_pk_bf16_f32 v226, v226, v227
	ds_write_b16 v221, v226 offset:1296
	ds_write_b16_d16_hi v221, v226 offset:1360
	s_waitcnt vmcnt(9)
	v_mul_f32_e32 v226, v6, v141
	v_mul_f32_e32 v227, v22, v141
	v_fma_f32 v226, v22, v140, -v226
	v_fma_f32 v227, v6, v140, v227
	v_mul_f32_e32 v226, s88, v226
	v_mul_f32_e32 v227, s88, v227
	v_cvt_pk_bf16_f32 v226, v226, v227
	ds_write_b16 v221, v226 offset:1440
	ds_write_b16_d16_hi v221, v226 offset:1504
	s_waitcnt vmcnt(8)
	v_mul_f32_e32 v226, v7, v143
	v_mul_f32_e32 v227, v23, v143
	v_fma_f32 v226, v23, v142, -v226
	v_fma_f32 v227, v7, v142, v227
	v_mul_f32_e32 v226, s88, v226
	v_mul_f32_e32 v227, s88, v227
	v_cvt_pk_bf16_f32 v226, v226, v227
	ds_write_b16 v221, v226 offset:1584
	ds_write_b16_d16_hi v221, v226 offset:1648
	s_waitcnt vmcnt(7)
	v_mul_f32_e32 v226, v8, v145
	v_mul_f32_e32 v227, v24, v145
	v_fma_f32 v226, v24, v144, -v226
	v_fma_f32 v227, v8, v144, v227
	v_mul_f32_e32 v226, s88, v226
	v_mul_f32_e32 v227, s88, v227
	v_cvt_pk_bf16_f32 v226, v226, v227
	ds_write_b16 v221, v226 offset:2304
	ds_write_b16_d16_hi v221, v226 offset:2368
	s_waitcnt vmcnt(6)
	v_mul_f32_e32 v226, v9, v147
	v_mul_f32_e32 v227, v25, v147
	v_fma_f32 v226, v25, v146, -v226
	v_fma_f32 v227, v9, v146, v227
	v_mul_f32_e32 v226, s88, v226
	v_mul_f32_e32 v227, s88, v227
	v_cvt_pk_bf16_f32 v226, v226, v227
	ds_write_b16 v221, v226 offset:2448
	ds_write_b16_d16_hi v221, v226 offset:2512
	s_waitcnt vmcnt(5)
	v_mul_f32_e32 v226, v10, v149
	v_mul_f32_e32 v227, v26, v149
	v_fma_f32 v226, v26, v148, -v226
	v_fma_f32 v227, v10, v148, v227
	v_mul_f32_e32 v226, s88, v226
	v_mul_f32_e32 v227, s88, v227
	v_cvt_pk_bf16_f32 v226, v226, v227
	ds_write_b16 v221, v226 offset:2592
	ds_write_b16_d16_hi v221, v226 offset:2656
	s_waitcnt vmcnt(4)
	v_mul_f32_e32 v226, v11, v151
	v_mul_f32_e32 v227, v27, v151
	v_fma_f32 v226, v27, v150, -v226
	v_fma_f32 v227, v11, v150, v227
	v_mul_f32_e32 v226, s88, v226
	v_mul_f32_e32 v227, s88, v227
	v_cvt_pk_bf16_f32 v226, v226, v227
	ds_write_b16 v221, v226 offset:2736
	ds_write_b16_d16_hi v221, v226 offset:2800
	s_waitcnt vmcnt(3)
	v_mul_f32_e32 v226, v12, v153
	v_mul_f32_e32 v227, v28, v153
	v_fma_f32 v226, v28, v152, -v226
	v_fma_f32 v227, v12, v152, v227
	v_mul_f32_e32 v226, s88, v226
	v_mul_f32_e32 v227, s88, v227
	v_cvt_pk_bf16_f32 v226, v226, v227
	ds_write_b16 v221, v226 offset:3456
	ds_write_b16_d16_hi v221, v226 offset:3520
	s_waitcnt vmcnt(2)
	v_mul_f32_e32 v226, v13, v155
	v_mul_f32_e32 v227, v29, v155
	v_fma_f32 v226, v29, v154, -v226
	v_fma_f32 v227, v13, v154, v227
	v_mul_f32_e32 v226, s88, v226
	v_mul_f32_e32 v227, s88, v227
	v_cvt_pk_bf16_f32 v226, v226, v227
	ds_write_b16 v221, v226 offset:3600
	ds_write_b16_d16_hi v221, v226 offset:3664
	s_waitcnt vmcnt(1)
	v_mul_f32_e32 v226, v14, v157
	v_mul_f32_e32 v227, v30, v157
	v_fma_f32 v226, v30, v156, -v226
	v_fma_f32 v227, v14, v156, v227
	v_mul_f32_e32 v226, s88, v226
	v_mul_f32_e32 v227, s88, v227
	v_cvt_pk_bf16_f32 v226, v226, v227
	ds_write_b16 v221, v226 offset:3744
	ds_write_b16_d16_hi v221, v226 offset:3808
	s_waitcnt vmcnt(0)
	v_mul_f32_e32 v226, v15, v159
	v_mul_f32_e32 v227, v31, v159
	v_fma_f32 v226, v31, v158, -v226
	v_fma_f32 v227, v15, v158, v227
	v_mul_f32_e32 v226, s88, v226
	v_mul_f32_e32 v227, s88, v227
	v_cvt_pk_bf16_f32 v226, v226, v227
	ds_write_b16 v221, v226 offset:3888
	ds_write_b16_d16_hi v221, v226 offset:3952
	s_branch .Lep4_11_st
.Lep4_11_mS:
	v_mul_f32_e32 v226, 0xbfb8aa3b, v16
	v_mul_f32_e32 v227, 0xbfb8aa3b, v0
	v_exp_f32_e32 v226, v226
	v_exp_f32_e32 v227, v227
	v_add_f32_e32 v226, 1.0, v226
	v_add_f32_e32 v227, 1.0, v227
	v_rcp_f32_e32 v226, v226
	v_rcp_f32_e32 v227, v227
	v_mul_f32_e32 v226, v16, v226
	v_mul_f32_e32 v227, v0, v227
	v_cvt_pk_bf16_f32 v226, v226, v227
	ds_write_b16 v221, v226
	ds_write_b16_d16_hi v221, v226 offset:64
	v_mul_f32_e32 v228, 0xbfb8aa3b, v17
	v_mul_f32_e32 v229, 0xbfb8aa3b, v1
	v_exp_f32_e32 v228, v228
	v_exp_f32_e32 v229, v229
	v_add_f32_e32 v228, 1.0, v228
	v_add_f32_e32 v229, 1.0, v229
	v_rcp_f32_e32 v228, v228
	v_rcp_f32_e32 v229, v229
	v_mul_f32_e32 v228, v17, v228
	v_mul_f32_e32 v229, v1, v229
	v_cvt_pk_bf16_f32 v228, v228, v229
	ds_write_b16 v221, v228 offset:144
	ds_write_b16_d16_hi v221, v228 offset:208
	v_mul_f32_e32 v226, 0xbfb8aa3b, v18
	v_mul_f32_e32 v227, 0xbfb8aa3b, v2
	v_exp_f32_e32 v226, v226
	v_exp_f32_e32 v227, v227
	v_add_f32_e32 v226, 1.0, v226
	v_add_f32_e32 v227, 1.0, v227
	v_rcp_f32_e32 v226, v226
	v_rcp_f32_e32 v227, v227
	v_mul_f32_e32 v226, v18, v226
	v_mul_f32_e32 v227, v2, v227
	v_cvt_pk_bf16_f32 v226, v226, v227
	ds_write_b16 v221, v226 offset:288
	ds_write_b16_d16_hi v221, v226 offset:352
	v_mul_f32_e32 v228, 0xbfb8aa3b, v19
	v_mul_f32_e32 v229, 0xbfb8aa3b, v3
	v_exp_f32_e32 v228, v228
	v_exp_f32_e32 v229, v229
	v_add_f32_e32 v228, 1.0, v228
	v_add_f32_e32 v229, 1.0, v229
	v_rcp_f32_e32 v228, v228
	v_rcp_f32_e32 v229, v229
	v_mul_f32_e32 v228, v19, v228
	v_mul_f32_e32 v229, v3, v229
	v_cvt_pk_bf16_f32 v228, v228, v229
	ds_write_b16 v221, v228 offset:432
	ds_write_b16_d16_hi v221, v228 offset:496
	v_mul_f32_e32 v226, 0xbfb8aa3b, v20
	v_mul_f32_e32 v227, 0xbfb8aa3b, v4
	v_exp_f32_e32 v226, v226
	v_exp_f32_e32 v227, v227
	v_add_f32_e32 v226, 1.0, v226
	v_add_f32_e32 v227, 1.0, v227
	v_rcp_f32_e32 v226, v226
	v_rcp_f32_e32 v227, v227
	v_mul_f32_e32 v226, v20, v226
	v_mul_f32_e32 v227, v4, v227
	v_cvt_pk_bf16_f32 v226, v226, v227
	ds_write_b16 v221, v226 offset:1152
	ds_write_b16_d16_hi v221, v226 offset:1216
	v_mul_f32_e32 v228, 0xbfb8aa3b, v21
	v_mul_f32_e32 v229, 0xbfb8aa3b, v5
	v_exp_f32_e32 v228, v228
	v_exp_f32_e32 v229, v229
	v_add_f32_e32 v228, 1.0, v228
	v_add_f32_e32 v229, 1.0, v229
	v_rcp_f32_e32 v228, v228
	v_rcp_f32_e32 v229, v229
	v_mul_f32_e32 v228, v21, v228
	v_mul_f32_e32 v229, v5, v229
	v_cvt_pk_bf16_f32 v228, v228, v229
	ds_write_b16 v221, v228 offset:1296
	ds_write_b16_d16_hi v221, v228 offset:1360
	v_mul_f32_e32 v226, 0xbfb8aa3b, v22
	v_mul_f32_e32 v227, 0xbfb8aa3b, v6
	v_exp_f32_e32 v226, v226
	v_exp_f32_e32 v227, v227
	v_add_f32_e32 v226, 1.0, v226
	v_add_f32_e32 v227, 1.0, v227
	v_rcp_f32_e32 v226, v226
	v_rcp_f32_e32 v227, v227
	v_mul_f32_e32 v226, v22, v226
	v_mul_f32_e32 v227, v6, v227
	v_cvt_pk_bf16_f32 v226, v226, v227
	ds_write_b16 v221, v226 offset:1440
	ds_write_b16_d16_hi v221, v226 offset:1504
	v_mul_f32_e32 v228, 0xbfb8aa3b, v23
	v_mul_f32_e32 v229, 0xbfb8aa3b, v7
	v_exp_f32_e32 v228, v228
	v_exp_f32_e32 v229, v229
	v_add_f32_e32 v228, 1.0, v228
	v_add_f32_e32 v229, 1.0, v229
	v_rcp_f32_e32 v228, v228
	v_rcp_f32_e32 v229, v229
	v_mul_f32_e32 v228, v23, v228
	v_mul_f32_e32 v229, v7, v229
	v_cvt_pk_bf16_f32 v228, v228, v229
	ds_write_b16 v221, v228 offset:1584
	ds_write_b16_d16_hi v221, v228 offset:1648
	v_mul_f32_e32 v226, 0xbfb8aa3b, v24
	v_mul_f32_e32 v227, 0xbfb8aa3b, v8
	v_exp_f32_e32 v226, v226
	v_exp_f32_e32 v227, v227
	v_add_f32_e32 v226, 1.0, v226
	v_add_f32_e32 v227, 1.0, v227
	v_rcp_f32_e32 v226, v226
	v_rcp_f32_e32 v227, v227
	v_mul_f32_e32 v226, v24, v226
	v_mul_f32_e32 v227, v8, v227
	v_cvt_pk_bf16_f32 v226, v226, v227
	ds_write_b16 v221, v226 offset:2304
	ds_write_b16_d16_hi v221, v226 offset:2368
	v_mul_f32_e32 v228, 0xbfb8aa3b, v25
	v_mul_f32_e32 v229, 0xbfb8aa3b, v9
	v_exp_f32_e32 v228, v228
	v_exp_f32_e32 v229, v229
	v_add_f32_e32 v228, 1.0, v228
	v_add_f32_e32 v229, 1.0, v229
	v_rcp_f32_e32 v228, v228
	v_rcp_f32_e32 v229, v229
	v_mul_f32_e32 v228, v25, v228
	v_mul_f32_e32 v229, v9, v229
	v_cvt_pk_bf16_f32 v228, v228, v229
	ds_write_b16 v221, v228 offset:2448
	ds_write_b16_d16_hi v221, v228 offset:2512
	v_mul_f32_e32 v226, 0xbfb8aa3b, v26
	v_mul_f32_e32 v227, 0xbfb8aa3b, v10
	v_exp_f32_e32 v226, v226
	v_exp_f32_e32 v227, v227
	v_add_f32_e32 v226, 1.0, v226
	v_add_f32_e32 v227, 1.0, v227
	v_rcp_f32_e32 v226, v226
	v_rcp_f32_e32 v227, v227
	v_mul_f32_e32 v226, v26, v226
	v_mul_f32_e32 v227, v10, v227
	v_cvt_pk_bf16_f32 v226, v226, v227
	ds_write_b16 v221, v226 offset:2592
	ds_write_b16_d16_hi v221, v226 offset:2656
	v_mul_f32_e32 v228, 0xbfb8aa3b, v27
	v_mul_f32_e32 v229, 0xbfb8aa3b, v11
	v_exp_f32_e32 v228, v228
	v_exp_f32_e32 v229, v229
	v_add_f32_e32 v228, 1.0, v228
	v_add_f32_e32 v229, 1.0, v229
	v_rcp_f32_e32 v228, v228
	v_rcp_f32_e32 v229, v229
	v_mul_f32_e32 v228, v27, v228
	v_mul_f32_e32 v229, v11, v229
	v_cvt_pk_bf16_f32 v228, v228, v229
	ds_write_b16 v221, v228 offset:2736
	ds_write_b16_d16_hi v221, v228 offset:2800
	v_mul_f32_e32 v226, 0xbfb8aa3b, v28
	v_mul_f32_e32 v227, 0xbfb8aa3b, v12
	v_exp_f32_e32 v226, v226
	v_exp_f32_e32 v227, v227
	v_add_f32_e32 v226, 1.0, v226
	v_add_f32_e32 v227, 1.0, v227
	v_rcp_f32_e32 v226, v226
	v_rcp_f32_e32 v227, v227
	v_mul_f32_e32 v226, v28, v226
	v_mul_f32_e32 v227, v12, v227
	v_cvt_pk_bf16_f32 v226, v226, v227
	ds_write_b16 v221, v226 offset:3456
	ds_write_b16_d16_hi v221, v226 offset:3520
	v_mul_f32_e32 v228, 0xbfb8aa3b, v29
	v_mul_f32_e32 v229, 0xbfb8aa3b, v13
	v_exp_f32_e32 v228, v228
	v_exp_f32_e32 v229, v229
	v_add_f32_e32 v228, 1.0, v228
	v_add_f32_e32 v229, 1.0, v229
	v_rcp_f32_e32 v228, v228
	v_rcp_f32_e32 v229, v229
	v_mul_f32_e32 v228, v29, v228
	v_mul_f32_e32 v229, v13, v229
	v_cvt_pk_bf16_f32 v228, v228, v229
	ds_write_b16 v221, v228 offset:3600
	ds_write_b16_d16_hi v221, v228 offset:3664
	v_mul_f32_e32 v226, 0xbfb8aa3b, v30
	v_mul_f32_e32 v227, 0xbfb8aa3b, v14
	v_exp_f32_e32 v226, v226
	v_exp_f32_e32 v227, v227
	v_add_f32_e32 v226, 1.0, v226
	v_add_f32_e32 v227, 1.0, v227
	v_rcp_f32_e32 v226, v226
	v_rcp_f32_e32 v227, v227
	v_mul_f32_e32 v226, v30, v226
	v_mul_f32_e32 v227, v14, v227
	v_cvt_pk_bf16_f32 v226, v226, v227
	ds_write_b16 v221, v226 offset:3744
	ds_write_b16_d16_hi v221, v226 offset:3808
	v_mul_f32_e32 v228, 0xbfb8aa3b, v31
	v_mul_f32_e32 v229, 0xbfb8aa3b, v15
	v_exp_f32_e32 v228, v228
	v_exp_f32_e32 v229, v229
	v_add_f32_e32 v228, 1.0, v228
	v_add_f32_e32 v229, 1.0, v229
	v_rcp_f32_e32 v228, v228
	v_rcp_f32_e32 v229, v229
	v_mul_f32_e32 v228, v31, v228
	v_mul_f32_e32 v229, v15, v229
	v_cvt_pk_bf16_f32 v228, v228, v229
	ds_write_b16 v221, v228 offset:3888
	ds_write_b16_d16_hi v221, v228 offset:3952
	s_branch .Lep4_11_st

.Lep4_11_end:
	s_branch .LBB0_2408
.LBB0_3853:
	s_cmp_lt_i32 s45, 13
	s_cbranch_scc1 .LBB0_3907
	s_waitcnt vmcnt(0)
	v_cmp_eq_u32_e32 vcc, 0, v188
	s_waitcnt lgkmcnt(0)
	s_and_b64 s[4:5], s[46:47], vcc
	s_waitcnt vmcnt(63) expcnt(7) lgkmcnt(15)
	s_barrier
	s_and_saveexec_b64 s[2:3], s[4:5]
	s_cbranch_execz .LBB0_3906
	v_mov_b32_e32 v0, 0x24400
	s_waitcnt vmcnt(0) expcnt(0) lgkmcnt(0)
	ds_read_b32 v2, v0
	v_mov_b32_e32 v0, 0x24404
	ds_read_b32 v0, v0
	s_waitcnt lgkmcnt(1)
	v_cmp_ne_u32_e32 vcc, 0, v2
	s_cbranch_vccnz .LBB0_3870
	s_add_u32 s4, s40, 0x1000
	s_addc_u32 s5, s41, 0
	s_add_u32 s6, s40, 0x1100
	s_addc_u32 s7, s41, 0
	s_add_u32 s8, s40, 0x1200
	s_addc_u32 s9, s41, 0
	s_mul_i32 s18, s43, s33
	s_add_u32 s10, s40, 0x1300
	s_mul_i32 s18, s18, s42
	s_addc_u32 s11, s41, 0
	s_mov_b32 s19, 1
	v_mov_b32_e32 v16, 0
	s_branch .LBB0_3858
